# strategy 7.11: loop counter / exit-test SALU block moved in front of the loop-back barrier in all five GEMM K-loops (peeled copy and loop)
# baseline (speedup 1.0000x reference)
; #define PG8_STAGE(bufoff, gbase, voff) do { _Pragma("unroll") for (int _i = 0; _i < 2; ++_i) \
;         __builtin_amdgcn_global_load_lds((const unsigned*)((const char*)(gbase) + (voff)[_i]), (PG8_LAS unsigned*)(lds + (bufoff) + ldsw + _i * 8192), 16, 0, 0); } while (0)
; #define PG8_LDA(dst, b, h) do { _Pragma("unroll") for (int m = 0; m < 4; ++m) _Pragma("unroll") for (int k = 0; k < 2; ++k) dst[m][k] = *(const PG8_LAS bf16x8*)(lds + PG8_SA(b, h) + aoff + m * 2048 + k * 1024); } while (0)
; #define PG8_LDB(dst, b, h) do { _Pragma("unroll") for (int n = 0; n < 2; ++n) _Pragma("unroll") for (int k = 0; k < 2; ++k) dst[n][k] = *(const PG8_LAS bf16x8*)(lds + PG8_SB(b, h) + boff + n * 2048 + k * 1024); } while (0)
; #define PG8_WAIT_V(n) asm volatile("s_waitcnt vmcnt(" #n ")" ::: "memory")
; #define PG8_WAIT_L(n) asm volatile("s_waitcnt lgkmcnt(" #n ")" ::: "memory")
; #define PG8_BAR __builtin_amdgcn_s_barrier()
; #define PG8_SCHED __builtin_amdgcn_sched_barrier(0)
; template <class Epi, class Sched, bool ALIGN_EPI = false, bool SP2 = false>
; __device__ __forceinline__ void gemm_phase(PG8_LAS unsigned char* lds, const Gemm g, const Sched& S, const Epi& E) {
;     ...
;         const char* nA = has_next ? (const char*)g.A + (size_t)nxt.pm * tstep : cA; const char* nB = has_next ? (const char*)g.Bt + (size_t)nxt.pn * tstep : cB;
;         for (int t = 0; t < nt; t += 2) {
;             const bool last = (t == nt - 2);
;             const char* a1 = cA + (size_t)(t + 1) * kstep;
;             const char* a2 = last ? nA : cA + (size_t)(t + 2) * kstep; const char* b2 = last ? nB : cB + (size_t)(t + 2) * kstep;
;             const char* a3 = a2 + kstep; const char* b3 = b2 + kstep;
;             if (last && has_next) S.a_ready(nxt);
;             if constexpr (SP2) {
;             PG8_LDB(B0, 0, 0); PG8_LDB(B1, 0, 1); PG8_SCHED; PG8_LDA(At, 0, 0); PG8_STAGE(PG8_SA(1, 1), a1 + hstep, voffA);
;             PG8_WAIT_V(8); PG8_WAIT_L(0); PG8_BAR; PG8_MMA(0, 0, At, B0); PG8_MMA(0, 1, At, B1); PG8_BAR; PG8_SCHED;
;             PG8_LDA(At, 0, 1); PG8_STAGE(PG8_SB(0, 0), b2, voffB); PG8_STAGE(PG8_SB(0, 1), b2 + hstep, voffB); PG8_STAGE(PG8_SA(0, 0), a2, voffA);
;             PG8_WAIT_V(8); PG8_WAIT_L(0); PG8_BAR; PG8_MMA(1, 0, At, B0); PG8_MMA(1, 1, At, B1); PG8_BAR; PG8_SCHED;
.LBB0_43:
	s_ashr_i32 s47, s46, 31
	s_lshl_b64 s[24:25], s[46:47], 19
	s_add_u32 s48, s26, s24
	s_addc_u32 s49, s27, s25
	s_and_b64 s[24:25], s[40:41], exec
	s_cselect_b32 s1, s49, s61
	s_cselect_b32 s12, s48, s60
	s_ashr_i32 s3, s2, 31
	s_lshl_b64 s[24:25], s[2:3], 19
	s_add_u32 s56, s23, s24
	s_addc_u32 s57, s29, s25
	s_and_b64 s[24:25], s[40:41], exec
	s_cselect_b32 s3, s57, s63
	s_cselect_b32 s22, s56, s62
	s_add_u32 s60, s60, 0x40080
	s_addc_u32 s61, s61, 0
	s_add_u32 s33, s62, 0x100
	s_addc_u32 s44, s63, 0
	s_mov_b32 s45, -2
	s_add_u32 s24, s60, 0xfffc0080
	s_addc_u32 s25, s61, -1
	s_add_i32 s47, 0, 0x10000
	s_cmp_eq_u32 s45, 12
	s_cselect_b32 s65, s1, s25
	s_cselect_b32 s64, s12, s24
	v_add_u32_e32 v150, s47, v153
	s_cselect_b32 s63, s3, s44
	s_cselect_b32 s62, s22, s33
	s_add_i32 s50, 0, 0x14000
	ds_read_b128 v[146:149], v150
	ds_read_b128 v[156:159], v150 offset:1024
	ds_read_b128 v[160:163], v150 offset:2048
	ds_read_b128 v[164:167], v150 offset:3072
	v_add_u32_e32 v150, s50, v153
	ds_read_b128 v[168:171], v150
	ds_read_b128 v[192:195], v150 offset:1024
	ds_read_b128 v[196:199], v150 offset:2048
	ds_read_b128 v[200:203], v150 offset:3072
	v_lshl_add_u64 v[150:151], s[60:61], 0, v[142:143]
	s_add_i32 m0, s68, 0xc000
	ds_read_b128 v[204:207], v155
	ds_read_b128 v[208:211], v155 offset:1024
	ds_read_b128 v[212:215], v155 offset:2048
	ds_read_b128 v[216:219], v155 offset:3072
	ds_read_b128 v[220:223], v155 offset:4096
	ds_read_b128 v[224:227], v155 offset:5120
	ds_read_b128 v[228:231], v155 offset:6144
	ds_read_b128 v[232:235], v155 offset:7168
	global_load_lds_dwordx4 v[150:151], off
	v_lshl_add_u64 v[150:151], s[60:61], 0, v[144:145]
	s_add_i32 m0, s68, 0xe000
	s_nop 0
	global_load_lds_dwordx4 v[150:151], off
	s_waitcnt vmcnt(10)
	s_waitcnt lgkmcnt(0)
	s_barrier
	s_setprio 1
	s_waitcnt lgkmcnt(0)
	v_mfma_f32_16x16x32_bf16 v[124:127], v[146:149], v[204:207], 0
	v_mfma_f32_16x16x32_bf16 v[120:123], v[160:163], v[204:207], 0
	v_mfma_f32_16x16x32_bf16 v[108:111], v[146:149], v[212:215], 0
	v_mfma_f32_16x16x32_bf16 v[104:107], v[160:163], v[212:215], 0
	v_mfma_f32_16x16x32_bf16 v[92:95], v[146:149], v[220:223], 0
	v_mfma_f32_16x16x32_bf16 v[88:91], v[160:163], v[220:223], 0
	v_mfma_f32_16x16x32_bf16 v[76:79], v[146:149], v[228:231], 0
	v_mfma_f32_16x16x32_bf16 v[72:75], v[160:163], v[228:231], 0
	v_mfma_f32_16x16x32_bf16 v[124:127], v[156:159], v[208:211], v[124:127]
	v_mfma_f32_16x16x32_bf16 v[120:123], v[164:167], v[208:211], v[120:123]
	v_mfma_f32_16x16x32_bf16 v[108:111], v[156:159], v[216:219], v[108:111]
	v_mfma_f32_16x16x32_bf16 v[104:107], v[164:167], v[216:219], v[104:107]
	v_mfma_f32_16x16x32_bf16 v[92:95], v[156:159], v[224:227], v[92:95]
	v_mfma_f32_16x16x32_bf16 v[88:91], v[164:167], v[224:227], v[88:91]
	v_mfma_f32_16x16x32_bf16 v[76:79], v[156:159], v[232:235], v[76:79]
	v_mfma_f32_16x16x32_bf16 v[72:75], v[164:167], v[232:235], v[72:75]
	s_setprio 0
	s_setprio 1
	v_mfma_f32_16x16x32_bf16 v[116:119], v[168:171], v[204:207], 0
	v_mfma_f32_16x16x32_bf16 v[112:115], v[196:199], v[204:207], 0
	v_mfma_f32_16x16x32_bf16 v[100:103], v[168:171], v[212:215], 0
	v_mfma_f32_16x16x32_bf16 v[96:99], v[196:199], v[212:215], 0
	v_mfma_f32_16x16x32_bf16 v[84:87], v[168:171], v[220:223], 0
	v_mfma_f32_16x16x32_bf16 v[80:83], v[196:199], v[220:223], 0
	v_mfma_f32_16x16x32_bf16 v[68:71], v[168:171], v[228:231], 0
	v_mfma_f32_16x16x32_bf16 v[64:67], v[196:199], v[228:231], 0
	v_mfma_f32_16x16x32_bf16 v[116:119], v[192:195], v[208:211], v[116:119]
	v_mfma_f32_16x16x32_bf16 v[112:115], v[200:203], v[208:211], v[112:115]
	v_mfma_f32_16x16x32_bf16 v[100:103], v[192:195], v[216:219], v[100:103]
	v_mfma_f32_16x16x32_bf16 v[96:99], v[200:203], v[216:219], v[96:99]
	v_mfma_f32_16x16x32_bf16 v[84:87], v[192:195], v[224:227], v[84:87]
	v_mfma_f32_16x16x32_bf16 v[80:83], v[200:203], v[224:227], v[80:83]
	v_mfma_f32_16x16x32_bf16 v[68:71], v[192:195], v[232:235], v[68:71]
	v_mfma_f32_16x16x32_bf16 v[64:67], v[200:203], v[232:235], v[64:67]
	s_setprio 0
	s_barrier
	s_add_i32 s24, s47, s66
	v_lshl_add_u64 v[150:151], s[62:63], 0, v[132:133]
	s_mov_b32 m0, s24
	ds_read_b128 v[204:207], v155 offset:16384
	ds_read_b128 v[208:211], v155 offset:17408
	ds_read_b128 v[212:215], v155 offset:18432
	ds_read_b128 v[216:219], v155 offset:19456
	ds_read_b128 v[220:223], v155 offset:20480
	ds_read_b128 v[224:227], v155 offset:21504
	ds_read_b128 v[228:231], v155 offset:22528
	ds_read_b128 v[232:235], v155 offset:23552
	global_load_lds_dwordx4 v[150:151], off
	s_add_i32 m0, s24, 0x2000
	s_add_u32 s24, s62, 0x40000
	v_lshl_add_u64 v[236:237], s[62:63], 0, v[128:129]
	s_addc_u32 s25, s63, 0
	s_add_i32 s47, s50, s66
	global_load_lds_dwordx4 v[236:237], off
	v_lshl_add_u64 v[238:239], s[24:25], 0, v[132:133]
	s_mov_b32 m0, s47
	v_lshl_add_u64 v[240:241], s[64:65], 0, v[130:131]
	global_load_lds_dwordx4 v[238:239], off
	v_lshl_add_u64 v[238:239], s[24:25], 0, v[128:129]
	s_add_i32 m0, s47, 0x2000
	s_nop 0
	global_load_lds_dwordx4 v[238:239], off
	v_lshl_add_u64 v[238:239], s[64:65], 0, v[140:141]
	s_mov_b32 m0, s68
	s_nop 0
	global_load_lds_dwordx4 v[238:239], off
	s_mov_b32 m0, s69
	s_nop 0
	global_load_lds_dwordx4 v[240:241], off
	s_waitcnt vmcnt(16)
	s_waitcnt lgkmcnt(0)
	s_barrier
; #define PG8_STAGE(bufoff, gbase, voff) do { _Pragma("unroll") for (int _i = 0; _i < 2; ++_i) \
;         __builtin_amdgcn_global_load_lds((const unsigned*)((const char*)(gbase) + (voff)[_i]), (PG8_LAS unsigned*)(lds + (bufoff) + ldsw + _i * 8192), 16, 0, 0); } while (0)
; #define PG8_LDA(dst, b, h) do { _Pragma("unroll") for (int m = 0; m < 4; ++m) _Pragma("unroll") for (int k = 0; k < 2; ++k) dst[m][k] = *(const PG8_LAS bf16x8*)(lds + PG8_SA(b, h) + aoff + m * 2048 + k * 1024); } while (0)
; #define PG8_LDB(dst, b, h) do { _Pragma("unroll") for (int n = 0; n < 2; ++n) _Pragma("unroll") for (int k = 0; k < 2; ++k) dst[n][k] = *(const PG8_LAS bf16x8*)(lds + PG8_SB(b, h) + boff + n * 2048 + k * 1024); } while (0)
; #define PG8_MMA(ai, bj, At, Bt) do { __builtin_amdgcn_s_setprio(1); _Pragma("unroll") for (int m = 0; m < 4; ++m) _Pragma("unroll") for (int n = 0; n < 2; ++n) _Pragma("unroll") for (int k = 0; k < 2; ++k) \
;         acc[ai][bj][m][n] = __builtin_amdgcn_mfma_f32_16x16x32_bf16(Bt[n][k], At[m][k], acc[ai][bj][m][n], 0, 0, 0); __builtin_amdgcn_s_setprio(0); } while (0)
; #define PG8_WAIT_V(n) asm volatile("s_waitcnt vmcnt(" #n ")" ::: "memory")
; #define PG8_WAIT_L(n) asm volatile("s_waitcnt lgkmcnt(" #n ")" ::: "memory")
; #define PG8_BAR __builtin_amdgcn_s_barrier()
; #define PG8_SCHED __builtin_amdgcn_sched_barrier(0)
; template <class Epi, class Sched, bool ALIGN_EPI = false, bool SP2 = false>
; __device__ __forceinline__ void gemm_phase(PG8_LAS unsigned char* lds, const Gemm g, const Sched& S, const Epi& E) {
;     ...
;             PG8_WAIT_V(8); PG8_WAIT_L(0); PG8_BAR; PG8_MMA(1, 0, At, B0); PG8_MMA(1, 1, At, B1); PG8_BAR; PG8_SCHED;
;             PG8_LDB(B0, 1, 0); PG8_LDB(B1, 1, 1); PG8_SCHED; PG8_LDA(At, 1, 0); PG8_STAGE(PG8_SA(0, 1), a2 + hstep, voffA);
;             PG8_WAIT_V(8); PG8_WAIT_L(0); PG8_BAR; PG8_MMA(0, 0, At, B0); PG8_MMA(0, 1, At, B1); PG8_BAR; PG8_SCHED;
	s_setprio 1
	s_waitcnt lgkmcnt(0)
	v_mfma_f32_16x16x32_bf16 v[60:63], v[146:149], v[204:207], 0
	v_mfma_f32_16x16x32_bf16 v[56:59], v[160:163], v[204:207], 0
	v_mfma_f32_16x16x32_bf16 v[44:47], v[146:149], v[212:215], 0
	v_mfma_f32_16x16x32_bf16 v[40:43], v[160:163], v[212:215], 0
	v_mfma_f32_16x16x32_bf16 v[28:31], v[146:149], v[220:223], 0
	v_mfma_f32_16x16x32_bf16 v[24:27], v[160:163], v[220:223], 0
	v_mfma_f32_16x16x32_bf16 v[12:15], v[146:149], v[228:231], 0
	v_mfma_f32_16x16x32_bf16 v[8:11], v[160:163], v[228:231], 0
	v_mfma_f32_16x16x32_bf16 v[60:63], v[156:159], v[208:211], v[60:63]
	v_mfma_f32_16x16x32_bf16 v[56:59], v[164:167], v[208:211], v[56:59]
	v_mfma_f32_16x16x32_bf16 v[44:47], v[156:159], v[216:219], v[44:47]
	v_mfma_f32_16x16x32_bf16 v[40:43], v[164:167], v[216:219], v[40:43]
	v_mfma_f32_16x16x32_bf16 v[28:31], v[156:159], v[224:227], v[28:31]
	v_mfma_f32_16x16x32_bf16 v[24:27], v[164:167], v[224:227], v[24:27]
	v_mfma_f32_16x16x32_bf16 v[12:15], v[156:159], v[232:235], v[12:15]
	v_mfma_f32_16x16x32_bf16 v[8:11], v[164:167], v[232:235], v[8:11]
	s_setprio 0
	s_setprio 1
	v_mfma_f32_16x16x32_bf16 v[52:55], v[168:171], v[204:207], 0
	v_mfma_f32_16x16x32_bf16 v[48:51], v[196:199], v[204:207], 0
	v_mfma_f32_16x16x32_bf16 v[36:39], v[168:171], v[212:215], 0
	v_mfma_f32_16x16x32_bf16 v[32:35], v[196:199], v[212:215], 0
	v_mfma_f32_16x16x32_bf16 v[20:23], v[168:171], v[220:223], 0
	v_mfma_f32_16x16x32_bf16 v[16:19], v[196:199], v[220:223], 0
	v_mfma_f32_16x16x32_bf16 v[4:7], v[168:171], v[228:231], 0
	v_mfma_f32_16x16x32_bf16 v[0:3], v[196:199], v[228:231], 0
	v_mfma_f32_16x16x32_bf16 v[52:55], v[192:195], v[208:211], v[52:55]
	v_mfma_f32_16x16x32_bf16 v[48:51], v[200:203], v[208:211], v[48:51]
	v_mfma_f32_16x16x32_bf16 v[36:39], v[192:195], v[216:219], v[36:39]
	v_mfma_f32_16x16x32_bf16 v[32:35], v[200:203], v[216:219], v[32:35]
	v_mfma_f32_16x16x32_bf16 v[20:23], v[192:195], v[224:227], v[20:23]
	v_mfma_f32_16x16x32_bf16 v[16:19], v[200:203], v[224:227], v[16:19]
	v_mfma_f32_16x16x32_bf16 v[4:7], v[192:195], v[232:235], v[4:7]
	v_mfma_f32_16x16x32_bf16 v[0:3], v[200:203], v[232:235], v[0:3]
	s_setprio 0
	s_barrier
	s_add_i32 s47, 0, 0x18000
	s_add_i32 s50, 0, 0x1c000
	v_add_u32_e32 v164, s47, v153
	v_add_u32_e32 v184, s50, v153
	ds_read_b128 v[146:149], v164
	ds_read_b128 v[156:159], v164 offset:1024
	ds_read_b128 v[160:163], v164 offset:2048
	ds_read_b128 v[164:167], v164 offset:3072
	ds_read_b128 v[168:171], v184
	ds_read_b128 v[192:195], v184 offset:1024
	ds_read_b128 v[196:199], v184 offset:2048
	ds_read_b128 v[200:203], v184 offset:3072
	s_add_u32 s24, s64, 0x40000
	s_addc_u32 s25, s65, 0
	s_mov_b32 m0, s71
	v_lshl_add_u64 v[242:243], s[24:25], 0, v[140:141]
	ds_read_b128 v[204:207], v155 offset:32768
	ds_read_b128 v[208:211], v155 offset:33792
	ds_read_b128 v[212:215], v155 offset:34816
	ds_read_b128 v[216:219], v155 offset:35840
	ds_read_b128 v[220:223], v155 offset:36864
	ds_read_b128 v[224:227], v155 offset:37888
	ds_read_b128 v[228:231], v155 offset:38912
	ds_read_b128 v[232:235], v155 offset:39936
	global_load_lds_dwordx4 v[242:243], off
	v_lshl_add_u64 v[242:243], s[24:25], 0, v[130:131]
	s_mov_b32 m0, s87
	s_nop 0
	global_load_lds_dwordx4 v[242:243], off
	s_waitcnt vmcnt(8)
	s_waitcnt lgkmcnt(0)
	s_barrier
	s_setprio 1
	s_waitcnt lgkmcnt(0)
	v_mfma_f32_16x16x32_bf16 v[124:127], v[146:149], v[204:207], v[124:127]
	v_mfma_f32_16x16x32_bf16 v[120:123], v[160:163], v[204:207], v[120:123]
	v_mfma_f32_16x16x32_bf16 v[108:111], v[146:149], v[212:215], v[108:111]
	v_mfma_f32_16x16x32_bf16 v[104:107], v[160:163], v[212:215], v[104:107]
	v_mfma_f32_16x16x32_bf16 v[92:95], v[146:149], v[220:223], v[92:95]
	v_mfma_f32_16x16x32_bf16 v[88:91], v[160:163], v[220:223], v[88:91]
	v_mfma_f32_16x16x32_bf16 v[76:79], v[146:149], v[228:231], v[76:79]
	v_mfma_f32_16x16x32_bf16 v[72:75], v[160:163], v[228:231], v[72:75]
	v_mfma_f32_16x16x32_bf16 v[124:127], v[156:159], v[208:211], v[124:127]
	v_mfma_f32_16x16x32_bf16 v[120:123], v[164:167], v[208:211], v[120:123]
	v_mfma_f32_16x16x32_bf16 v[108:111], v[156:159], v[216:219], v[108:111]
	v_mfma_f32_16x16x32_bf16 v[104:107], v[164:167], v[216:219], v[104:107]
	v_mfma_f32_16x16x32_bf16 v[92:95], v[156:159], v[224:227], v[92:95]
	v_mfma_f32_16x16x32_bf16 v[88:91], v[164:167], v[224:227], v[88:91]
	v_mfma_f32_16x16x32_bf16 v[76:79], v[156:159], v[232:235], v[76:79]
	v_mfma_f32_16x16x32_bf16 v[72:75], v[164:167], v[232:235], v[72:75]
	s_setprio 0
	s_setprio 1
	v_mfma_f32_16x16x32_bf16 v[116:119], v[168:171], v[204:207], v[116:119]
	v_mfma_f32_16x16x32_bf16 v[112:115], v[196:199], v[204:207], v[112:115]
	v_mfma_f32_16x16x32_bf16 v[100:103], v[168:171], v[212:215], v[100:103]
	v_mfma_f32_16x16x32_bf16 v[96:99], v[196:199], v[212:215], v[96:99]
	v_mfma_f32_16x16x32_bf16 v[84:87], v[168:171], v[220:223], v[84:87]
	v_mfma_f32_16x16x32_bf16 v[80:83], v[196:199], v[220:223], v[80:83]
	v_mfma_f32_16x16x32_bf16 v[68:71], v[168:171], v[228:231], v[68:71]
	v_mfma_f32_16x16x32_bf16 v[64:67], v[196:199], v[228:231], v[64:67]
	v_mfma_f32_16x16x32_bf16 v[116:119], v[192:195], v[208:211], v[116:119]
	v_mfma_f32_16x16x32_bf16 v[112:115], v[200:203], v[208:211], v[112:115]
	v_mfma_f32_16x16x32_bf16 v[100:103], v[192:195], v[216:219], v[100:103]
	v_mfma_f32_16x16x32_bf16 v[96:99], v[200:203], v[216:219], v[96:99]
	v_mfma_f32_16x16x32_bf16 v[84:87], v[192:195], v[224:227], v[84:87]
	v_mfma_f32_16x16x32_bf16 v[80:83], v[200:203], v[224:227], v[80:83]
	v_mfma_f32_16x16x32_bf16 v[68:71], v[192:195], v[232:235], v[68:71]
	v_mfma_f32_16x16x32_bf16 v[64:67], v[200:203], v[232:235], v[64:67]
	s_setprio 0
	s_barrier
; #define PG8_STAGE(bufoff, gbase, voff) do { _Pragma("unroll") for (int _i = 0; _i < 2; ++_i) \
;         __builtin_amdgcn_global_load_lds((const unsigned*)((const char*)(gbase) + (voff)[_i]), (PG8_LAS unsigned*)(lds + (bufoff) + ldsw + _i * 8192), 16, 0, 0); } while (0)
; #define PG8_LDA(dst, b, h) do { _Pragma("unroll") for (int m = 0; m < 4; ++m) _Pragma("unroll") for (int k = 0; k < 2; ++k) dst[m][k] = *(const PG8_LAS bf16x8*)(lds + PG8_SA(b, h) + aoff + m * 2048 + k * 1024); } while (0)
; #define PG8_LDB(dst, b, h) do { _Pragma("unroll") for (int n = 0; n < 2; ++n) _Pragma("unroll") for (int k = 0; k < 2; ++k) dst[n][k] = *(const PG8_LAS bf16x8*)(lds + PG8_SB(b, h) + boff + n * 2048 + k * 1024); } while (0)
; #define PG8_MMA(ai, bj, At, Bt) do { __builtin_amdgcn_s_setprio(1); _Pragma("unroll") for (int m = 0; m < 4; ++m) _Pragma("unroll") for (int n = 0; n < 2; ++n) _Pragma("unroll") for (int k = 0; k < 2; ++k) \
;         acc[ai][bj][m][n] = __builtin_amdgcn_mfma_f32_16x16x32_bf16(Bt[n][k], At[m][k], acc[ai][bj][m][n], 0, 0, 0); __builtin_amdgcn_s_setprio(0); } while (0)
; #define PG8_WAIT_V(n) asm volatile("s_waitcnt vmcnt(" #n ")" ::: "memory")
; #define PG8_BAR __builtin_amdgcn_s_barrier()
; template <class Epi, class Sched, bool ALIGN_EPI = false, bool SP2 = false>
; __device__ __forceinline__ void gemm_phase(PG8_LAS unsigned char* lds, const Gemm g, const Sched& S, const Epi& E) {
;     ...
;         for (int t = 0; t < nt; t += 2) {
;             const bool last = (t == nt - 2);
;             const char* a1 = cA + (size_t)(t + 1) * kstep;
;             const char* a2 = last ? nA : cA + (size_t)(t + 2) * kstep; const char* b2 = last ? nB : cB + (size_t)(t + 2) * kstep;
;             const char* a3 = a2 + kstep; const char* b3 = b2 + kstep;
;             if (last && has_next) S.a_ready(nxt);
;             if constexpr (SP2) {
;             PG8_LDB(B0, 0, 0); PG8_LDB(B1, 0, 1); PG8_SCHED; PG8_LDA(At, 0, 0); PG8_STAGE(PG8_SA(1, 1), a1 + hstep, voffA);
;             PG8_WAIT_V(8); PG8_WAIT_L(0); PG8_BAR; PG8_MMA(0, 0, At, B0); PG8_MMA(0, 1, At, B1); PG8_BAR; PG8_SCHED;
;     ...
;             PG8_LDA(At, 1, 1); PG8_STAGE(PG8_SB(1, 0), b3, voffB); PG8_STAGE(PG8_SB(1, 1), b3 + hstep, voffB); PG8_STAGE(PG8_SA(1, 0), a3, voffA);
;             PG8_WAIT_V(8); PG8_WAIT_L(0); PG8_BAR; PG8_MMA(1, 0, At, B0); PG8_MMA(1, 1, At, B1); PG8_BAR; PG8_SCHED;
	s_add_i32 s24, s47, s66
	v_lshl_add_u64 v[150:151], v[150:151], 0, s[14:15]
	s_mov_b32 m0, s24
	ds_read_b128 v[204:207], v155 offset:49152
	ds_read_b128 v[208:211], v155 offset:50176
	ds_read_b128 v[212:215], v155 offset:51200
	ds_read_b128 v[216:219], v155 offset:52224
	ds_read_b128 v[220:223], v155 offset:53248
	ds_read_b128 v[224:227], v155 offset:54272
	ds_read_b128 v[228:231], v155 offset:55296
	ds_read_b128 v[232:235], v155 offset:56320
	global_load_lds_dwordx4 v[150:151], off
	s_add_i32 m0, s24, 0x2000
	s_add_u32 s24, s62, 0x40080
	v_lshl_add_u64 v[150:151], v[236:237], 0, s[14:15]
	s_addc_u32 s25, s63, 0
	s_add_i32 s47, s50, s66
	global_load_lds_dwordx4 v[150:151], off
	v_lshl_add_u64 v[150:151], s[24:25], 0, v[132:133]
	s_mov_b32 m0, s47
	s_nop 0
	global_load_lds_dwordx4 v[150:151], off
	v_lshl_add_u64 v[150:151], s[24:25], 0, v[128:129]
	s_add_i32 m0, s47, 0x2000
	s_nop 0
	global_load_lds_dwordx4 v[150:151], off
	v_lshl_add_u64 v[150:151], v[238:239], 0, s[14:15]
	s_mov_b32 m0, s88
	s_nop 0
	global_load_lds_dwordx4 v[150:151], off
	v_lshl_add_u64 v[150:151], v[240:241], 0, s[14:15]
	s_mov_b32 m0, s89
	s_nop 0
	global_load_lds_dwordx4 v[150:151], off
	s_waitcnt vmcnt(8)
	s_waitcnt lgkmcnt(0)
	s_barrier
	s_setprio 1
	s_waitcnt lgkmcnt(0)
	v_mfma_f32_16x16x32_bf16 v[60:63], v[146:149], v[204:207], v[60:63]
	v_mfma_f32_16x16x32_bf16 v[56:59], v[160:163], v[204:207], v[56:59]
	v_mfma_f32_16x16x32_bf16 v[44:47], v[146:149], v[212:215], v[44:47]
	v_mfma_f32_16x16x32_bf16 v[40:43], v[160:163], v[212:215], v[40:43]
	v_mfma_f32_16x16x32_bf16 v[28:31], v[146:149], v[220:223], v[28:31]
	v_mfma_f32_16x16x32_bf16 v[24:27], v[160:163], v[220:223], v[24:27]
	v_mfma_f32_16x16x32_bf16 v[12:15], v[146:149], v[228:231], v[12:15]
	v_mfma_f32_16x16x32_bf16 v[8:11], v[160:163], v[228:231], v[8:11]
	v_mfma_f32_16x16x32_bf16 v[60:63], v[156:159], v[208:211], v[60:63]
	v_mfma_f32_16x16x32_bf16 v[56:59], v[164:167], v[208:211], v[56:59]
	v_mfma_f32_16x16x32_bf16 v[44:47], v[156:159], v[216:219], v[44:47]
	v_mfma_f32_16x16x32_bf16 v[40:43], v[164:167], v[216:219], v[40:43]
	v_mfma_f32_16x16x32_bf16 v[28:31], v[156:159], v[224:227], v[28:31]
	v_mfma_f32_16x16x32_bf16 v[24:27], v[164:167], v[224:227], v[24:27]
	v_mfma_f32_16x16x32_bf16 v[12:15], v[156:159], v[232:235], v[12:15]
	v_mfma_f32_16x16x32_bf16 v[8:11], v[164:167], v[232:235], v[8:11]
	s_setprio 0
	s_setprio 1
	v_mfma_f32_16x16x32_bf16 v[52:55], v[168:171], v[204:207], v[52:55]
	v_mfma_f32_16x16x32_bf16 v[48:51], v[196:199], v[204:207], v[48:51]
	v_mfma_f32_16x16x32_bf16 v[36:39], v[168:171], v[212:215], v[36:39]
	v_mfma_f32_16x16x32_bf16 v[32:35], v[196:199], v[212:215], v[32:35]
	v_mfma_f32_16x16x32_bf16 v[20:23], v[168:171], v[220:223], v[20:23]
	v_mfma_f32_16x16x32_bf16 v[16:19], v[196:199], v[220:223], v[16:19]
	v_mfma_f32_16x16x32_bf16 v[4:7], v[168:171], v[228:231], v[4:7]
	v_mfma_f32_16x16x32_bf16 v[0:3], v[196:199], v[228:231], v[0:3]
	v_mfma_f32_16x16x32_bf16 v[52:55], v[192:195], v[208:211], v[52:55]
	v_mfma_f32_16x16x32_bf16 v[48:51], v[200:203], v[208:211], v[48:51]
	v_mfma_f32_16x16x32_bf16 v[36:39], v[192:195], v[216:219], v[36:39]
	v_mfma_f32_16x16x32_bf16 v[32:35], v[200:203], v[216:219], v[32:35]
	v_mfma_f32_16x16x32_bf16 v[20:23], v[192:195], v[224:227], v[20:23]
	v_mfma_f32_16x16x32_bf16 v[16:19], v[200:203], v[224:227], v[16:19]
	v_mfma_f32_16x16x32_bf16 v[4:7], v[192:195], v[232:235], v[4:7]
	v_mfma_f32_16x16x32_bf16 v[0:3], v[200:203], v[232:235], v[0:3]
	s_setprio 0
	s_add_i32 s45, s45, 2
	s_add_u32 s60, s60, 0x100
	s_addc_u32 s61, s61, 0
	s_add_u32 s33, s33, 0x100
	s_addc_u32 s44, s44, 0
	s_cmp_gt_u32 s45, 13
	s_barrier
.LBB0_44:
	s_add_u32 s24, s60, 0xfffc0080
	s_addc_u32 s25, s61, -1
	s_add_i32 s47, 0, 0x10000
	s_cmp_eq_u32 s45, 12
	s_cselect_b32 s65, s1, s25
	s_cselect_b32 s64, s12, s24
	v_add_u32_e32 v150, s47, v153
	s_cselect_b32 s63, s3, s44
	s_cselect_b32 s62, s22, s33
	s_add_i32 s50, 0, 0x14000
	ds_read_b128 v[146:149], v150
	ds_read_b128 v[156:159], v150 offset:1024
	ds_read_b128 v[160:163], v150 offset:2048
	ds_read_b128 v[164:167], v150 offset:3072
	v_add_u32_e32 v150, s50, v153
	ds_read_b128 v[168:171], v150
	ds_read_b128 v[192:195], v150 offset:1024
	ds_read_b128 v[196:199], v150 offset:2048
	ds_read_b128 v[200:203], v150 offset:3072
	v_lshl_add_u64 v[150:151], s[60:61], 0, v[142:143]
	s_add_i32 m0, s68, 0xc000
	ds_read_b128 v[204:207], v155
	ds_read_b128 v[208:211], v155 offset:1024
	ds_read_b128 v[212:215], v155 offset:2048
	ds_read_b128 v[216:219], v155 offset:3072
	ds_read_b128 v[220:223], v155 offset:4096
	ds_read_b128 v[224:227], v155 offset:5120
	ds_read_b128 v[228:231], v155 offset:6144
	ds_read_b128 v[232:235], v155 offset:7168
	global_load_lds_dwordx4 v[150:151], off
	v_lshl_add_u64 v[150:151], s[60:61], 0, v[144:145]
	s_add_i32 m0, s68, 0xe000
	s_nop 0
	global_load_lds_dwordx4 v[150:151], off
	s_waitcnt vmcnt(8)
	s_waitcnt lgkmcnt(0)
	s_barrier
; #define PG8_STAGE(bufoff, gbase, voff) do { _Pragma("unroll") for (int _i = 0; _i < 2; ++_i) \
;         __builtin_amdgcn_global_load_lds((const unsigned*)((const char*)(gbase) + (voff)[_i]), (PG8_LAS unsigned*)(lds + (bufoff) + ldsw + _i * 8192), 16, 0, 0); } while (0)
; #define PG8_LDA(dst, b, h) do { _Pragma("unroll") for (int m = 0; m < 4; ++m) _Pragma("unroll") for (int k = 0; k < 2; ++k) dst[m][k] = *(const PG8_LAS bf16x8*)(lds + PG8_SA(b, h) + aoff + m * 2048 + k * 1024); } while (0)
; #define PG8_MMA(ai, bj, At, Bt) do { __builtin_amdgcn_s_setprio(1); _Pragma("unroll") for (int m = 0; m < 4; ++m) _Pragma("unroll") for (int n = 0; n < 2; ++n) _Pragma("unroll") for (int k = 0; k < 2; ++k) \
;         acc[ai][bj][m][n] = __builtin_amdgcn_mfma_f32_16x16x32_bf16(Bt[n][k], At[m][k], acc[ai][bj][m][n], 0, 0, 0); __builtin_amdgcn_s_setprio(0); } while (0)
; #define PG8_WAIT_V(n) asm volatile("s_waitcnt vmcnt(" #n ")" ::: "memory")
; #define PG8_WAIT_L(n) asm volatile("s_waitcnt lgkmcnt(" #n ")" ::: "memory")
; #define PG8_BAR __builtin_amdgcn_s_barrier()
; #define PG8_SCHED __builtin_amdgcn_sched_barrier(0)
; template <class Epi, class Sched, bool ALIGN_EPI = false, bool SP2 = false>
; __device__ __forceinline__ void gemm_phase(PG8_LAS unsigned char* lds, const Gemm g, const Sched& S, const Epi& E) {
;     ...
;             PG8_WAIT_V(8); PG8_WAIT_L(0); PG8_BAR; PG8_MMA(0, 0, At, B0); PG8_MMA(0, 1, At, B1); PG8_BAR; PG8_SCHED;
;             PG8_LDA(At, 0, 1); PG8_STAGE(PG8_SB(0, 0), b2, voffB); PG8_STAGE(PG8_SB(0, 1), b2 + hstep, voffB); PG8_STAGE(PG8_SA(0, 0), a2, voffA);
;             PG8_WAIT_V(8); PG8_WAIT_L(0); PG8_BAR; PG8_MMA(1, 0, At, B0); PG8_MMA(1, 1, At, B1); PG8_BAR; PG8_SCHED;
	s_setprio 1
	s_waitcnt lgkmcnt(0)
	v_mfma_f32_16x16x32_bf16 v[124:127], v[146:149], v[204:207], v[124:127]
	v_mfma_f32_16x16x32_bf16 v[120:123], v[160:163], v[204:207], v[120:123]
	v_mfma_f32_16x16x32_bf16 v[108:111], v[146:149], v[212:215], v[108:111]
	v_mfma_f32_16x16x32_bf16 v[104:107], v[160:163], v[212:215], v[104:107]
	v_mfma_f32_16x16x32_bf16 v[92:95], v[146:149], v[220:223], v[92:95]
	v_mfma_f32_16x16x32_bf16 v[88:91], v[160:163], v[220:223], v[88:91]
	v_mfma_f32_16x16x32_bf16 v[76:79], v[146:149], v[228:231], v[76:79]
	v_mfma_f32_16x16x32_bf16 v[72:75], v[160:163], v[228:231], v[72:75]
	v_mfma_f32_16x16x32_bf16 v[124:127], v[156:159], v[208:211], v[124:127]
	v_mfma_f32_16x16x32_bf16 v[120:123], v[164:167], v[208:211], v[120:123]
	v_mfma_f32_16x16x32_bf16 v[108:111], v[156:159], v[216:219], v[108:111]
	v_mfma_f32_16x16x32_bf16 v[104:107], v[164:167], v[216:219], v[104:107]
	v_mfma_f32_16x16x32_bf16 v[92:95], v[156:159], v[224:227], v[92:95]
	v_mfma_f32_16x16x32_bf16 v[88:91], v[164:167], v[224:227], v[88:91]
	v_mfma_f32_16x16x32_bf16 v[76:79], v[156:159], v[232:235], v[76:79]
	v_mfma_f32_16x16x32_bf16 v[72:75], v[164:167], v[232:235], v[72:75]
	s_setprio 0
	s_setprio 1
	v_mfma_f32_16x16x32_bf16 v[116:119], v[168:171], v[204:207], v[116:119]
	v_mfma_f32_16x16x32_bf16 v[112:115], v[196:199], v[204:207], v[112:115]
	v_mfma_f32_16x16x32_bf16 v[100:103], v[168:171], v[212:215], v[100:103]
	v_mfma_f32_16x16x32_bf16 v[96:99], v[196:199], v[212:215], v[96:99]
	v_mfma_f32_16x16x32_bf16 v[84:87], v[168:171], v[220:223], v[84:87]
	v_mfma_f32_16x16x32_bf16 v[80:83], v[196:199], v[220:223], v[80:83]
	v_mfma_f32_16x16x32_bf16 v[68:71], v[168:171], v[228:231], v[68:71]
	v_mfma_f32_16x16x32_bf16 v[64:67], v[196:199], v[228:231], v[64:67]
	v_mfma_f32_16x16x32_bf16 v[116:119], v[192:195], v[208:211], v[116:119]
	v_mfma_f32_16x16x32_bf16 v[112:115], v[200:203], v[208:211], v[112:115]
	v_mfma_f32_16x16x32_bf16 v[100:103], v[192:195], v[216:219], v[100:103]
	v_mfma_f32_16x16x32_bf16 v[96:99], v[200:203], v[216:219], v[96:99]
	v_mfma_f32_16x16x32_bf16 v[84:87], v[192:195], v[224:227], v[84:87]
	v_mfma_f32_16x16x32_bf16 v[80:83], v[200:203], v[224:227], v[80:83]
	v_mfma_f32_16x16x32_bf16 v[68:71], v[192:195], v[232:235], v[68:71]
	v_mfma_f32_16x16x32_bf16 v[64:67], v[200:203], v[232:235], v[64:67]
	s_setprio 0
	s_barrier
	s_add_i32 s24, s47, s66
	v_lshl_add_u64 v[150:151], s[62:63], 0, v[132:133]
	s_mov_b32 m0, s24
	ds_read_b128 v[204:207], v155 offset:16384
	ds_read_b128 v[208:211], v155 offset:17408
	ds_read_b128 v[212:215], v155 offset:18432
	ds_read_b128 v[216:219], v155 offset:19456
	ds_read_b128 v[220:223], v155 offset:20480
	ds_read_b128 v[224:227], v155 offset:21504
	ds_read_b128 v[228:231], v155 offset:22528
	ds_read_b128 v[232:235], v155 offset:23552
	global_load_lds_dwordx4 v[150:151], off
	s_add_i32 m0, s24, 0x2000
	s_add_u32 s24, s62, 0x40000
	v_lshl_add_u64 v[236:237], s[62:63], 0, v[128:129]
	s_addc_u32 s25, s63, 0
	s_add_i32 s47, s50, s66
	global_load_lds_dwordx4 v[236:237], off
	v_lshl_add_u64 v[238:239], s[24:25], 0, v[132:133]
	s_mov_b32 m0, s47
	v_lshl_add_u64 v[240:241], s[64:65], 0, v[130:131]
	global_load_lds_dwordx4 v[238:239], off
	v_lshl_add_u64 v[238:239], s[24:25], 0, v[128:129]
	s_add_i32 m0, s47, 0x2000
	s_nop 0
	global_load_lds_dwordx4 v[238:239], off
	v_lshl_add_u64 v[238:239], s[64:65], 0, v[140:141]
	s_mov_b32 m0, s68
	s_nop 0
	global_load_lds_dwordx4 v[238:239], off
	s_mov_b32 m0, s69
	s_nop 0
	global_load_lds_dwordx4 v[240:241], off
	s_waitcnt vmcnt(8)
	s_waitcnt lgkmcnt(0)
	s_barrier
	s_setprio 1
	s_waitcnt lgkmcnt(0)
	v_mfma_f32_16x16x32_bf16 v[60:63], v[146:149], v[204:207], v[60:63]
	v_mfma_f32_16x16x32_bf16 v[56:59], v[160:163], v[204:207], v[56:59]
	v_mfma_f32_16x16x32_bf16 v[44:47], v[146:149], v[212:215], v[44:47]
	v_mfma_f32_16x16x32_bf16 v[40:43], v[160:163], v[212:215], v[40:43]
	v_mfma_f32_16x16x32_bf16 v[28:31], v[146:149], v[220:223], v[28:31]
	v_mfma_f32_16x16x32_bf16 v[24:27], v[160:163], v[220:223], v[24:27]
	v_mfma_f32_16x16x32_bf16 v[12:15], v[146:149], v[228:231], v[12:15]
	v_mfma_f32_16x16x32_bf16 v[8:11], v[160:163], v[228:231], v[8:11]
	v_mfma_f32_16x16x32_bf16 v[60:63], v[156:159], v[208:211], v[60:63]
	v_mfma_f32_16x16x32_bf16 v[56:59], v[164:167], v[208:211], v[56:59]
	v_mfma_f32_16x16x32_bf16 v[44:47], v[156:159], v[216:219], v[44:47]
	v_mfma_f32_16x16x32_bf16 v[40:43], v[164:167], v[216:219], v[40:43]
	v_mfma_f32_16x16x32_bf16 v[28:31], v[156:159], v[224:227], v[28:31]
	v_mfma_f32_16x16x32_bf16 v[24:27], v[164:167], v[224:227], v[24:27]
	v_mfma_f32_16x16x32_bf16 v[12:15], v[156:159], v[232:235], v[12:15]
	v_mfma_f32_16x16x32_bf16 v[8:11], v[164:167], v[232:235], v[8:11]
	s_setprio 0
	s_setprio 1
	v_mfma_f32_16x16x32_bf16 v[52:55], v[168:171], v[204:207], v[52:55]
	v_mfma_f32_16x16x32_bf16 v[48:51], v[196:199], v[204:207], v[48:51]
	v_mfma_f32_16x16x32_bf16 v[36:39], v[168:171], v[212:215], v[36:39]
	v_mfma_f32_16x16x32_bf16 v[32:35], v[196:199], v[212:215], v[32:35]
	v_mfma_f32_16x16x32_bf16 v[20:23], v[168:171], v[220:223], v[20:23]
	v_mfma_f32_16x16x32_bf16 v[16:19], v[196:199], v[220:223], v[16:19]
	v_mfma_f32_16x16x32_bf16 v[4:7], v[168:171], v[228:231], v[4:7]
	v_mfma_f32_16x16x32_bf16 v[0:3], v[196:199], v[228:231], v[0:3]
	v_mfma_f32_16x16x32_bf16 v[52:55], v[192:195], v[208:211], v[52:55]
	v_mfma_f32_16x16x32_bf16 v[48:51], v[200:203], v[208:211], v[48:51]
	v_mfma_f32_16x16x32_bf16 v[36:39], v[192:195], v[216:219], v[36:39]
	v_mfma_f32_16x16x32_bf16 v[32:35], v[200:203], v[216:219], v[32:35]
	v_mfma_f32_16x16x32_bf16 v[20:23], v[192:195], v[224:227], v[20:23]
	v_mfma_f32_16x16x32_bf16 v[16:19], v[200:203], v[224:227], v[16:19]
	v_mfma_f32_16x16x32_bf16 v[4:7], v[192:195], v[232:235], v[4:7]
	v_mfma_f32_16x16x32_bf16 v[0:3], v[200:203], v[232:235], v[0:3]
	s_setprio 0
	s_barrier
; #define PG8_STAGE(bufoff, gbase, voff) do { _Pragma("unroll") for (int _i = 0; _i < 2; ++_i) \
;         __builtin_amdgcn_global_load_lds((const unsigned*)((const char*)(gbase) + (voff)[_i]), (PG8_LAS unsigned*)(lds + (bufoff) + ldsw + _i * 8192), 16, 0, 0); } while (0)
; #define PG8_LDA(dst, b, h) do { _Pragma("unroll") for (int m = 0; m < 4; ++m) _Pragma("unroll") for (int k = 0; k < 2; ++k) dst[m][k] = *(const PG8_LAS bf16x8*)(lds + PG8_SA(b, h) + aoff + m * 2048 + k * 1024); } while (0)
; #define PG8_LDB(dst, b, h) do { _Pragma("unroll") for (int n = 0; n < 2; ++n) _Pragma("unroll") for (int k = 0; k < 2; ++k) dst[n][k] = *(const PG8_LAS bf16x8*)(lds + PG8_SB(b, h) + boff + n * 2048 + k * 1024); } while (0)
; #define PG8_MMA(ai, bj, At, Bt) do { __builtin_amdgcn_s_setprio(1); _Pragma("unroll") for (int m = 0; m < 4; ++m) _Pragma("unroll") for (int n = 0; n < 2; ++n) _Pragma("unroll") for (int k = 0; k < 2; ++k) \
;         acc[ai][bj][m][n] = __builtin_amdgcn_mfma_f32_16x16x32_bf16(Bt[n][k], At[m][k], acc[ai][bj][m][n], 0, 0, 0); __builtin_amdgcn_s_setprio(0); } while (0)
; #define PG8_WAIT_V(n) asm volatile("s_waitcnt vmcnt(" #n ")" ::: "memory")
; #define PG8_WAIT_L(n) asm volatile("s_waitcnt lgkmcnt(" #n ")" ::: "memory")
; #define PG8_BAR __builtin_amdgcn_s_barrier()
; #define PG8_SCHED __builtin_amdgcn_sched_barrier(0)
; template <class Epi, class Sched, bool ALIGN_EPI = false, bool SP2 = false>
; __device__ __forceinline__ void gemm_phase(PG8_LAS unsigned char* lds, const Gemm g, const Sched& S, const Epi& E) {
;     ...
;             PG8_LDB(B0, 1, 0); PG8_LDB(B1, 1, 1); PG8_SCHED; PG8_LDA(At, 1, 0); PG8_STAGE(PG8_SA(0, 1), a2 + hstep, voffA);
;             PG8_WAIT_V(8); PG8_WAIT_L(0); PG8_BAR; PG8_MMA(0, 0, At, B0); PG8_MMA(0, 1, At, B1); PG8_BAR; PG8_SCHED;
	s_add_i32 s47, 0, 0x18000
	s_add_i32 s50, 0, 0x1c000
	v_add_u32_e32 v164, s47, v153
	v_add_u32_e32 v184, s50, v153
	ds_read_b128 v[146:149], v164
	ds_read_b128 v[156:159], v164 offset:1024
	ds_read_b128 v[160:163], v164 offset:2048
	ds_read_b128 v[164:167], v164 offset:3072
	ds_read_b128 v[168:171], v184
	ds_read_b128 v[192:195], v184 offset:1024
	ds_read_b128 v[196:199], v184 offset:2048
	ds_read_b128 v[200:203], v184 offset:3072
	s_add_u32 s24, s64, 0x40000
	s_addc_u32 s25, s65, 0
	s_mov_b32 m0, s71
	v_lshl_add_u64 v[242:243], s[24:25], 0, v[140:141]
	ds_read_b128 v[204:207], v155 offset:32768
	ds_read_b128 v[208:211], v155 offset:33792
	ds_read_b128 v[212:215], v155 offset:34816
	ds_read_b128 v[216:219], v155 offset:35840
	ds_read_b128 v[220:223], v155 offset:36864
	ds_read_b128 v[224:227], v155 offset:37888
	ds_read_b128 v[228:231], v155 offset:38912
	ds_read_b128 v[232:235], v155 offset:39936
	global_load_lds_dwordx4 v[242:243], off
	v_lshl_add_u64 v[242:243], s[24:25], 0, v[130:131]
	s_mov_b32 m0, s87
	s_nop 0
	global_load_lds_dwordx4 v[242:243], off
	s_waitcnt vmcnt(8)
	s_waitcnt lgkmcnt(0)
	s_barrier
	s_setprio 1
	s_waitcnt lgkmcnt(0)
	v_mfma_f32_16x16x32_bf16 v[124:127], v[146:149], v[204:207], v[124:127]
	v_mfma_f32_16x16x32_bf16 v[120:123], v[160:163], v[204:207], v[120:123]
	v_mfma_f32_16x16x32_bf16 v[108:111], v[146:149], v[212:215], v[108:111]
	v_mfma_f32_16x16x32_bf16 v[104:107], v[160:163], v[212:215], v[104:107]
	v_mfma_f32_16x16x32_bf16 v[92:95], v[146:149], v[220:223], v[92:95]
	v_mfma_f32_16x16x32_bf16 v[88:91], v[160:163], v[220:223], v[88:91]
	v_mfma_f32_16x16x32_bf16 v[76:79], v[146:149], v[228:231], v[76:79]
	v_mfma_f32_16x16x32_bf16 v[72:75], v[160:163], v[228:231], v[72:75]
	v_mfma_f32_16x16x32_bf16 v[124:127], v[156:159], v[208:211], v[124:127]
	v_mfma_f32_16x16x32_bf16 v[120:123], v[164:167], v[208:211], v[120:123]
	v_mfma_f32_16x16x32_bf16 v[108:111], v[156:159], v[216:219], v[108:111]
	v_mfma_f32_16x16x32_bf16 v[104:107], v[164:167], v[216:219], v[104:107]
	v_mfma_f32_16x16x32_bf16 v[92:95], v[156:159], v[224:227], v[92:95]
	v_mfma_f32_16x16x32_bf16 v[88:91], v[164:167], v[224:227], v[88:91]
	v_mfma_f32_16x16x32_bf16 v[76:79], v[156:159], v[232:235], v[76:79]
	v_mfma_f32_16x16x32_bf16 v[72:75], v[164:167], v[232:235], v[72:75]
	s_setprio 0
	s_setprio 1
	v_mfma_f32_16x16x32_bf16 v[116:119], v[168:171], v[204:207], v[116:119]
	v_mfma_f32_16x16x32_bf16 v[112:115], v[196:199], v[204:207], v[112:115]
	v_mfma_f32_16x16x32_bf16 v[100:103], v[168:171], v[212:215], v[100:103]
	v_mfma_f32_16x16x32_bf16 v[96:99], v[196:199], v[212:215], v[96:99]
	v_mfma_f32_16x16x32_bf16 v[84:87], v[168:171], v[220:223], v[84:87]
	v_mfma_f32_16x16x32_bf16 v[80:83], v[196:199], v[220:223], v[80:83]
	v_mfma_f32_16x16x32_bf16 v[68:71], v[168:171], v[228:231], v[68:71]
	v_mfma_f32_16x16x32_bf16 v[64:67], v[196:199], v[228:231], v[64:67]
	v_mfma_f32_16x16x32_bf16 v[116:119], v[192:195], v[208:211], v[116:119]
	v_mfma_f32_16x16x32_bf16 v[112:115], v[200:203], v[208:211], v[112:115]
	v_mfma_f32_16x16x32_bf16 v[100:103], v[192:195], v[216:219], v[100:103]
	v_mfma_f32_16x16x32_bf16 v[96:99], v[200:203], v[216:219], v[96:99]
	v_mfma_f32_16x16x32_bf16 v[84:87], v[192:195], v[224:227], v[84:87]
	v_mfma_f32_16x16x32_bf16 v[80:83], v[200:203], v[224:227], v[80:83]
	v_mfma_f32_16x16x32_bf16 v[68:71], v[192:195], v[232:235], v[68:71]
	v_mfma_f32_16x16x32_bf16 v[64:67], v[200:203], v[232:235], v[64:67]
	s_setprio 0
	s_barrier
; #define PG8_STAGE(bufoff, gbase, voff) do { _Pragma("unroll") for (int _i = 0; _i < 2; ++_i) \
;         __builtin_amdgcn_global_load_lds((const unsigned*)((const char*)(gbase) + (voff)[_i]), (PG8_LAS unsigned*)(lds + (bufoff) + ldsw + _i * 8192), 16, 0, 0); } while (0)
; #define PG8_LDA(dst, b, h) do { _Pragma("unroll") for (int m = 0; m < 4; ++m) _Pragma("unroll") for (int k = 0; k < 2; ++k) dst[m][k] = *(const PG8_LAS bf16x8*)(lds + PG8_SA(b, h) + aoff + m * 2048 + k * 1024); } while (0)
; #define PG8_MMA(ai, bj, At, Bt) do { __builtin_amdgcn_s_setprio(1); _Pragma("unroll") for (int m = 0; m < 4; ++m) _Pragma("unroll") for (int n = 0; n < 2; ++n) _Pragma("unroll") for (int k = 0; k < 2; ++k) \
;         acc[ai][bj][m][n] = __builtin_amdgcn_mfma_f32_16x16x32_bf16(Bt[n][k], At[m][k], acc[ai][bj][m][n], 0, 0, 0); __builtin_amdgcn_s_setprio(0); } while (0)
; #define PG8_WAIT_V(n) asm volatile("s_waitcnt vmcnt(" #n ")" ::: "memory")
; #define PG8_WAIT_L(n) asm volatile("s_waitcnt lgkmcnt(" #n ")" ::: "memory")
; #define PG8_BAR __builtin_amdgcn_s_barrier()
; #define PG8_SCHED __builtin_amdgcn_sched_barrier(0)
; template <class Epi, class Sched, bool ALIGN_EPI = false, bool SP2 = false>
; __device__ __forceinline__ void gemm_phase(PG8_LAS unsigned char* lds, const Gemm g, const Sched& S, const Epi& E) {
;     ...
;             PG8_LDA(At, 1, 1); PG8_STAGE(PG8_SB(1, 0), b3, voffB); PG8_STAGE(PG8_SB(1, 1), b3 + hstep, voffB); PG8_STAGE(PG8_SA(1, 0), a3, voffA);
;             PG8_WAIT_V(8); PG8_WAIT_L(0); PG8_BAR; PG8_MMA(1, 0, At, B0); PG8_MMA(1, 1, At, B1); PG8_BAR; PG8_SCHED;
;     ...
;         if constexpr (ALIGN_EPI) { if (wr == 0) PG8_BAR; }
	s_add_i32 s24, s47, s66
	v_lshl_add_u64 v[150:151], v[150:151], 0, s[14:15]
	s_mov_b32 m0, s24
	ds_read_b128 v[204:207], v155 offset:49152
	ds_read_b128 v[208:211], v155 offset:50176
	ds_read_b128 v[212:215], v155 offset:51200
	ds_read_b128 v[216:219], v155 offset:52224
	ds_read_b128 v[220:223], v155 offset:53248
	ds_read_b128 v[224:227], v155 offset:54272
	ds_read_b128 v[228:231], v155 offset:55296
	ds_read_b128 v[232:235], v155 offset:56320
	global_load_lds_dwordx4 v[150:151], off
	s_add_i32 m0, s24, 0x2000
	s_add_u32 s24, s62, 0x40080
	v_lshl_add_u64 v[150:151], v[236:237], 0, s[14:15]
	s_addc_u32 s25, s63, 0
	s_add_i32 s47, s50, s66
	global_load_lds_dwordx4 v[150:151], off
	v_lshl_add_u64 v[150:151], s[24:25], 0, v[132:133]
	s_mov_b32 m0, s47
	s_nop 0
	global_load_lds_dwordx4 v[150:151], off
	v_lshl_add_u64 v[150:151], s[24:25], 0, v[128:129]
	s_add_i32 m0, s47, 0x2000
	s_nop 0
	global_load_lds_dwordx4 v[150:151], off
	v_lshl_add_u64 v[150:151], v[238:239], 0, s[14:15]
	s_mov_b32 m0, s88
	s_nop 0
	global_load_lds_dwordx4 v[150:151], off
	v_lshl_add_u64 v[150:151], v[240:241], 0, s[14:15]
	s_mov_b32 m0, s89
	s_nop 0
	global_load_lds_dwordx4 v[150:151], off
	s_waitcnt vmcnt(8)
	s_waitcnt lgkmcnt(0)
	s_barrier
	s_setprio 1
	s_waitcnt lgkmcnt(0)
	v_mfma_f32_16x16x32_bf16 v[60:63], v[146:149], v[204:207], v[60:63]
	v_mfma_f32_16x16x32_bf16 v[56:59], v[160:163], v[204:207], v[56:59]
	v_mfma_f32_16x16x32_bf16 v[44:47], v[146:149], v[212:215], v[44:47]
	v_mfma_f32_16x16x32_bf16 v[40:43], v[160:163], v[212:215], v[40:43]
	v_mfma_f32_16x16x32_bf16 v[28:31], v[146:149], v[220:223], v[28:31]
	v_mfma_f32_16x16x32_bf16 v[24:27], v[160:163], v[220:223], v[24:27]
	v_mfma_f32_16x16x32_bf16 v[12:15], v[146:149], v[228:231], v[12:15]
	v_mfma_f32_16x16x32_bf16 v[8:11], v[160:163], v[228:231], v[8:11]
	v_mfma_f32_16x16x32_bf16 v[60:63], v[156:159], v[208:211], v[60:63]
	v_mfma_f32_16x16x32_bf16 v[56:59], v[164:167], v[208:211], v[56:59]
	v_mfma_f32_16x16x32_bf16 v[44:47], v[156:159], v[216:219], v[44:47]
	v_mfma_f32_16x16x32_bf16 v[40:43], v[164:167], v[216:219], v[40:43]
	v_mfma_f32_16x16x32_bf16 v[28:31], v[156:159], v[224:227], v[28:31]
	v_mfma_f32_16x16x32_bf16 v[24:27], v[164:167], v[224:227], v[24:27]
	v_mfma_f32_16x16x32_bf16 v[12:15], v[156:159], v[232:235], v[12:15]
	v_mfma_f32_16x16x32_bf16 v[8:11], v[164:167], v[232:235], v[8:11]
	s_setprio 0
	s_setprio 1
	v_mfma_f32_16x16x32_bf16 v[52:55], v[168:171], v[204:207], v[52:55]
	v_mfma_f32_16x16x32_bf16 v[48:51], v[196:199], v[204:207], v[48:51]
	v_mfma_f32_16x16x32_bf16 v[36:39], v[168:171], v[212:215], v[36:39]
	v_mfma_f32_16x16x32_bf16 v[32:35], v[196:199], v[212:215], v[32:35]
	v_mfma_f32_16x16x32_bf16 v[20:23], v[168:171], v[220:223], v[20:23]
	v_mfma_f32_16x16x32_bf16 v[16:19], v[196:199], v[220:223], v[16:19]
	v_mfma_f32_16x16x32_bf16 v[4:7], v[168:171], v[228:231], v[4:7]
	v_mfma_f32_16x16x32_bf16 v[0:3], v[196:199], v[228:231], v[0:3]
	v_mfma_f32_16x16x32_bf16 v[52:55], v[192:195], v[208:211], v[52:55]
	v_mfma_f32_16x16x32_bf16 v[48:51], v[200:203], v[208:211], v[48:51]
	v_mfma_f32_16x16x32_bf16 v[36:39], v[192:195], v[216:219], v[36:39]
	v_mfma_f32_16x16x32_bf16 v[32:35], v[200:203], v[216:219], v[32:35]
	v_mfma_f32_16x16x32_bf16 v[20:23], v[192:195], v[224:227], v[20:23]
	v_mfma_f32_16x16x32_bf16 v[16:19], v[200:203], v[224:227], v[16:19]
	v_mfma_f32_16x16x32_bf16 v[4:7], v[192:195], v[232:235], v[4:7]
	v_mfma_f32_16x16x32_bf16 v[0:3], v[200:203], v[232:235], v[0:3]
	s_setprio 0
	s_add_i32 s45, s45, 2
	s_add_u32 s60, s60, 0x100
	s_addc_u32 s61, s61, 0
	s_add_u32 s33, s33, 0x100
	s_addc_u32 s44, s44, 0
	s_cmp_gt_u32 s45, 13
	s_barrier
	s_cbranch_scc0 .LBB0_44
	s_and_b64 vcc, exec, s[20:21]
	s_cbranch_vccz .LBB0_47
	s_barrier

; #define PG8_STAGE(bufoff, gbase, voff) do { _Pragma("unroll") for (int _i = 0; _i < 2; ++_i) \
;         __builtin_amdgcn_global_load_lds((const unsigned*)((const char*)(gbase) + (voff)[_i]), (PG8_LAS unsigned*)(lds + (bufoff) + ldsw + _i * 8192), 16, 0, 0); } while (0)
; #define PG8_LDA(dst, b, h) do { _Pragma("unroll") for (int m = 0; m < 4; ++m) _Pragma("unroll") for (int k = 0; k < 2; ++k) dst[m][k] = *(const PG8_LAS bf16x8*)(lds + PG8_SA(b, h) + aoff + m * 2048 + k * 1024); } while (0)
; #define PG8_LDB(dst, b, h) do { _Pragma("unroll") for (int n = 0; n < 2; ++n) _Pragma("unroll") for (int k = 0; k < 2; ++k) dst[n][k] = *(const PG8_LAS bf16x8*)(lds + PG8_SB(b, h) + boff + n * 2048 + k * 1024); } while (0)
; #define PG8_WAIT_V(n) asm volatile("s_waitcnt vmcnt(" #n ")" ::: "memory")
; #define PG8_WAIT_L(n) asm volatile("s_waitcnt lgkmcnt(" #n ")" ::: "memory")
; #define PG8_BAR __builtin_amdgcn_s_barrier()
; #define PG8_SCHED __builtin_amdgcn_sched_barrier(0)
; template <class Epi, class Sched, bool ALIGN_EPI = false, bool SP2 = false>
; __device__ __forceinline__ void gemm_phase(PG8_LAS unsigned char* lds, const Gemm g, const Sched& S, const Epi& E) {
;     ...
;         const char* nA = has_next ? (const char*)g.A + (size_t)nxt.pm * tstep : cA; const char* nB = has_next ? (const char*)g.Bt + (size_t)nxt.pn * tstep : cB;
;         for (int t = 0; t < nt; t += 2) {
;             const bool last = (t == nt - 2);
;             const char* a1 = cA + (size_t)(t + 1) * kstep;
;             const char* a2 = last ? nA : cA + (size_t)(t + 2) * kstep; const char* b2 = last ? nB : cB + (size_t)(t + 2) * kstep;
;             const char* a3 = a2 + kstep; const char* b3 = b2 + kstep;
;             if (last && has_next) S.a_ready(nxt);
;             if constexpr (SP2) {
;             PG8_LDB(B0, 0, 0); PG8_LDB(B1, 0, 1); PG8_SCHED; PG8_LDA(At, 0, 0); PG8_STAGE(PG8_SA(1, 1), a1 + hstep, voffA);
;             PG8_WAIT_V(8); PG8_WAIT_L(0); PG8_BAR; PG8_MMA(0, 0, At, B0); PG8_MMA(0, 1, At, B1); PG8_BAR; PG8_SCHED;
;             PG8_LDA(At, 0, 1); PG8_STAGE(PG8_SB(0, 0), b2, voffB); PG8_STAGE(PG8_SB(0, 1), b2 + hstep, voffB); PG8_STAGE(PG8_SA(0, 0), a2, voffA);
;             PG8_WAIT_V(8); PG8_WAIT_L(0); PG8_BAR; PG8_MMA(1, 0, At, B0); PG8_MMA(1, 1, At, B1); PG8_BAR; PG8_SCHED;
.LBB0_121:
	s_add_u32 s22, s46, 0x100
	s_addc_u32 s33, s47, 0
	s_mov_b32 s50, -2
	s_add_u32 s42, s44, 0x100
	s_addc_u32 s43, s45, 0
	s_add_i32 s24, 0, 0x10000
	s_cmp_eq_u32 s50, 8
	s_cselect_b32 s69, s65, s43
	s_cselect_b32 s68, s64, s42
	s_cselect_b32 s47, s67, s33
	s_cselect_b32 s46, s66, s22
	s_add_i32 s51, 0, 0x14000
	v_add_u32_e32 v162, s24, v150
	v_add_u32_e32 v170, s51, v150
	ds_read_b128 v[146:149], v162
	ds_read_b128 v[154:157], v162 offset:1024
	ds_read_b128 v[158:161], v162 offset:2048
	ds_read_b128 v[162:165], v162 offset:3072
	ds_read_b128 v[166:169], v170
	ds_read_b128 v[192:195], v170 offset:1024
	ds_read_b128 v[196:199], v170 offset:2048
	ds_read_b128 v[200:203], v170 offset:3072
	v_lshl_add_u64 v[170:171], s[44:45], 0, v[142:143]
	s_add_i32 m0, s71, 0xc000
	ds_read_b128 v[204:207], v153
	ds_read_b128 v[208:211], v153 offset:1024
	ds_read_b128 v[212:215], v153 offset:2048
	ds_read_b128 v[216:219], v153 offset:3072
	ds_read_b128 v[220:223], v153 offset:4096
	ds_read_b128 v[224:227], v153 offset:5120
	ds_read_b128 v[228:231], v153 offset:6144
	ds_read_b128 v[232:235], v153 offset:7168
	global_load_lds_dwordx4 v[170:171], off
	v_lshl_add_u64 v[170:171], s[44:45], 0, v[144:145]
	s_add_i32 m0, s71, 0xe000
	s_nop 0
	global_load_lds_dwordx4 v[170:171], off
	s_waitcnt vmcnt(8)
	s_waitcnt lgkmcnt(0)
	s_barrier
	s_setprio 1
	s_waitcnt lgkmcnt(0)
	v_mfma_f32_16x16x32_bf16 v[124:127], v[146:149], v[204:207], 0
	v_mfma_f32_16x16x32_bf16 v[120:123], v[158:161], v[204:207], 0
	v_mfma_f32_16x16x32_bf16 v[108:111], v[146:149], v[212:215], 0
	v_mfma_f32_16x16x32_bf16 v[104:107], v[158:161], v[212:215], 0
	v_mfma_f32_16x16x32_bf16 v[92:95], v[146:149], v[220:223], 0
	v_mfma_f32_16x16x32_bf16 v[88:91], v[158:161], v[220:223], 0
	v_mfma_f32_16x16x32_bf16 v[76:79], v[146:149], v[228:231], 0
	v_mfma_f32_16x16x32_bf16 v[72:75], v[158:161], v[228:231], 0
	v_mfma_f32_16x16x32_bf16 v[124:127], v[154:157], v[208:211], v[124:127]
	v_mfma_f32_16x16x32_bf16 v[120:123], v[162:165], v[208:211], v[120:123]
	v_mfma_f32_16x16x32_bf16 v[108:111], v[154:157], v[216:219], v[108:111]
	v_mfma_f32_16x16x32_bf16 v[104:107], v[162:165], v[216:219], v[104:107]
	v_mfma_f32_16x16x32_bf16 v[92:95], v[154:157], v[224:227], v[92:95]
	v_mfma_f32_16x16x32_bf16 v[88:91], v[162:165], v[224:227], v[88:91]
	v_mfma_f32_16x16x32_bf16 v[76:79], v[154:157], v[232:235], v[76:79]
	v_mfma_f32_16x16x32_bf16 v[72:75], v[162:165], v[232:235], v[72:75]
	s_setprio 0
	s_setprio 1
	v_mfma_f32_16x16x32_bf16 v[116:119], v[166:169], v[204:207], 0
	v_mfma_f32_16x16x32_bf16 v[112:115], v[196:199], v[204:207], 0
	v_mfma_f32_16x16x32_bf16 v[100:103], v[166:169], v[212:215], 0
	v_mfma_f32_16x16x32_bf16 v[96:99], v[196:199], v[212:215], 0
	v_mfma_f32_16x16x32_bf16 v[84:87], v[166:169], v[220:223], 0
	v_mfma_f32_16x16x32_bf16 v[80:83], v[196:199], v[220:223], 0
	v_mfma_f32_16x16x32_bf16 v[68:71], v[166:169], v[228:231], 0
	v_mfma_f32_16x16x32_bf16 v[64:67], v[196:199], v[228:231], 0
	v_mfma_f32_16x16x32_bf16 v[116:119], v[192:195], v[208:211], v[116:119]
	v_mfma_f32_16x16x32_bf16 v[112:115], v[200:203], v[208:211], v[112:115]
	v_mfma_f32_16x16x32_bf16 v[100:103], v[192:195], v[216:219], v[100:103]
	v_mfma_f32_16x16x32_bf16 v[96:99], v[200:203], v[216:219], v[96:99]
	v_mfma_f32_16x16x32_bf16 v[84:87], v[192:195], v[224:227], v[84:87]
	v_mfma_f32_16x16x32_bf16 v[80:83], v[200:203], v[224:227], v[80:83]
	v_mfma_f32_16x16x32_bf16 v[68:71], v[192:195], v[232:235], v[68:71]
	v_mfma_f32_16x16x32_bf16 v[64:67], v[200:203], v[232:235], v[64:67]
	s_setprio 0
	s_barrier
	s_add_i32 s24, s24, s29
	v_lshl_add_u64 v[170:171], s[46:47], 0, v[128:129]
	s_mov_b32 m0, s24
	ds_read_b128 v[204:207], v153 offset:16384
	ds_read_b128 v[208:211], v153 offset:17408
	ds_read_b128 v[212:215], v153 offset:18432
	ds_read_b128 v[216:219], v153 offset:19456
	ds_read_b128 v[220:223], v153 offset:20480
	ds_read_b128 v[224:227], v153 offset:21504
	ds_read_b128 v[228:231], v153 offset:22528
	ds_read_b128 v[232:235], v153 offset:23552
	global_load_lds_dwordx4 v[170:171], off
	s_add_i32 m0, s24, 0x2000
	s_add_u32 s24, s46, 0x30000
	v_lshl_add_u64 v[236:237], s[46:47], 0, v[130:131]
	s_addc_u32 s25, s47, 0
	s_add_i32 s44, s51, s29
	global_load_lds_dwordx4 v[236:237], off
	v_lshl_add_u64 v[238:239], s[24:25], 0, v[128:129]
	s_mov_b32 m0, s44
	v_lshl_add_u64 v[240:241], s[68:69], 0, v[130:131]
	global_load_lds_dwordx4 v[238:239], off
	v_lshl_add_u64 v[238:239], s[24:25], 0, v[130:131]
	s_add_i32 m0, s44, 0x2000
	s_nop 0
	global_load_lds_dwordx4 v[238:239], off
	v_lshl_add_u64 v[238:239], s[68:69], 0, v[128:129]
	s_mov_b32 m0, s71
	s_nop 0
	global_load_lds_dwordx4 v[238:239], off
	s_mov_b32 m0, s87
	s_nop 0
	global_load_lds_dwordx4 v[240:241], off
	s_waitcnt vmcnt(8)
	s_waitcnt lgkmcnt(0)
	s_barrier
; #define PG8_STAGE(bufoff, gbase, voff) do { _Pragma("unroll") for (int _i = 0; _i < 2; ++_i) \
;         __builtin_amdgcn_global_load_lds((const unsigned*)((const char*)(gbase) + (voff)[_i]), (PG8_LAS unsigned*)(lds + (bufoff) + ldsw + _i * 8192), 16, 0, 0); } while (0)
; #define PG8_LDA(dst, b, h) do { _Pragma("unroll") for (int m = 0; m < 4; ++m) _Pragma("unroll") for (int k = 0; k < 2; ++k) dst[m][k] = *(const PG8_LAS bf16x8*)(lds + PG8_SA(b, h) + aoff + m * 2048 + k * 1024); } while (0)
; #define PG8_LDB(dst, b, h) do { _Pragma("unroll") for (int n = 0; n < 2; ++n) _Pragma("unroll") for (int k = 0; k < 2; ++k) dst[n][k] = *(const PG8_LAS bf16x8*)(lds + PG8_SB(b, h) + boff + n * 2048 + k * 1024); } while (0)
; #define PG8_MMA(ai, bj, At, Bt) do { __builtin_amdgcn_s_setprio(1); _Pragma("unroll") for (int m = 0; m < 4; ++m) _Pragma("unroll") for (int n = 0; n < 2; ++n) _Pragma("unroll") for (int k = 0; k < 2; ++k) \
;         acc[ai][bj][m][n] = __builtin_amdgcn_mfma_f32_16x16x32_bf16(Bt[n][k], At[m][k], acc[ai][bj][m][n], 0, 0, 0); __builtin_amdgcn_s_setprio(0); } while (0)
; #define PG8_WAIT_V(n) asm volatile("s_waitcnt vmcnt(" #n ")" ::: "memory")
; #define PG8_WAIT_L(n) asm volatile("s_waitcnt lgkmcnt(" #n ")" ::: "memory")
; #define PG8_BAR __builtin_amdgcn_s_barrier()
; #define PG8_SCHED __builtin_amdgcn_sched_barrier(0)
; template <class Epi, class Sched, bool ALIGN_EPI = false, bool SP2 = false>
; __device__ __forceinline__ void gemm_phase(PG8_LAS unsigned char* lds, const Gemm g, const Sched& S, const Epi& E) {
;     ...
;             PG8_WAIT_V(8); PG8_WAIT_L(0); PG8_BAR; PG8_MMA(1, 0, At, B0); PG8_MMA(1, 1, At, B1); PG8_BAR; PG8_SCHED;
;             PG8_LDB(B0, 1, 0); PG8_LDB(B1, 1, 1); PG8_SCHED; PG8_LDA(At, 1, 0); PG8_STAGE(PG8_SA(0, 1), a2 + hstep, voffA);
;             PG8_WAIT_V(8); PG8_WAIT_L(0); PG8_BAR; PG8_MMA(0, 0, At, B0); PG8_MMA(0, 1, At, B1); PG8_BAR; PG8_SCHED;
	s_setprio 1
	s_waitcnt lgkmcnt(0)
	v_mfma_f32_16x16x32_bf16 v[60:63], v[146:149], v[204:207], 0
	v_mfma_f32_16x16x32_bf16 v[56:59], v[158:161], v[204:207], 0
	v_mfma_f32_16x16x32_bf16 v[44:47], v[146:149], v[212:215], 0
	v_mfma_f32_16x16x32_bf16 v[40:43], v[158:161], v[212:215], 0
	v_mfma_f32_16x16x32_bf16 v[28:31], v[146:149], v[220:223], 0
	v_mfma_f32_16x16x32_bf16 v[24:27], v[158:161], v[220:223], 0
	v_mfma_f32_16x16x32_bf16 v[12:15], v[146:149], v[228:231], 0
	v_mfma_f32_16x16x32_bf16 v[8:11], v[158:161], v[228:231], 0
	v_mfma_f32_16x16x32_bf16 v[60:63], v[154:157], v[208:211], v[60:63]
	v_mfma_f32_16x16x32_bf16 v[56:59], v[162:165], v[208:211], v[56:59]
	v_mfma_f32_16x16x32_bf16 v[44:47], v[154:157], v[216:219], v[44:47]
	v_mfma_f32_16x16x32_bf16 v[40:43], v[162:165], v[216:219], v[40:43]
	v_mfma_f32_16x16x32_bf16 v[28:31], v[154:157], v[224:227], v[28:31]
	v_mfma_f32_16x16x32_bf16 v[24:27], v[162:165], v[224:227], v[24:27]
	v_mfma_f32_16x16x32_bf16 v[12:15], v[154:157], v[232:235], v[12:15]
	v_mfma_f32_16x16x32_bf16 v[8:11], v[162:165], v[232:235], v[8:11]
	s_setprio 0
	s_setprio 1
	v_mfma_f32_16x16x32_bf16 v[52:55], v[166:169], v[204:207], 0
	v_mfma_f32_16x16x32_bf16 v[48:51], v[196:199], v[204:207], 0
	v_mfma_f32_16x16x32_bf16 v[36:39], v[166:169], v[212:215], 0
	v_mfma_f32_16x16x32_bf16 v[32:35], v[196:199], v[212:215], 0
	v_mfma_f32_16x16x32_bf16 v[20:23], v[166:169], v[220:223], 0
	v_mfma_f32_16x16x32_bf16 v[16:19], v[196:199], v[220:223], 0
	v_mfma_f32_16x16x32_bf16 v[4:7], v[166:169], v[228:231], 0
	v_mfma_f32_16x16x32_bf16 v[0:3], v[196:199], v[228:231], 0
	v_mfma_f32_16x16x32_bf16 v[52:55], v[192:195], v[208:211], v[52:55]
	v_mfma_f32_16x16x32_bf16 v[48:51], v[200:203], v[208:211], v[48:51]
	v_mfma_f32_16x16x32_bf16 v[36:39], v[192:195], v[216:219], v[36:39]
	v_mfma_f32_16x16x32_bf16 v[32:35], v[200:203], v[216:219], v[32:35]
	v_mfma_f32_16x16x32_bf16 v[20:23], v[192:195], v[224:227], v[20:23]
	v_mfma_f32_16x16x32_bf16 v[16:19], v[200:203], v[224:227], v[16:19]
	v_mfma_f32_16x16x32_bf16 v[4:7], v[192:195], v[232:235], v[4:7]
	v_mfma_f32_16x16x32_bf16 v[0:3], v[200:203], v[232:235], v[0:3]
	s_setprio 0
	s_barrier
	s_add_i32 s44, 0, 0x18000
	s_add_i32 s45, 0, 0x1c000
	v_add_u32_e32 v162, s44, v150
	v_add_u32_e32 v184, s45, v150
	ds_read_b128 v[146:149], v162
	ds_read_b128 v[154:157], v162 offset:1024
	ds_read_b128 v[158:161], v162 offset:2048
	ds_read_b128 v[162:165], v162 offset:3072
	ds_read_b128 v[166:169], v184
	ds_read_b128 v[192:195], v184 offset:1024
	ds_read_b128 v[196:199], v184 offset:2048
	ds_read_b128 v[200:203], v184 offset:3072
	s_add_u32 s24, s68, 0x30000
	s_addc_u32 s25, s69, 0
	s_mov_b32 m0, s88
	v_lshl_add_u64 v[242:243], s[24:25], 0, v[128:129]
	ds_read_b128 v[204:207], v153 offset:32768
	ds_read_b128 v[208:211], v153 offset:33792
	ds_read_b128 v[212:215], v153 offset:34816
	ds_read_b128 v[216:219], v153 offset:35840
	ds_read_b128 v[220:223], v153 offset:36864
	ds_read_b128 v[224:227], v153 offset:37888
	ds_read_b128 v[228:231], v153 offset:38912
	ds_read_b128 v[232:235], v153 offset:39936
	global_load_lds_dwordx4 v[242:243], off
	v_lshl_add_u64 v[242:243], s[24:25], 0, v[130:131]
	s_mov_b32 m0, s89
	s_nop 0
	global_load_lds_dwordx4 v[242:243], off
	s_waitcnt vmcnt(8)
	s_waitcnt lgkmcnt(0)
	s_barrier
	s_setprio 1
	s_waitcnt lgkmcnt(0)
	v_mfma_f32_16x16x32_bf16 v[124:127], v[146:149], v[204:207], v[124:127]
	v_mfma_f32_16x16x32_bf16 v[120:123], v[158:161], v[204:207], v[120:123]
	v_mfma_f32_16x16x32_bf16 v[108:111], v[146:149], v[212:215], v[108:111]
	v_mfma_f32_16x16x32_bf16 v[104:107], v[158:161], v[212:215], v[104:107]
	v_mfma_f32_16x16x32_bf16 v[92:95], v[146:149], v[220:223], v[92:95]
	v_mfma_f32_16x16x32_bf16 v[88:91], v[158:161], v[220:223], v[88:91]
	v_mfma_f32_16x16x32_bf16 v[76:79], v[146:149], v[228:231], v[76:79]
	v_mfma_f32_16x16x32_bf16 v[72:75], v[158:161], v[228:231], v[72:75]
	v_mfma_f32_16x16x32_bf16 v[124:127], v[154:157], v[208:211], v[124:127]
	v_mfma_f32_16x16x32_bf16 v[120:123], v[162:165], v[208:211], v[120:123]
	v_mfma_f32_16x16x32_bf16 v[108:111], v[154:157], v[216:219], v[108:111]
	v_mfma_f32_16x16x32_bf16 v[104:107], v[162:165], v[216:219], v[104:107]
	v_mfma_f32_16x16x32_bf16 v[92:95], v[154:157], v[224:227], v[92:95]
	v_mfma_f32_16x16x32_bf16 v[88:91], v[162:165], v[224:227], v[88:91]
	v_mfma_f32_16x16x32_bf16 v[76:79], v[154:157], v[232:235], v[76:79]
	v_mfma_f32_16x16x32_bf16 v[72:75], v[162:165], v[232:235], v[72:75]
	s_setprio 0
	s_setprio 1
	v_mfma_f32_16x16x32_bf16 v[116:119], v[166:169], v[204:207], v[116:119]
	v_mfma_f32_16x16x32_bf16 v[112:115], v[196:199], v[204:207], v[112:115]
	v_mfma_f32_16x16x32_bf16 v[100:103], v[166:169], v[212:215], v[100:103]
	v_mfma_f32_16x16x32_bf16 v[96:99], v[196:199], v[212:215], v[96:99]
	v_mfma_f32_16x16x32_bf16 v[84:87], v[166:169], v[220:223], v[84:87]
	v_mfma_f32_16x16x32_bf16 v[80:83], v[196:199], v[220:223], v[80:83]
	v_mfma_f32_16x16x32_bf16 v[68:71], v[166:169], v[228:231], v[68:71]
	v_mfma_f32_16x16x32_bf16 v[64:67], v[196:199], v[228:231], v[64:67]
	v_mfma_f32_16x16x32_bf16 v[116:119], v[192:195], v[208:211], v[116:119]
	v_mfma_f32_16x16x32_bf16 v[112:115], v[200:203], v[208:211], v[112:115]
	v_mfma_f32_16x16x32_bf16 v[100:103], v[192:195], v[216:219], v[100:103]
	v_mfma_f32_16x16x32_bf16 v[96:99], v[200:203], v[216:219], v[96:99]
	v_mfma_f32_16x16x32_bf16 v[84:87], v[192:195], v[224:227], v[84:87]
	v_mfma_f32_16x16x32_bf16 v[80:83], v[200:203], v[224:227], v[80:83]
	v_mfma_f32_16x16x32_bf16 v[68:71], v[192:195], v[232:235], v[68:71]
	v_mfma_f32_16x16x32_bf16 v[64:67], v[200:203], v[232:235], v[64:67]
	s_setprio 0
	s_barrier
; #define PG8_STAGE(bufoff, gbase, voff) do { _Pragma("unroll") for (int _i = 0; _i < 2; ++_i) \
;         __builtin_amdgcn_global_load_lds((const unsigned*)((const char*)(gbase) + (voff)[_i]), (PG8_LAS unsigned*)(lds + (bufoff) + ldsw + _i * 8192), 16, 0, 0); } while (0)
; #define PG8_LDA(dst, b, h) do { _Pragma("unroll") for (int m = 0; m < 4; ++m) _Pragma("unroll") for (int k = 0; k < 2; ++k) dst[m][k] = *(const PG8_LAS bf16x8*)(lds + PG8_SA(b, h) + aoff + m * 2048 + k * 1024); } while (0)
; #define PG8_LDB(dst, b, h) do { _Pragma("unroll") for (int n = 0; n < 2; ++n) _Pragma("unroll") for (int k = 0; k < 2; ++k) dst[n][k] = *(const PG8_LAS bf16x8*)(lds + PG8_SB(b, h) + boff + n * 2048 + k * 1024); } while (0)
; template <class Epi, class Sched, bool ALIGN_EPI = false, bool SP2 = false>
; __device__ __forceinline__ void gemm_phase(PG8_LAS unsigned char* lds, const Gemm g, const Sched& S, const Epi& E) {
;     ...
;         for (int t = 0; t < nt; t += 2) {
;             const bool last = (t == nt - 2);
;             const char* a1 = cA + (size_t)(t + 1) * kstep;
;             const char* a2 = last ? nA : cA + (size_t)(t + 2) * kstep; const char* b2 = last ? nB : cB + (size_t)(t + 2) * kstep;
;             const char* a3 = a2 + kstep; const char* b3 = b2 + kstep;
;             if (last && has_next) S.a_ready(nxt);
;             if constexpr (SP2) {
;             PG8_LDB(B0, 0, 0); PG8_LDB(B1, 0, 1); PG8_SCHED; PG8_LDA(At, 0, 0); PG8_STAGE(PG8_SA(1, 1), a1 + hstep, voffA);
;             PG8_WAIT_V(8); PG8_WAIT_L(0); PG8_BAR; PG8_MMA(0, 0, At, B0); PG8_MMA(0, 1, At, B1); PG8_BAR; PG8_SCHED;
;             PG8_LDA(At, 0, 1); PG8_STAGE(PG8_SB(0, 0), b2, voffB); PG8_STAGE(PG8_SB(0, 1), b2 + hstep, voffB); PG8_STAGE(PG8_SA(0, 0), a2, voffA);
;             PG8_WAIT_V(8); PG8_WAIT_L(0); PG8_BAR; PG8_MMA(1, 0, At, B0); PG8_MMA(1, 1, At, B1); PG8_BAR; PG8_SCHED;
;             PG8_LDB(B0, 1, 0); PG8_LDB(B1, 1, 1); PG8_SCHED; PG8_LDA(At, 1, 0); PG8_STAGE(PG8_SA(0, 1), a2 + hstep, voffA);
;             PG8_WAIT_V(8); PG8_WAIT_L(0); PG8_BAR; PG8_MMA(0, 0, At, B0); PG8_MMA(0, 1, At, B1); PG8_BAR; PG8_SCHED;
;             PG8_LDA(At, 1, 1); PG8_STAGE(PG8_SB(1, 0), b3, voffB); PG8_STAGE(PG8_SB(1, 1), b3 + hstep, voffB); PG8_STAGE(PG8_SA(1, 0), a3, voffA);
;             PG8_WAIT_V(8); PG8_WAIT_L(0); PG8_BAR; PG8_MMA(1, 0, At, B0); PG8_MMA(1, 1, At, B1); PG8_BAR; PG8_SCHED;
	s_add_i32 s24, s44, s29
	v_lshl_add_u64 v[170:171], v[170:171], 0, s[14:15]
	s_mov_b32 m0, s24
	ds_read_b128 v[204:207], v153 offset:49152
	ds_read_b128 v[208:211], v153 offset:50176
	ds_read_b128 v[212:215], v153 offset:51200
	ds_read_b128 v[216:219], v153 offset:52224
	ds_read_b128 v[220:223], v153 offset:53248
	ds_read_b128 v[224:227], v153 offset:54272
	ds_read_b128 v[228:231], v153 offset:55296
	ds_read_b128 v[232:235], v153 offset:56320
	global_load_lds_dwordx4 v[170:171], off
	s_add_i32 m0, s24, 0x2000
	s_add_u32 s24, s46, 0x30080
	v_lshl_add_u64 v[170:171], v[236:237], 0, s[14:15]
	s_addc_u32 s25, s47, 0
	s_add_i32 s44, s45, s29
	global_load_lds_dwordx4 v[170:171], off
	v_lshl_add_u64 v[170:171], s[24:25], 0, v[128:129]
	s_mov_b32 m0, s44
	s_nop 0
	global_load_lds_dwordx4 v[170:171], off
	v_lshl_add_u64 v[170:171], s[24:25], 0, v[130:131]
	s_add_i32 m0, s44, 0x2000
	s_nop 0
	global_load_lds_dwordx4 v[170:171], off
	v_lshl_add_u64 v[170:171], v[238:239], 0, s[14:15]
	s_mov_b32 m0, s91
	s_nop 0
	global_load_lds_dwordx4 v[170:171], off
	v_lshl_add_u64 v[170:171], v[240:241], 0, s[14:15]
	s_mov_b32 m0, s92
	s_nop 0
	global_load_lds_dwordx4 v[170:171], off
	s_waitcnt vmcnt(8)
	s_waitcnt lgkmcnt(0)
	s_barrier
	s_setprio 1
	s_waitcnt lgkmcnt(0)
	v_mfma_f32_16x16x32_bf16 v[60:63], v[146:149], v[204:207], v[60:63]
	v_mfma_f32_16x16x32_bf16 v[56:59], v[158:161], v[204:207], v[56:59]
	v_mfma_f32_16x16x32_bf16 v[44:47], v[146:149], v[212:215], v[44:47]
	v_mfma_f32_16x16x32_bf16 v[40:43], v[158:161], v[212:215], v[40:43]
	v_mfma_f32_16x16x32_bf16 v[28:31], v[146:149], v[220:223], v[28:31]
	v_mfma_f32_16x16x32_bf16 v[24:27], v[158:161], v[220:223], v[24:27]
	v_mfma_f32_16x16x32_bf16 v[12:15], v[146:149], v[228:231], v[12:15]
	v_mfma_f32_16x16x32_bf16 v[8:11], v[158:161], v[228:231], v[8:11]
	v_mfma_f32_16x16x32_bf16 v[60:63], v[154:157], v[208:211], v[60:63]
	v_mfma_f32_16x16x32_bf16 v[56:59], v[162:165], v[208:211], v[56:59]
	v_mfma_f32_16x16x32_bf16 v[44:47], v[154:157], v[216:219], v[44:47]
	v_mfma_f32_16x16x32_bf16 v[40:43], v[162:165], v[216:219], v[40:43]
	v_mfma_f32_16x16x32_bf16 v[28:31], v[154:157], v[224:227], v[28:31]
	v_mfma_f32_16x16x32_bf16 v[24:27], v[162:165], v[224:227], v[24:27]
	v_mfma_f32_16x16x32_bf16 v[12:15], v[154:157], v[232:235], v[12:15]
	v_mfma_f32_16x16x32_bf16 v[8:11], v[162:165], v[232:235], v[8:11]
	s_setprio 0
	s_setprio 1
	v_mfma_f32_16x16x32_bf16 v[52:55], v[166:169], v[204:207], v[52:55]
	v_mfma_f32_16x16x32_bf16 v[48:51], v[196:199], v[204:207], v[48:51]
	v_mfma_f32_16x16x32_bf16 v[36:39], v[166:169], v[212:215], v[36:39]
	v_mfma_f32_16x16x32_bf16 v[32:35], v[196:199], v[212:215], v[32:35]
	v_mfma_f32_16x16x32_bf16 v[20:23], v[166:169], v[220:223], v[20:23]
	v_mfma_f32_16x16x32_bf16 v[16:19], v[196:199], v[220:223], v[16:19]
	v_mfma_f32_16x16x32_bf16 v[4:7], v[166:169], v[228:231], v[4:7]
	v_mfma_f32_16x16x32_bf16 v[0:3], v[196:199], v[228:231], v[0:3]
	v_mfma_f32_16x16x32_bf16 v[52:55], v[192:195], v[208:211], v[52:55]
	v_mfma_f32_16x16x32_bf16 v[48:51], v[200:203], v[208:211], v[48:51]
	v_mfma_f32_16x16x32_bf16 v[36:39], v[192:195], v[216:219], v[36:39]
	v_mfma_f32_16x16x32_bf16 v[32:35], v[200:203], v[216:219], v[32:35]
	v_mfma_f32_16x16x32_bf16 v[20:23], v[192:195], v[224:227], v[20:23]
	v_mfma_f32_16x16x32_bf16 v[16:19], v[200:203], v[224:227], v[16:19]
	v_mfma_f32_16x16x32_bf16 v[4:7], v[192:195], v[232:235], v[4:7]
	v_mfma_f32_16x16x32_bf16 v[0:3], v[200:203], v[232:235], v[0:3]
	s_setprio 0
	s_add_i32 s50, s50, 2
	s_add_u32 s22, s22, 0x100
	s_addc_u32 s33, s33, 0
	s_cmp_gt_u32 s50, 9
	s_mov_b64 s[44:45], s[42:43]
	s_barrier
.LBB0_122:
	s_add_u32 s42, s44, 0x100
	s_addc_u32 s43, s45, 0
	s_add_i32 s24, 0, 0x10000
	s_cmp_eq_u32 s50, 8
	s_cselect_b32 s69, s65, s43
	s_cselect_b32 s68, s64, s42
	s_cselect_b32 s47, s67, s33
	s_cselect_b32 s46, s66, s22
	s_add_i32 s51, 0, 0x14000
	v_add_u32_e32 v162, s24, v150
	v_add_u32_e32 v170, s51, v150
	ds_read_b128 v[146:149], v162
	ds_read_b128 v[154:157], v162 offset:1024
	ds_read_b128 v[158:161], v162 offset:2048
	ds_read_b128 v[162:165], v162 offset:3072
	ds_read_b128 v[166:169], v170
	ds_read_b128 v[192:195], v170 offset:1024
	ds_read_b128 v[196:199], v170 offset:2048
	ds_read_b128 v[200:203], v170 offset:3072
	v_lshl_add_u64 v[170:171], s[44:45], 0, v[142:143]
	s_add_i32 m0, s71, 0xc000
	ds_read_b128 v[204:207], v153
	ds_read_b128 v[208:211], v153 offset:1024
	ds_read_b128 v[212:215], v153 offset:2048
	ds_read_b128 v[216:219], v153 offset:3072
	ds_read_b128 v[220:223], v153 offset:4096
	ds_read_b128 v[224:227], v153 offset:5120
	ds_read_b128 v[228:231], v153 offset:6144
	ds_read_b128 v[232:235], v153 offset:7168
	global_load_lds_dwordx4 v[170:171], off
	v_lshl_add_u64 v[170:171], s[44:45], 0, v[144:145]
	s_add_i32 m0, s71, 0xe000
	s_nop 0
	global_load_lds_dwordx4 v[170:171], off
	s_waitcnt vmcnt(8)
	s_waitcnt lgkmcnt(0)
	s_barrier
; #define PG8_STAGE(bufoff, gbase, voff) do { _Pragma("unroll") for (int _i = 0; _i < 2; ++_i) \
;         __builtin_amdgcn_global_load_lds((const unsigned*)((const char*)(gbase) + (voff)[_i]), (PG8_LAS unsigned*)(lds + (bufoff) + ldsw + _i * 8192), 16, 0, 0); } while (0)
; #define PG8_LDA(dst, b, h) do { _Pragma("unroll") for (int m = 0; m < 4; ++m) _Pragma("unroll") for (int k = 0; k < 2; ++k) dst[m][k] = *(const PG8_LAS bf16x8*)(lds + PG8_SA(b, h) + aoff + m * 2048 + k * 1024); } while (0)
; #define PG8_MMA(ai, bj, At, Bt) do { __builtin_amdgcn_s_setprio(1); _Pragma("unroll") for (int m = 0; m < 4; ++m) _Pragma("unroll") for (int n = 0; n < 2; ++n) _Pragma("unroll") for (int k = 0; k < 2; ++k) \
;         acc[ai][bj][m][n] = __builtin_amdgcn_mfma_f32_16x16x32_bf16(Bt[n][k], At[m][k], acc[ai][bj][m][n], 0, 0, 0); __builtin_amdgcn_s_setprio(0); } while (0)
; #define PG8_WAIT_V(n) asm volatile("s_waitcnt vmcnt(" #n ")" ::: "memory")
; #define PG8_WAIT_L(n) asm volatile("s_waitcnt lgkmcnt(" #n ")" ::: "memory")
; #define PG8_BAR __builtin_amdgcn_s_barrier()
; #define PG8_SCHED __builtin_amdgcn_sched_barrier(0)
; template <class Epi, class Sched, bool ALIGN_EPI = false, bool SP2 = false>
; __device__ __forceinline__ void gemm_phase(PG8_LAS unsigned char* lds, const Gemm g, const Sched& S, const Epi& E) {
;     ...
;             PG8_WAIT_V(8); PG8_WAIT_L(0); PG8_BAR; PG8_MMA(0, 0, At, B0); PG8_MMA(0, 1, At, B1); PG8_BAR; PG8_SCHED;
;             PG8_LDA(At, 0, 1); PG8_STAGE(PG8_SB(0, 0), b2, voffB); PG8_STAGE(PG8_SB(0, 1), b2 + hstep, voffB); PG8_STAGE(PG8_SA(0, 0), a2, voffA);
;             PG8_WAIT_V(8); PG8_WAIT_L(0); PG8_BAR; PG8_MMA(1, 0, At, B0); PG8_MMA(1, 1, At, B1); PG8_BAR; PG8_SCHED;
	s_setprio 1
	s_waitcnt lgkmcnt(0)
	v_mfma_f32_16x16x32_bf16 v[124:127], v[146:149], v[204:207], v[124:127]
	v_mfma_f32_16x16x32_bf16 v[120:123], v[158:161], v[204:207], v[120:123]
	v_mfma_f32_16x16x32_bf16 v[108:111], v[146:149], v[212:215], v[108:111]
	v_mfma_f32_16x16x32_bf16 v[104:107], v[158:161], v[212:215], v[104:107]
	v_mfma_f32_16x16x32_bf16 v[92:95], v[146:149], v[220:223], v[92:95]
	v_mfma_f32_16x16x32_bf16 v[88:91], v[158:161], v[220:223], v[88:91]
	v_mfma_f32_16x16x32_bf16 v[76:79], v[146:149], v[228:231], v[76:79]
	v_mfma_f32_16x16x32_bf16 v[72:75], v[158:161], v[228:231], v[72:75]
	v_mfma_f32_16x16x32_bf16 v[124:127], v[154:157], v[208:211], v[124:127]
	v_mfma_f32_16x16x32_bf16 v[120:123], v[162:165], v[208:211], v[120:123]
	v_mfma_f32_16x16x32_bf16 v[108:111], v[154:157], v[216:219], v[108:111]
	v_mfma_f32_16x16x32_bf16 v[104:107], v[162:165], v[216:219], v[104:107]
	v_mfma_f32_16x16x32_bf16 v[92:95], v[154:157], v[224:227], v[92:95]
	v_mfma_f32_16x16x32_bf16 v[88:91], v[162:165], v[224:227], v[88:91]
	v_mfma_f32_16x16x32_bf16 v[76:79], v[154:157], v[232:235], v[76:79]
	v_mfma_f32_16x16x32_bf16 v[72:75], v[162:165], v[232:235], v[72:75]
	s_setprio 0
	s_setprio 1
	v_mfma_f32_16x16x32_bf16 v[116:119], v[166:169], v[204:207], v[116:119]
	v_mfma_f32_16x16x32_bf16 v[112:115], v[196:199], v[204:207], v[112:115]
	v_mfma_f32_16x16x32_bf16 v[100:103], v[166:169], v[212:215], v[100:103]
	v_mfma_f32_16x16x32_bf16 v[96:99], v[196:199], v[212:215], v[96:99]
	v_mfma_f32_16x16x32_bf16 v[84:87], v[166:169], v[220:223], v[84:87]
	v_mfma_f32_16x16x32_bf16 v[80:83], v[196:199], v[220:223], v[80:83]
	v_mfma_f32_16x16x32_bf16 v[68:71], v[166:169], v[228:231], v[68:71]
	v_mfma_f32_16x16x32_bf16 v[64:67], v[196:199], v[228:231], v[64:67]
	v_mfma_f32_16x16x32_bf16 v[116:119], v[192:195], v[208:211], v[116:119]
	v_mfma_f32_16x16x32_bf16 v[112:115], v[200:203], v[208:211], v[112:115]
	v_mfma_f32_16x16x32_bf16 v[100:103], v[192:195], v[216:219], v[100:103]
	v_mfma_f32_16x16x32_bf16 v[96:99], v[200:203], v[216:219], v[96:99]
	v_mfma_f32_16x16x32_bf16 v[84:87], v[192:195], v[224:227], v[84:87]
	v_mfma_f32_16x16x32_bf16 v[80:83], v[200:203], v[224:227], v[80:83]
	v_mfma_f32_16x16x32_bf16 v[68:71], v[192:195], v[232:235], v[68:71]
	v_mfma_f32_16x16x32_bf16 v[64:67], v[200:203], v[232:235], v[64:67]
	s_setprio 0
	s_barrier
	s_add_i32 s24, s24, s29
	v_lshl_add_u64 v[170:171], s[46:47], 0, v[128:129]
	s_mov_b32 m0, s24
	ds_read_b128 v[204:207], v153 offset:16384
	ds_read_b128 v[208:211], v153 offset:17408
	ds_read_b128 v[212:215], v153 offset:18432
	ds_read_b128 v[216:219], v153 offset:19456
	ds_read_b128 v[220:223], v153 offset:20480
	ds_read_b128 v[224:227], v153 offset:21504
	ds_read_b128 v[228:231], v153 offset:22528
	ds_read_b128 v[232:235], v153 offset:23552
	global_load_lds_dwordx4 v[170:171], off
	s_add_i32 m0, s24, 0x2000
	s_add_u32 s24, s46, 0x30000
	v_lshl_add_u64 v[236:237], s[46:47], 0, v[130:131]
	s_addc_u32 s25, s47, 0
	s_add_i32 s44, s51, s29
	global_load_lds_dwordx4 v[236:237], off
	v_lshl_add_u64 v[238:239], s[24:25], 0, v[128:129]
	s_mov_b32 m0, s44
	v_lshl_add_u64 v[240:241], s[68:69], 0, v[130:131]
	global_load_lds_dwordx4 v[238:239], off
	v_lshl_add_u64 v[238:239], s[24:25], 0, v[130:131]
	s_add_i32 m0, s44, 0x2000
	s_nop 0
	global_load_lds_dwordx4 v[238:239], off
	v_lshl_add_u64 v[238:239], s[68:69], 0, v[128:129]
	s_mov_b32 m0, s71
	s_nop 0
	global_load_lds_dwordx4 v[238:239], off
	s_mov_b32 m0, s87
	s_nop 0
	global_load_lds_dwordx4 v[240:241], off
	s_waitcnt vmcnt(8)
	s_waitcnt lgkmcnt(0)
	s_barrier
	s_setprio 1
	s_waitcnt lgkmcnt(0)
	v_mfma_f32_16x16x32_bf16 v[60:63], v[146:149], v[204:207], v[60:63]
	v_mfma_f32_16x16x32_bf16 v[56:59], v[158:161], v[204:207], v[56:59]
	v_mfma_f32_16x16x32_bf16 v[44:47], v[146:149], v[212:215], v[44:47]
	v_mfma_f32_16x16x32_bf16 v[40:43], v[158:161], v[212:215], v[40:43]
	v_mfma_f32_16x16x32_bf16 v[28:31], v[146:149], v[220:223], v[28:31]
	v_mfma_f32_16x16x32_bf16 v[24:27], v[158:161], v[220:223], v[24:27]
	v_mfma_f32_16x16x32_bf16 v[12:15], v[146:149], v[228:231], v[12:15]
	v_mfma_f32_16x16x32_bf16 v[8:11], v[158:161], v[228:231], v[8:11]
	v_mfma_f32_16x16x32_bf16 v[60:63], v[154:157], v[208:211], v[60:63]
	v_mfma_f32_16x16x32_bf16 v[56:59], v[162:165], v[208:211], v[56:59]
	v_mfma_f32_16x16x32_bf16 v[44:47], v[154:157], v[216:219], v[44:47]
	v_mfma_f32_16x16x32_bf16 v[40:43], v[162:165], v[216:219], v[40:43]
	v_mfma_f32_16x16x32_bf16 v[28:31], v[154:157], v[224:227], v[28:31]
	v_mfma_f32_16x16x32_bf16 v[24:27], v[162:165], v[224:227], v[24:27]
	v_mfma_f32_16x16x32_bf16 v[12:15], v[154:157], v[232:235], v[12:15]
	v_mfma_f32_16x16x32_bf16 v[8:11], v[162:165], v[232:235], v[8:11]
	s_setprio 0
	s_setprio 1
	v_mfma_f32_16x16x32_bf16 v[52:55], v[166:169], v[204:207], v[52:55]
	v_mfma_f32_16x16x32_bf16 v[48:51], v[196:199], v[204:207], v[48:51]
	v_mfma_f32_16x16x32_bf16 v[36:39], v[166:169], v[212:215], v[36:39]
	v_mfma_f32_16x16x32_bf16 v[32:35], v[196:199], v[212:215], v[32:35]
	v_mfma_f32_16x16x32_bf16 v[20:23], v[166:169], v[220:223], v[20:23]
	v_mfma_f32_16x16x32_bf16 v[16:19], v[196:199], v[220:223], v[16:19]
	v_mfma_f32_16x16x32_bf16 v[4:7], v[166:169], v[228:231], v[4:7]
	v_mfma_f32_16x16x32_bf16 v[0:3], v[196:199], v[228:231], v[0:3]
	v_mfma_f32_16x16x32_bf16 v[52:55], v[192:195], v[208:211], v[52:55]
	v_mfma_f32_16x16x32_bf16 v[48:51], v[200:203], v[208:211], v[48:51]
	v_mfma_f32_16x16x32_bf16 v[36:39], v[192:195], v[216:219], v[36:39]
	v_mfma_f32_16x16x32_bf16 v[32:35], v[200:203], v[216:219], v[32:35]
	v_mfma_f32_16x16x32_bf16 v[20:23], v[192:195], v[224:227], v[20:23]
	v_mfma_f32_16x16x32_bf16 v[16:19], v[200:203], v[224:227], v[16:19]
	v_mfma_f32_16x16x32_bf16 v[4:7], v[192:195], v[232:235], v[4:7]
	v_mfma_f32_16x16x32_bf16 v[0:3], v[200:203], v[232:235], v[0:3]
	s_setprio 0
	s_barrier
; #define PG8_STAGE(bufoff, gbase, voff) do { _Pragma("unroll") for (int _i = 0; _i < 2; ++_i) \
;         __builtin_amdgcn_global_load_lds((const unsigned*)((const char*)(gbase) + (voff)[_i]), (PG8_LAS unsigned*)(lds + (bufoff) + ldsw + _i * 8192), 16, 0, 0); } while (0)
; #define PG8_LDA(dst, b, h) do { _Pragma("unroll") for (int m = 0; m < 4; ++m) _Pragma("unroll") for (int k = 0; k < 2; ++k) dst[m][k] = *(const PG8_LAS bf16x8*)(lds + PG8_SA(b, h) + aoff + m * 2048 + k * 1024); } while (0)
; #define PG8_LDB(dst, b, h) do { _Pragma("unroll") for (int n = 0; n < 2; ++n) _Pragma("unroll") for (int k = 0; k < 2; ++k) dst[n][k] = *(const PG8_LAS bf16x8*)(lds + PG8_SB(b, h) + boff + n * 2048 + k * 1024); } while (0)
; #define PG8_MMA(ai, bj, At, Bt) do { __builtin_amdgcn_s_setprio(1); _Pragma("unroll") for (int m = 0; m < 4; ++m) _Pragma("unroll") for (int n = 0; n < 2; ++n) _Pragma("unroll") for (int k = 0; k < 2; ++k) \
;         acc[ai][bj][m][n] = __builtin_amdgcn_mfma_f32_16x16x32_bf16(Bt[n][k], At[m][k], acc[ai][bj][m][n], 0, 0, 0); __builtin_amdgcn_s_setprio(0); } while (0)
; #define PG8_WAIT_V(n) asm volatile("s_waitcnt vmcnt(" #n ")" ::: "memory")
; #define PG8_WAIT_L(n) asm volatile("s_waitcnt lgkmcnt(" #n ")" ::: "memory")
; #define PG8_BAR __builtin_amdgcn_s_barrier()
; #define PG8_SCHED __builtin_amdgcn_sched_barrier(0)
; template <class Epi, class Sched, bool ALIGN_EPI = false, bool SP2 = false>
; __device__ __forceinline__ void gemm_phase(PG8_LAS unsigned char* lds, const Gemm g, const Sched& S, const Epi& E) {
;     ...
;             PG8_LDB(B0, 1, 0); PG8_LDB(B1, 1, 1); PG8_SCHED; PG8_LDA(At, 1, 0); PG8_STAGE(PG8_SA(0, 1), a2 + hstep, voffA);
;             PG8_WAIT_V(8); PG8_WAIT_L(0); PG8_BAR; PG8_MMA(0, 0, At, B0); PG8_MMA(0, 1, At, B1); PG8_BAR; PG8_SCHED;
	s_add_i32 s44, 0, 0x18000
	s_add_i32 s45, 0, 0x1c000
	v_add_u32_e32 v162, s44, v150
	v_add_u32_e32 v184, s45, v150
	ds_read_b128 v[146:149], v162
	ds_read_b128 v[154:157], v162 offset:1024
	ds_read_b128 v[158:161], v162 offset:2048
	ds_read_b128 v[162:165], v162 offset:3072
	ds_read_b128 v[166:169], v184
	ds_read_b128 v[192:195], v184 offset:1024
	ds_read_b128 v[196:199], v184 offset:2048
	ds_read_b128 v[200:203], v184 offset:3072
	s_add_u32 s24, s68, 0x30000
	s_addc_u32 s25, s69, 0
	s_mov_b32 m0, s88
	v_lshl_add_u64 v[242:243], s[24:25], 0, v[128:129]
	ds_read_b128 v[204:207], v153 offset:32768
	ds_read_b128 v[208:211], v153 offset:33792
	ds_read_b128 v[212:215], v153 offset:34816
	ds_read_b128 v[216:219], v153 offset:35840
	ds_read_b128 v[220:223], v153 offset:36864
	ds_read_b128 v[224:227], v153 offset:37888
	ds_read_b128 v[228:231], v153 offset:38912
	ds_read_b128 v[232:235], v153 offset:39936
	global_load_lds_dwordx4 v[242:243], off
	v_lshl_add_u64 v[242:243], s[24:25], 0, v[130:131]
	s_mov_b32 m0, s89
	s_nop 0
	global_load_lds_dwordx4 v[242:243], off
	s_waitcnt vmcnt(8)
	s_waitcnt lgkmcnt(0)
	s_barrier
	s_setprio 1
	s_waitcnt lgkmcnt(0)
	v_mfma_f32_16x16x32_bf16 v[124:127], v[146:149], v[204:207], v[124:127]
	v_mfma_f32_16x16x32_bf16 v[120:123], v[158:161], v[204:207], v[120:123]
	v_mfma_f32_16x16x32_bf16 v[108:111], v[146:149], v[212:215], v[108:111]
	v_mfma_f32_16x16x32_bf16 v[104:107], v[158:161], v[212:215], v[104:107]
	v_mfma_f32_16x16x32_bf16 v[92:95], v[146:149], v[220:223], v[92:95]
	v_mfma_f32_16x16x32_bf16 v[88:91], v[158:161], v[220:223], v[88:91]
	v_mfma_f32_16x16x32_bf16 v[76:79], v[146:149], v[228:231], v[76:79]
	v_mfma_f32_16x16x32_bf16 v[72:75], v[158:161], v[228:231], v[72:75]
	v_mfma_f32_16x16x32_bf16 v[124:127], v[154:157], v[208:211], v[124:127]
	v_mfma_f32_16x16x32_bf16 v[120:123], v[162:165], v[208:211], v[120:123]
	v_mfma_f32_16x16x32_bf16 v[108:111], v[154:157], v[216:219], v[108:111]
	v_mfma_f32_16x16x32_bf16 v[104:107], v[162:165], v[216:219], v[104:107]
	v_mfma_f32_16x16x32_bf16 v[92:95], v[154:157], v[224:227], v[92:95]
	v_mfma_f32_16x16x32_bf16 v[88:91], v[162:165], v[224:227], v[88:91]
	v_mfma_f32_16x16x32_bf16 v[76:79], v[154:157], v[232:235], v[76:79]
	v_mfma_f32_16x16x32_bf16 v[72:75], v[162:165], v[232:235], v[72:75]
	s_setprio 0
	s_setprio 1
	v_mfma_f32_16x16x32_bf16 v[116:119], v[166:169], v[204:207], v[116:119]
	v_mfma_f32_16x16x32_bf16 v[112:115], v[196:199], v[204:207], v[112:115]
	v_mfma_f32_16x16x32_bf16 v[100:103], v[166:169], v[212:215], v[100:103]
	v_mfma_f32_16x16x32_bf16 v[96:99], v[196:199], v[212:215], v[96:99]
	v_mfma_f32_16x16x32_bf16 v[84:87], v[166:169], v[220:223], v[84:87]
	v_mfma_f32_16x16x32_bf16 v[80:83], v[196:199], v[220:223], v[80:83]
	v_mfma_f32_16x16x32_bf16 v[68:71], v[166:169], v[228:231], v[68:71]
	v_mfma_f32_16x16x32_bf16 v[64:67], v[196:199], v[228:231], v[64:67]
	v_mfma_f32_16x16x32_bf16 v[116:119], v[192:195], v[208:211], v[116:119]
	v_mfma_f32_16x16x32_bf16 v[112:115], v[200:203], v[208:211], v[112:115]
	v_mfma_f32_16x16x32_bf16 v[100:103], v[192:195], v[216:219], v[100:103]
	v_mfma_f32_16x16x32_bf16 v[96:99], v[200:203], v[216:219], v[96:99]
	v_mfma_f32_16x16x32_bf16 v[84:87], v[192:195], v[224:227], v[84:87]
	v_mfma_f32_16x16x32_bf16 v[80:83], v[200:203], v[224:227], v[80:83]
	v_mfma_f32_16x16x32_bf16 v[68:71], v[192:195], v[232:235], v[68:71]
	v_mfma_f32_16x16x32_bf16 v[64:67], v[200:203], v[232:235], v[64:67]
	s_setprio 0
	s_barrier
; #define PG8_STAGE(bufoff, gbase, voff) do { _Pragma("unroll") for (int _i = 0; _i < 2; ++_i) \
;         __builtin_amdgcn_global_load_lds((const unsigned*)((const char*)(gbase) + (voff)[_i]), (PG8_LAS unsigned*)(lds + (bufoff) + ldsw + _i * 8192), 16, 0, 0); } while (0)
; #define PG8_LDA(dst, b, h) do { _Pragma("unroll") for (int m = 0; m < 4; ++m) _Pragma("unroll") for (int k = 0; k < 2; ++k) dst[m][k] = *(const PG8_LAS bf16x8*)(lds + PG8_SA(b, h) + aoff + m * 2048 + k * 1024); } while (0)
; #define PG8_MMA(ai, bj, At, Bt) do { __builtin_amdgcn_s_setprio(1); _Pragma("unroll") for (int m = 0; m < 4; ++m) _Pragma("unroll") for (int n = 0; n < 2; ++n) _Pragma("unroll") for (int k = 0; k < 2; ++k) \
;         acc[ai][bj][m][n] = __builtin_amdgcn_mfma_f32_16x16x32_bf16(Bt[n][k], At[m][k], acc[ai][bj][m][n], 0, 0, 0); __builtin_amdgcn_s_setprio(0); } while (0)
; #define PG8_WAIT_V(n) asm volatile("s_waitcnt vmcnt(" #n ")" ::: "memory")
; #define PG8_WAIT_L(n) asm volatile("s_waitcnt lgkmcnt(" #n ")" ::: "memory")
; #define PG8_BAR __builtin_amdgcn_s_barrier()
; #define PG8_SCHED __builtin_amdgcn_sched_barrier(0)
; template <class Epi, class Sched, bool ALIGN_EPI = false, bool SP2 = false>
; __device__ __forceinline__ void gemm_phase(PG8_LAS unsigned char* lds, const Gemm g, const Sched& S, const Epi& E) {
;     ...
;         for (int t = 0; t < nt; t += 2) {
;             const bool last = (t == nt - 2);
;     ...
;             PG8_LDA(At, 1, 1); PG8_STAGE(PG8_SB(1, 0), b3, voffB); PG8_STAGE(PG8_SB(1, 1), b3 + hstep, voffB); PG8_STAGE(PG8_SA(1, 0), a3, voffA);
;             PG8_WAIT_V(8); PG8_WAIT_L(0); PG8_BAR; PG8_MMA(1, 0, At, B0); PG8_MMA(1, 1, At, B1); PG8_BAR; PG8_SCHED;
	s_add_i32 s24, s44, s29
	v_lshl_add_u64 v[170:171], v[170:171], 0, s[14:15]
	s_mov_b32 m0, s24
	ds_read_b128 v[204:207], v153 offset:49152
	ds_read_b128 v[208:211], v153 offset:50176
	ds_read_b128 v[212:215], v153 offset:51200
	ds_read_b128 v[216:219], v153 offset:52224
	ds_read_b128 v[220:223], v153 offset:53248
	ds_read_b128 v[224:227], v153 offset:54272
	ds_read_b128 v[228:231], v153 offset:55296
	ds_read_b128 v[232:235], v153 offset:56320
	global_load_lds_dwordx4 v[170:171], off
	s_add_i32 m0, s24, 0x2000
	s_add_u32 s24, s46, 0x30080
	v_lshl_add_u64 v[170:171], v[236:237], 0, s[14:15]
	s_addc_u32 s25, s47, 0
	s_add_i32 s44, s45, s29
	global_load_lds_dwordx4 v[170:171], off
	v_lshl_add_u64 v[170:171], s[24:25], 0, v[128:129]
	s_mov_b32 m0, s44
	s_nop 0
	global_load_lds_dwordx4 v[170:171], off
	v_lshl_add_u64 v[170:171], s[24:25], 0, v[130:131]
	s_add_i32 m0, s44, 0x2000
	s_nop 0
	global_load_lds_dwordx4 v[170:171], off
	v_lshl_add_u64 v[170:171], v[238:239], 0, s[14:15]
	s_mov_b32 m0, s91
	s_nop 0
	global_load_lds_dwordx4 v[170:171], off
	v_lshl_add_u64 v[170:171], v[240:241], 0, s[14:15]
	s_mov_b32 m0, s92
	s_nop 0
	global_load_lds_dwordx4 v[170:171], off
	s_waitcnt vmcnt(8)
	s_waitcnt lgkmcnt(0)
	s_barrier
	s_setprio 1
	s_waitcnt lgkmcnt(0)
	v_mfma_f32_16x16x32_bf16 v[60:63], v[146:149], v[204:207], v[60:63]
	v_mfma_f32_16x16x32_bf16 v[56:59], v[158:161], v[204:207], v[56:59]
	v_mfma_f32_16x16x32_bf16 v[44:47], v[146:149], v[212:215], v[44:47]
	v_mfma_f32_16x16x32_bf16 v[40:43], v[158:161], v[212:215], v[40:43]
	v_mfma_f32_16x16x32_bf16 v[28:31], v[146:149], v[220:223], v[28:31]
	v_mfma_f32_16x16x32_bf16 v[24:27], v[158:161], v[220:223], v[24:27]
	v_mfma_f32_16x16x32_bf16 v[12:15], v[146:149], v[228:231], v[12:15]
	v_mfma_f32_16x16x32_bf16 v[8:11], v[158:161], v[228:231], v[8:11]
	v_mfma_f32_16x16x32_bf16 v[60:63], v[154:157], v[208:211], v[60:63]
	v_mfma_f32_16x16x32_bf16 v[56:59], v[162:165], v[208:211], v[56:59]
	v_mfma_f32_16x16x32_bf16 v[44:47], v[154:157], v[216:219], v[44:47]
	v_mfma_f32_16x16x32_bf16 v[40:43], v[162:165], v[216:219], v[40:43]
	v_mfma_f32_16x16x32_bf16 v[28:31], v[154:157], v[224:227], v[28:31]
	v_mfma_f32_16x16x32_bf16 v[24:27], v[162:165], v[224:227], v[24:27]
	v_mfma_f32_16x16x32_bf16 v[12:15], v[154:157], v[232:235], v[12:15]
	v_mfma_f32_16x16x32_bf16 v[8:11], v[162:165], v[232:235], v[8:11]
	s_setprio 0
	s_setprio 1
	v_mfma_f32_16x16x32_bf16 v[52:55], v[166:169], v[204:207], v[52:55]
	v_mfma_f32_16x16x32_bf16 v[48:51], v[196:199], v[204:207], v[48:51]
	v_mfma_f32_16x16x32_bf16 v[36:39], v[166:169], v[212:215], v[36:39]
	v_mfma_f32_16x16x32_bf16 v[32:35], v[196:199], v[212:215], v[32:35]
	v_mfma_f32_16x16x32_bf16 v[20:23], v[166:169], v[220:223], v[20:23]
	v_mfma_f32_16x16x32_bf16 v[16:19], v[196:199], v[220:223], v[16:19]
	v_mfma_f32_16x16x32_bf16 v[4:7], v[166:169], v[228:231], v[4:7]
	v_mfma_f32_16x16x32_bf16 v[0:3], v[196:199], v[228:231], v[0:3]
	v_mfma_f32_16x16x32_bf16 v[52:55], v[192:195], v[208:211], v[52:55]
	v_mfma_f32_16x16x32_bf16 v[48:51], v[200:203], v[208:211], v[48:51]
	v_mfma_f32_16x16x32_bf16 v[36:39], v[192:195], v[216:219], v[36:39]
	v_mfma_f32_16x16x32_bf16 v[32:35], v[200:203], v[216:219], v[32:35]
	v_mfma_f32_16x16x32_bf16 v[20:23], v[192:195], v[224:227], v[20:23]
	v_mfma_f32_16x16x32_bf16 v[16:19], v[200:203], v[224:227], v[16:19]
	v_mfma_f32_16x16x32_bf16 v[4:7], v[192:195], v[232:235], v[4:7]
	v_mfma_f32_16x16x32_bf16 v[0:3], v[200:203], v[232:235], v[0:3]
	s_setprio 0
	s_add_i32 s50, s50, 2
	s_add_u32 s22, s22, 0x100
	s_addc_u32 s33, s33, 0
	s_cmp_gt_u32 s50, 9
	s_mov_b64 s[44:45], s[42:43]
	s_barrier
	s_cbranch_scc0 .LBB0_122
	s_and_b64 vcc, exec, s[2:3]
	s_cbranch_vccz .LBB0_125
	s_barrier

; #define PG8_STAGE(bufoff, gbase, voff) do { _Pragma("unroll") for (int _i = 0; _i < 2; ++_i) \
;         __builtin_amdgcn_global_load_lds((const unsigned*)((const char*)(gbase) + (voff)[_i]), (PG8_LAS unsigned*)(lds + (bufoff) + ldsw + _i * 8192), 16, 0, 0); } while (0)
; #define PG8_LDA(dst, b, h) do { _Pragma("unroll") for (int m = 0; m < 4; ++m) _Pragma("unroll") for (int k = 0; k < 2; ++k) dst[m][k] = *(const PG8_LAS bf16x8*)(lds + PG8_SA(b, h) + aoff + m * 2048 + k * 1024); } while (0)
; #define PG8_LDB(dst, b, h) do { _Pragma("unroll") for (int n = 0; n < 2; ++n) _Pragma("unroll") for (int k = 0; k < 2; ++k) dst[n][k] = *(const PG8_LAS bf16x8*)(lds + PG8_SB(b, h) + boff + n * 2048 + k * 1024); } while (0)
; #define PG8_MMA(ai, bj, At, Bt) do { __builtin_amdgcn_s_setprio(1); _Pragma("unroll") for (int m = 0; m < 4; ++m) _Pragma("unroll") for (int n = 0; n < 2; ++n) _Pragma("unroll") for (int k = 0; k < 2; ++k) \
;         acc[ai][bj][m][n] = __builtin_amdgcn_mfma_f32_16x16x32_bf16(Bt[n][k], At[m][k], acc[ai][bj][m][n], 0, 0, 0); __builtin_amdgcn_s_setprio(0); } while (0)
; #define PG8_BAR __builtin_amdgcn_s_barrier()
; template <class Epi, class Sched, bool ALIGN_EPI = false, bool SP2 = false>
; __device__ __forceinline__ void gemm_phase(PG8_LAS unsigned char* lds, const Gemm g, const Sched& S, const Epi& E) {
;     ...
;         const bool has_next = S.next(ui + 1, nxt);
;         const char* nA = has_next ? (const char*)g.A + (size_t)nxt.pm * tstep : cA; const char* nB = has_next ? (const char*)g.Bt + (size_t)nxt.pn * tstep : cB;
;         for (int t = 0; t < nt; t += 2) {
;             const bool last = (t == nt - 2);
;             const char* a1 = cA + (size_t)(t + 1) * kstep;
;             const char* a2 = last ? nA : cA + (size_t)(t + 2) * kstep; const char* b2 = last ? nB : cB + (size_t)(t + 2) * kstep;
;             const char* a3 = a2 + kstep; const char* b3 = b2 + kstep;
;             if (last && has_next) S.a_ready(nxt);
;             if constexpr (SP2) {
;             PG8_LDB(B0, 0, 0); PG8_LDB(B1, 0, 1); PG8_SCHED; PG8_LDA(At, 0, 0); PG8_STAGE(PG8_SA(1, 1), a1 + hstep, voffA);
;             PG8_WAIT_V(8); PG8_WAIT_L(0); PG8_BAR; PG8_MMA(0, 0, At, B0); PG8_MMA(0, 1, At, B1); PG8_BAR; PG8_SCHED;
;             PG8_LDA(At, 0, 1); PG8_STAGE(PG8_SB(0, 0), b2, voffB); PG8_STAGE(PG8_SB(0, 1), b2 + hstep, voffB); PG8_STAGE(PG8_SA(0, 0), a2, voffA);
.LBB0_174:
	s_ashr_i32 s39, s38, 31
	s_lshl_b64 s[0:1], s[38:39], 19
	s_add_u32 s48, s23, s0
	s_addc_u32 s49, s12, s1
	s_and_b64 s[0:1], s[42:43], exec
	s_cselect_b32 s0, s49, s57
	s_cselect_b32 s1, s48, s56
	s_ashr_i32 s37, s36, 31
	s_lshl_b64 s[24:25], s[36:37], 19
	s_add_u32 s52, s85, s24
	s_addc_u32 s53, s86, s25
	s_and_b64 s[24:25], s[42:43], exec
	s_cselect_b32 s10, s53, s59
	s_cselect_b32 s22, s52, s58
	s_add_u32 s56, s56, 0x40080
	s_addc_u32 s57, s57, 0
	s_add_u32 s33, s58, 0x100
	s_addc_u32 s37, s59, 0
	s_mov_b32 s39, -2
	s_waitcnt lgkmcnt(0)
	s_add_u32 s24, s56, 0xfffc0080
	s_addc_u32 s25, s57, -1
	s_add_i32 s45, 0, 0x10000
	s_cmp_eq_u32 s39, 12
	s_cselect_b32 s61, s0, s25
	s_cselect_b32 s60, s1, s24
	v_add_u32_e32 v132, s45, v192
	s_cselect_b32 s59, s10, s37
	s_cselect_b32 s58, s22, s33
	s_add_i32 s47, 0, 0x14000
	ds_read_b128 v[128:131], v132
	ds_read_b128 v[158:161], v132 offset:1024
	ds_read_b128 v[162:165], v132 offset:2048
	ds_read_b128 v[166:169], v132 offset:3072
	v_add_u32_e32 v132, s47, v192
	ds_read_b128 v[194:197], v132
	ds_read_b128 v[198:201], v132 offset:1024
	ds_read_b128 v[202:205], v132 offset:2048
	ds_read_b128 v[206:209], v132 offset:3072
	v_lshl_add_u64 v[170:171], s[56:57], 0, v[154:155]
	s_add_i32 m0, s73, 0xc000
	ds_read_b128 v[210:213], v193
	ds_read_b128 v[214:217], v193 offset:1024
	ds_read_b128 v[218:221], v193 offset:2048
	ds_read_b128 v[222:225], v193 offset:3072
	ds_read_b128 v[226:229], v193 offset:4096
	ds_read_b128 v[230:233], v193 offset:5120
	ds_read_b128 v[234:237], v193 offset:6144
	ds_read_b128 v[238:241], v193 offset:7168
	global_load_lds_dwordx4 v[170:171], off
	v_lshl_add_u64 v[170:171], s[56:57], 0, v[156:157]
	s_add_i32 m0, s73, 0xe000
	s_nop 0
	global_load_lds_dwordx4 v[170:171], off
	s_waitcnt vmcnt(8)
	s_waitcnt lgkmcnt(0)
	s_barrier
	s_setprio 1
	s_waitcnt lgkmcnt(0)
	v_mfma_f32_16x16x32_bf16 v[124:127], v[128:131], v[210:213], 0
	v_mfma_f32_16x16x32_bf16 v[120:123], v[162:165], v[210:213], 0
	v_mfma_f32_16x16x32_bf16 v[108:111], v[128:131], v[218:221], 0
	v_mfma_f32_16x16x32_bf16 v[104:107], v[162:165], v[218:221], 0
	v_mfma_f32_16x16x32_bf16 v[92:95], v[128:131], v[226:229], 0
	v_mfma_f32_16x16x32_bf16 v[88:91], v[162:165], v[226:229], 0
	v_mfma_f32_16x16x32_bf16 v[76:79], v[128:131], v[234:237], 0
	v_mfma_f32_16x16x32_bf16 v[72:75], v[162:165], v[234:237], 0
	v_mfma_f32_16x16x32_bf16 v[124:127], v[158:161], v[214:217], v[124:127]
	v_mfma_f32_16x16x32_bf16 v[120:123], v[166:169], v[214:217], v[120:123]
	v_mfma_f32_16x16x32_bf16 v[108:111], v[158:161], v[222:225], v[108:111]
	v_mfma_f32_16x16x32_bf16 v[104:107], v[166:169], v[222:225], v[104:107]
	v_mfma_f32_16x16x32_bf16 v[92:95], v[158:161], v[230:233], v[92:95]
	v_mfma_f32_16x16x32_bf16 v[88:91], v[166:169], v[230:233], v[88:91]
	v_mfma_f32_16x16x32_bf16 v[76:79], v[158:161], v[238:241], v[76:79]
	v_mfma_f32_16x16x32_bf16 v[72:75], v[166:169], v[238:241], v[72:75]
	s_setprio 0
	s_setprio 1
	v_mfma_f32_16x16x32_bf16 v[116:119], v[194:197], v[210:213], 0
	v_mfma_f32_16x16x32_bf16 v[112:115], v[202:205], v[210:213], 0
	v_mfma_f32_16x16x32_bf16 v[100:103], v[194:197], v[218:221], 0
	v_mfma_f32_16x16x32_bf16 v[96:99], v[202:205], v[218:221], 0
	v_mfma_f32_16x16x32_bf16 v[84:87], v[194:197], v[226:229], 0
	v_mfma_f32_16x16x32_bf16 v[80:83], v[202:205], v[226:229], 0
	v_mfma_f32_16x16x32_bf16 v[68:71], v[194:197], v[234:237], 0
	v_mfma_f32_16x16x32_bf16 v[64:67], v[202:205], v[234:237], 0
	v_mfma_f32_16x16x32_bf16 v[116:119], v[198:201], v[214:217], v[116:119]
	v_mfma_f32_16x16x32_bf16 v[112:115], v[206:209], v[214:217], v[112:115]
	v_mfma_f32_16x16x32_bf16 v[100:103], v[198:201], v[222:225], v[100:103]
	v_mfma_f32_16x16x32_bf16 v[96:99], v[206:209], v[222:225], v[96:99]
	v_mfma_f32_16x16x32_bf16 v[84:87], v[198:201], v[230:233], v[84:87]
	v_mfma_f32_16x16x32_bf16 v[80:83], v[206:209], v[230:233], v[80:83]
	v_mfma_f32_16x16x32_bf16 v[68:71], v[198:201], v[238:241], v[68:71]
	v_mfma_f32_16x16x32_bf16 v[64:67], v[206:209], v[238:241], v[64:67]
	s_setprio 0
	s_barrier
	s_add_i32 s24, s45, s29
	v_lshl_add_u64 v[170:171], s[58:59], 0, v[142:143]
	s_mov_b32 m0, s24
	ds_read_b128 v[210:213], v193 offset:16384
	ds_read_b128 v[214:217], v193 offset:17408
	ds_read_b128 v[218:221], v193 offset:18432
	ds_read_b128 v[222:225], v193 offset:19456
	ds_read_b128 v[226:229], v193 offset:20480
	ds_read_b128 v[230:233], v193 offset:21504
	ds_read_b128 v[234:237], v193 offset:22528
	ds_read_b128 v[238:241], v193 offset:23552
	global_load_lds_dwordx4 v[170:171], off
	s_add_i32 m0, s24, 0x2000
	s_add_u32 s24, s58, 0x40000
	v_lshl_add_u64 v[242:243], s[58:59], 0, v[146:147]
	s_addc_u32 s25, s59, 0
	s_add_i32 s45, s47, s29
	global_load_lds_dwordx4 v[242:243], off
	v_lshl_add_u64 v[244:245], s[24:25], 0, v[142:143]
	s_mov_b32 m0, s45
	v_lshl_add_u64 v[246:247], s[60:61], 0, v[144:145]
	global_load_lds_dwordx4 v[244:245], off
	v_lshl_add_u64 v[244:245], s[24:25], 0, v[146:147]
	s_add_i32 m0, s45, 0x2000
	s_nop 0
	global_load_lds_dwordx4 v[244:245], off
	v_lshl_add_u64 v[244:245], s[60:61], 0, v[140:141]
	s_mov_b32 m0, s73
	s_nop 0
	global_load_lds_dwordx4 v[244:245], off
	s_mov_b32 m0, s87
	s_nop 0
	global_load_lds_dwordx4 v[246:247], off
	s_waitcnt vmcnt(8)
	s_waitcnt lgkmcnt(0)
	s_barrier
; #define PG8_STAGE(bufoff, gbase, voff) do { _Pragma("unroll") for (int _i = 0; _i < 2; ++_i) \
;         __builtin_amdgcn_global_load_lds((const unsigned*)((const char*)(gbase) + (voff)[_i]), (PG8_LAS unsigned*)(lds + (bufoff) + ldsw + _i * 8192), 16, 0, 0); } while (0)
; #define PG8_LDA(dst, b, h) do { _Pragma("unroll") for (int m = 0; m < 4; ++m) _Pragma("unroll") for (int k = 0; k < 2; ++k) dst[m][k] = *(const PG8_LAS bf16x8*)(lds + PG8_SA(b, h) + aoff + m * 2048 + k * 1024); } while (0)
; #define PG8_LDB(dst, b, h) do { _Pragma("unroll") for (int n = 0; n < 2; ++n) _Pragma("unroll") for (int k = 0; k < 2; ++k) dst[n][k] = *(const PG8_LAS bf16x8*)(lds + PG8_SB(b, h) + boff + n * 2048 + k * 1024); } while (0)
; #define PG8_MMA(ai, bj, At, Bt) do { __builtin_amdgcn_s_setprio(1); _Pragma("unroll") for (int m = 0; m < 4; ++m) _Pragma("unroll") for (int n = 0; n < 2; ++n) _Pragma("unroll") for (int k = 0; k < 2; ++k) \
;         acc[ai][bj][m][n] = __builtin_amdgcn_mfma_f32_16x16x32_bf16(Bt[n][k], At[m][k], acc[ai][bj][m][n], 0, 0, 0); __builtin_amdgcn_s_setprio(0); } while (0)
; #define PG8_WAIT_V(n) asm volatile("s_waitcnt vmcnt(" #n ")" ::: "memory")
; #define PG8_WAIT_L(n) asm volatile("s_waitcnt lgkmcnt(" #n ")" ::: "memory")
; #define PG8_BAR __builtin_amdgcn_s_barrier()
; #define PG8_SCHED __builtin_amdgcn_sched_barrier(0)
; template <class Epi, class Sched, bool ALIGN_EPI = false, bool SP2 = false>
; __device__ __forceinline__ void gemm_phase(PG8_LAS unsigned char* lds, const Gemm g, const Sched& S, const Epi& E) {
;     ...
;             PG8_WAIT_V(8); PG8_WAIT_L(0); PG8_BAR; PG8_MMA(1, 0, At, B0); PG8_MMA(1, 1, At, B1); PG8_BAR; PG8_SCHED;
;             PG8_LDB(B0, 1, 0); PG8_LDB(B1, 1, 1); PG8_SCHED; PG8_LDA(At, 1, 0); PG8_STAGE(PG8_SA(0, 1), a2 + hstep, voffA);
;             PG8_WAIT_V(8); PG8_WAIT_L(0); PG8_BAR; PG8_MMA(0, 0, At, B0); PG8_MMA(0, 1, At, B1); PG8_BAR; PG8_SCHED;
	s_setprio 1
	s_waitcnt lgkmcnt(0)
	v_mfma_f32_16x16x32_bf16 v[60:63], v[128:131], v[210:213], 0
	v_mfma_f32_16x16x32_bf16 v[56:59], v[162:165], v[210:213], 0
	v_mfma_f32_16x16x32_bf16 v[44:47], v[128:131], v[218:221], 0
	v_mfma_f32_16x16x32_bf16 v[40:43], v[162:165], v[218:221], 0
	v_mfma_f32_16x16x32_bf16 v[28:31], v[128:131], v[226:229], 0
	v_mfma_f32_16x16x32_bf16 v[24:27], v[162:165], v[226:229], 0
	v_mfma_f32_16x16x32_bf16 v[12:15], v[128:131], v[234:237], 0
	v_mfma_f32_16x16x32_bf16 v[8:11], v[162:165], v[234:237], 0
	v_mfma_f32_16x16x32_bf16 v[60:63], v[158:161], v[214:217], v[60:63]
	v_mfma_f32_16x16x32_bf16 v[56:59], v[166:169], v[214:217], v[56:59]
	v_mfma_f32_16x16x32_bf16 v[44:47], v[158:161], v[222:225], v[44:47]
	v_mfma_f32_16x16x32_bf16 v[40:43], v[166:169], v[222:225], v[40:43]
	v_mfma_f32_16x16x32_bf16 v[28:31], v[158:161], v[230:233], v[28:31]
	v_mfma_f32_16x16x32_bf16 v[24:27], v[166:169], v[230:233], v[24:27]
	v_mfma_f32_16x16x32_bf16 v[12:15], v[158:161], v[238:241], v[12:15]
	v_mfma_f32_16x16x32_bf16 v[8:11], v[166:169], v[238:241], v[8:11]
	s_setprio 0
	s_setprio 1
	v_mfma_f32_16x16x32_bf16 v[52:55], v[194:197], v[210:213], 0
	v_mfma_f32_16x16x32_bf16 v[48:51], v[202:205], v[210:213], 0
	v_mfma_f32_16x16x32_bf16 v[36:39], v[194:197], v[218:221], 0
	v_mfma_f32_16x16x32_bf16 v[32:35], v[202:205], v[218:221], 0
	v_mfma_f32_16x16x32_bf16 v[20:23], v[194:197], v[226:229], 0
	v_mfma_f32_16x16x32_bf16 v[16:19], v[202:205], v[226:229], 0
	v_mfma_f32_16x16x32_bf16 v[4:7], v[194:197], v[234:237], 0
	v_mfma_f32_16x16x32_bf16 v[0:3], v[202:205], v[234:237], 0
	v_mfma_f32_16x16x32_bf16 v[52:55], v[198:201], v[214:217], v[52:55]
	v_mfma_f32_16x16x32_bf16 v[48:51], v[206:209], v[214:217], v[48:51]
	v_mfma_f32_16x16x32_bf16 v[36:39], v[198:201], v[222:225], v[36:39]
	v_mfma_f32_16x16x32_bf16 v[32:35], v[206:209], v[222:225], v[32:35]
	v_mfma_f32_16x16x32_bf16 v[20:23], v[198:201], v[230:233], v[20:23]
	v_mfma_f32_16x16x32_bf16 v[16:19], v[206:209], v[230:233], v[16:19]
	v_mfma_f32_16x16x32_bf16 v[4:7], v[198:201], v[238:241], v[4:7]
	v_mfma_f32_16x16x32_bf16 v[0:3], v[206:209], v[238:241], v[0:3]
	s_setprio 0
	s_barrier
	s_add_i32 s45, 0, 0x18000
	v_add_u32_e32 v132, s45, v192
	s_add_i32 s47, 0, 0x1c000
	ds_read_b128 v[128:131], v132
	ds_read_b128 v[158:161], v132 offset:1024
	ds_read_b128 v[162:165], v132 offset:2048
	ds_read_b128 v[166:169], v132 offset:3072
	v_add_u32_e32 v132, s47, v192
	ds_read_b128 v[194:197], v132
	ds_read_b128 v[198:201], v132 offset:1024
	ds_read_b128 v[202:205], v132 offset:2048
	ds_read_b128 v[206:209], v132 offset:3072
	s_add_u32 s24, s60, 0x40000
	s_addc_u32 s25, s61, 0
	s_mov_b32 m0, s88
	v_lshl_add_u64 v[248:249], s[24:25], 0, v[140:141]
	ds_read_b128 v[210:213], v193 offset:32768
	ds_read_b128 v[214:217], v193 offset:33792
	ds_read_b128 v[218:221], v193 offset:34816
	ds_read_b128 v[222:225], v193 offset:35840
	ds_read_b128 v[226:229], v193 offset:36864
	ds_read_b128 v[230:233], v193 offset:37888
	ds_read_b128 v[234:237], v193 offset:38912
	ds_read_b128 v[238:241], v193 offset:39936
	global_load_lds_dwordx4 v[248:249], off
	v_lshl_add_u64 v[248:249], s[24:25], 0, v[144:145]
	s_mov_b32 m0, s89
	s_nop 0
	global_load_lds_dwordx4 v[248:249], off
	s_waitcnt vmcnt(8)
	s_waitcnt lgkmcnt(0)
	s_barrier
	s_setprio 1
	s_waitcnt lgkmcnt(0)
	v_mfma_f32_16x16x32_bf16 v[124:127], v[128:131], v[210:213], v[124:127]
	v_mfma_f32_16x16x32_bf16 v[120:123], v[162:165], v[210:213], v[120:123]
	v_mfma_f32_16x16x32_bf16 v[108:111], v[128:131], v[218:221], v[108:111]
	v_mfma_f32_16x16x32_bf16 v[104:107], v[162:165], v[218:221], v[104:107]
	v_mfma_f32_16x16x32_bf16 v[92:95], v[128:131], v[226:229], v[92:95]
	v_mfma_f32_16x16x32_bf16 v[88:91], v[162:165], v[226:229], v[88:91]
	v_mfma_f32_16x16x32_bf16 v[76:79], v[128:131], v[234:237], v[76:79]
	v_mfma_f32_16x16x32_bf16 v[72:75], v[162:165], v[234:237], v[72:75]
	v_mfma_f32_16x16x32_bf16 v[124:127], v[158:161], v[214:217], v[124:127]
	v_mfma_f32_16x16x32_bf16 v[120:123], v[166:169], v[214:217], v[120:123]
	v_mfma_f32_16x16x32_bf16 v[108:111], v[158:161], v[222:225], v[108:111]
	v_mfma_f32_16x16x32_bf16 v[104:107], v[166:169], v[222:225], v[104:107]
	v_mfma_f32_16x16x32_bf16 v[92:95], v[158:161], v[230:233], v[92:95]
	v_mfma_f32_16x16x32_bf16 v[88:91], v[166:169], v[230:233], v[88:91]
	v_mfma_f32_16x16x32_bf16 v[76:79], v[158:161], v[238:241], v[76:79]
	v_mfma_f32_16x16x32_bf16 v[72:75], v[166:169], v[238:241], v[72:75]
	s_setprio 0
	s_setprio 1
	v_mfma_f32_16x16x32_bf16 v[116:119], v[194:197], v[210:213], v[116:119]
	v_mfma_f32_16x16x32_bf16 v[112:115], v[202:205], v[210:213], v[112:115]
	v_mfma_f32_16x16x32_bf16 v[100:103], v[194:197], v[218:221], v[100:103]
	v_mfma_f32_16x16x32_bf16 v[96:99], v[202:205], v[218:221], v[96:99]
	v_mfma_f32_16x16x32_bf16 v[84:87], v[194:197], v[226:229], v[84:87]
	v_mfma_f32_16x16x32_bf16 v[80:83], v[202:205], v[226:229], v[80:83]
	v_mfma_f32_16x16x32_bf16 v[68:71], v[194:197], v[234:237], v[68:71]
	v_mfma_f32_16x16x32_bf16 v[64:67], v[202:205], v[234:237], v[64:67]
	v_mfma_f32_16x16x32_bf16 v[116:119], v[198:201], v[214:217], v[116:119]
	v_mfma_f32_16x16x32_bf16 v[112:115], v[206:209], v[214:217], v[112:115]
	v_mfma_f32_16x16x32_bf16 v[100:103], v[198:201], v[222:225], v[100:103]
	v_mfma_f32_16x16x32_bf16 v[96:99], v[206:209], v[222:225], v[96:99]
	v_mfma_f32_16x16x32_bf16 v[84:87], v[198:201], v[230:233], v[84:87]
	v_mfma_f32_16x16x32_bf16 v[80:83], v[206:209], v[230:233], v[80:83]
	v_mfma_f32_16x16x32_bf16 v[68:71], v[198:201], v[238:241], v[68:71]
	v_mfma_f32_16x16x32_bf16 v[64:67], v[206:209], v[238:241], v[64:67]
	s_setprio 0
	s_barrier
; #define PG8_STAGE(bufoff, gbase, voff) do { _Pragma("unroll") for (int _i = 0; _i < 2; ++_i) \
;         __builtin_amdgcn_global_load_lds((const unsigned*)((const char*)(gbase) + (voff)[_i]), (PG8_LAS unsigned*)(lds + (bufoff) + ldsw + _i * 8192), 16, 0, 0); } while (0)
; #define PG8_LDA(dst, b, h) do { _Pragma("unroll") for (int m = 0; m < 4; ++m) _Pragma("unroll") for (int k = 0; k < 2; ++k) dst[m][k] = *(const PG8_LAS bf16x8*)(lds + PG8_SA(b, h) + aoff + m * 2048 + k * 1024); } while (0)
; #define PG8_LDB(dst, b, h) do { _Pragma("unroll") for (int n = 0; n < 2; ++n) _Pragma("unroll") for (int k = 0; k < 2; ++k) dst[n][k] = *(const PG8_LAS bf16x8*)(lds + PG8_SB(b, h) + boff + n * 2048 + k * 1024); } while (0)
; template <class Epi, class Sched, bool ALIGN_EPI = false, bool SP2 = false>
; __device__ __forceinline__ void gemm_phase(PG8_LAS unsigned char* lds, const Gemm g, const Sched& S, const Epi& E) {
;     ...
;         for (int t = 0; t < nt; t += 2) {
;             const bool last = (t == nt - 2);
;             const char* a1 = cA + (size_t)(t + 1) * kstep;
;             const char* a2 = last ? nA : cA + (size_t)(t + 2) * kstep; const char* b2 = last ? nB : cB + (size_t)(t + 2) * kstep;
;             const char* a3 = a2 + kstep; const char* b3 = b2 + kstep;
;             if (last && has_next) S.a_ready(nxt);
;             if constexpr (SP2) {
;             PG8_LDB(B0, 0, 0); PG8_LDB(B1, 0, 1); PG8_SCHED; PG8_LDA(At, 0, 0); PG8_STAGE(PG8_SA(1, 1), a1 + hstep, voffA);
;             PG8_WAIT_V(8); PG8_WAIT_L(0); PG8_BAR; PG8_MMA(0, 0, At, B0); PG8_MMA(0, 1, At, B1); PG8_BAR; PG8_SCHED;
;             PG8_LDA(At, 0, 1); PG8_STAGE(PG8_SB(0, 0), b2, voffB); PG8_STAGE(PG8_SB(0, 1), b2 + hstep, voffB); PG8_STAGE(PG8_SA(0, 0), a2, voffA);
;             PG8_WAIT_V(8); PG8_WAIT_L(0); PG8_BAR; PG8_MMA(1, 0, At, B0); PG8_MMA(1, 1, At, B1); PG8_BAR; PG8_SCHED;
;             PG8_LDB(B0, 1, 0); PG8_LDB(B1, 1, 1); PG8_SCHED; PG8_LDA(At, 1, 0); PG8_STAGE(PG8_SA(0, 1), a2 + hstep, voffA);
;             PG8_WAIT_V(8); PG8_WAIT_L(0); PG8_BAR; PG8_MMA(0, 0, At, B0); PG8_MMA(0, 1, At, B1); PG8_BAR; PG8_SCHED;
;             PG8_LDA(At, 1, 1); PG8_STAGE(PG8_SB(1, 0), b3, voffB); PG8_STAGE(PG8_SB(1, 1), b3 + hstep, voffB); PG8_STAGE(PG8_SA(1, 0), a3, voffA);
;             PG8_WAIT_V(8); PG8_WAIT_L(0); PG8_BAR; PG8_MMA(1, 0, At, B0); PG8_MMA(1, 1, At, B1); PG8_BAR; PG8_SCHED;
	s_add_i32 s24, s45, s29
	v_lshl_add_u64 v[170:171], v[170:171], 0, s[14:15]
	s_mov_b32 m0, s24
	ds_read_b128 v[210:213], v193 offset:49152
	ds_read_b128 v[214:217], v193 offset:50176
	ds_read_b128 v[218:221], v193 offset:51200
	ds_read_b128 v[222:225], v193 offset:52224
	ds_read_b128 v[226:229], v193 offset:53248
	ds_read_b128 v[230:233], v193 offset:54272
	ds_read_b128 v[234:237], v193 offset:55296
	ds_read_b128 v[238:241], v193 offset:56320
	global_load_lds_dwordx4 v[170:171], off
	s_add_i32 m0, s24, 0x2000
	s_add_u32 s24, s58, 0x40080
	v_lshl_add_u64 v[170:171], v[242:243], 0, s[14:15]
	s_addc_u32 s25, s59, 0
	s_add_i32 s45, s47, s29
	global_load_lds_dwordx4 v[170:171], off
	v_lshl_add_u64 v[170:171], s[24:25], 0, v[142:143]
	s_mov_b32 m0, s45
	s_nop 0
	global_load_lds_dwordx4 v[170:171], off
	v_lshl_add_u64 v[170:171], s[24:25], 0, v[146:147]
	s_add_i32 m0, s45, 0x2000
	s_nop 0
	global_load_lds_dwordx4 v[170:171], off
	v_lshl_add_u64 v[170:171], v[244:245], 0, s[14:15]
	s_mov_b32 m0, s90
	s_nop 0
	global_load_lds_dwordx4 v[170:171], off
	v_lshl_add_u64 v[170:171], v[246:247], 0, s[14:15]
	s_mov_b32 m0, s91
	s_nop 0
	global_load_lds_dwordx4 v[170:171], off
	s_waitcnt vmcnt(8)
	s_waitcnt lgkmcnt(0)
	s_barrier
	s_setprio 1
	s_waitcnt lgkmcnt(0)
	v_mfma_f32_16x16x32_bf16 v[60:63], v[128:131], v[210:213], v[60:63]
	v_mfma_f32_16x16x32_bf16 v[56:59], v[162:165], v[210:213], v[56:59]
	v_mfma_f32_16x16x32_bf16 v[44:47], v[128:131], v[218:221], v[44:47]
	v_mfma_f32_16x16x32_bf16 v[40:43], v[162:165], v[218:221], v[40:43]
	v_mfma_f32_16x16x32_bf16 v[28:31], v[128:131], v[226:229], v[28:31]
	v_mfma_f32_16x16x32_bf16 v[24:27], v[162:165], v[226:229], v[24:27]
	v_mfma_f32_16x16x32_bf16 v[12:15], v[128:131], v[234:237], v[12:15]
	v_mfma_f32_16x16x32_bf16 v[8:11], v[162:165], v[234:237], v[8:11]
	v_mfma_f32_16x16x32_bf16 v[60:63], v[158:161], v[214:217], v[60:63]
	v_mfma_f32_16x16x32_bf16 v[56:59], v[166:169], v[214:217], v[56:59]
	v_mfma_f32_16x16x32_bf16 v[44:47], v[158:161], v[222:225], v[44:47]
	v_mfma_f32_16x16x32_bf16 v[40:43], v[166:169], v[222:225], v[40:43]
	v_mfma_f32_16x16x32_bf16 v[28:31], v[158:161], v[230:233], v[28:31]
	v_mfma_f32_16x16x32_bf16 v[24:27], v[166:169], v[230:233], v[24:27]
	v_mfma_f32_16x16x32_bf16 v[12:15], v[158:161], v[238:241], v[12:15]
	v_mfma_f32_16x16x32_bf16 v[8:11], v[166:169], v[238:241], v[8:11]
	s_setprio 0
	s_setprio 1
	v_mfma_f32_16x16x32_bf16 v[52:55], v[194:197], v[210:213], v[52:55]
	v_mfma_f32_16x16x32_bf16 v[48:51], v[202:205], v[210:213], v[48:51]
	v_mfma_f32_16x16x32_bf16 v[36:39], v[194:197], v[218:221], v[36:39]
	v_mfma_f32_16x16x32_bf16 v[32:35], v[202:205], v[218:221], v[32:35]
	v_mfma_f32_16x16x32_bf16 v[20:23], v[194:197], v[226:229], v[20:23]
	v_mfma_f32_16x16x32_bf16 v[16:19], v[202:205], v[226:229], v[16:19]
	v_mfma_f32_16x16x32_bf16 v[4:7], v[194:197], v[234:237], v[4:7]
	v_mfma_f32_16x16x32_bf16 v[0:3], v[202:205], v[234:237], v[0:3]
	v_mfma_f32_16x16x32_bf16 v[52:55], v[198:201], v[214:217], v[52:55]
	v_mfma_f32_16x16x32_bf16 v[48:51], v[206:209], v[214:217], v[48:51]
	v_mfma_f32_16x16x32_bf16 v[36:39], v[198:201], v[222:225], v[36:39]
	v_mfma_f32_16x16x32_bf16 v[32:35], v[206:209], v[222:225], v[32:35]
	v_mfma_f32_16x16x32_bf16 v[20:23], v[198:201], v[230:233], v[20:23]
	v_mfma_f32_16x16x32_bf16 v[16:19], v[206:209], v[230:233], v[16:19]
	v_mfma_f32_16x16x32_bf16 v[4:7], v[198:201], v[238:241], v[4:7]
	v_mfma_f32_16x16x32_bf16 v[0:3], v[206:209], v[238:241], v[0:3]
	s_setprio 0
	s_add_i32 s39, s39, 2
	s_add_u32 s56, s56, 0x100
	s_addc_u32 s57, s57, 0
	s_add_u32 s33, s33, 0x100
	s_addc_u32 s37, s37, 0
	s_cmp_gt_u32 s39, 13
	s_barrier
.LBB0_175:
	s_add_u32 s24, s56, 0xfffc0080
	s_addc_u32 s25, s57, -1
	s_add_i32 s45, 0, 0x10000
	s_cmp_eq_u32 s39, 12
	s_cselect_b32 s61, s0, s25
	s_cselect_b32 s60, s1, s24
	v_add_u32_e32 v132, s45, v192
	s_cselect_b32 s59, s10, s37
	s_cselect_b32 s58, s22, s33
	s_add_i32 s47, 0, 0x14000
	ds_read_b128 v[128:131], v132
	ds_read_b128 v[158:161], v132 offset:1024
	ds_read_b128 v[162:165], v132 offset:2048
	ds_read_b128 v[166:169], v132 offset:3072
	v_add_u32_e32 v132, s47, v192
	ds_read_b128 v[194:197], v132
	ds_read_b128 v[198:201], v132 offset:1024
	ds_read_b128 v[202:205], v132 offset:2048
	ds_read_b128 v[206:209], v132 offset:3072
	v_lshl_add_u64 v[170:171], s[56:57], 0, v[154:155]
	s_add_i32 m0, s73, 0xc000
	ds_read_b128 v[210:213], v193
	ds_read_b128 v[214:217], v193 offset:1024
	ds_read_b128 v[218:221], v193 offset:2048
	ds_read_b128 v[222:225], v193 offset:3072
	ds_read_b128 v[226:229], v193 offset:4096
	ds_read_b128 v[230:233], v193 offset:5120
	ds_read_b128 v[234:237], v193 offset:6144
	ds_read_b128 v[238:241], v193 offset:7168
	global_load_lds_dwordx4 v[170:171], off
	v_lshl_add_u64 v[170:171], s[56:57], 0, v[156:157]
	s_add_i32 m0, s73, 0xe000
	s_nop 0
	global_load_lds_dwordx4 v[170:171], off
	s_waitcnt vmcnt(8)
	s_waitcnt lgkmcnt(0)
	s_barrier
; #define PG8_STAGE(bufoff, gbase, voff) do { _Pragma("unroll") for (int _i = 0; _i < 2; ++_i) \
;         __builtin_amdgcn_global_load_lds((const unsigned*)((const char*)(gbase) + (voff)[_i]), (PG8_LAS unsigned*)(lds + (bufoff) + ldsw + _i * 8192), 16, 0, 0); } while (0)
; #define PG8_LDA(dst, b, h) do { _Pragma("unroll") for (int m = 0; m < 4; ++m) _Pragma("unroll") for (int k = 0; k < 2; ++k) dst[m][k] = *(const PG8_LAS bf16x8*)(lds + PG8_SA(b, h) + aoff + m * 2048 + k * 1024); } while (0)
; #define PG8_MMA(ai, bj, At, Bt) do { __builtin_amdgcn_s_setprio(1); _Pragma("unroll") for (int m = 0; m < 4; ++m) _Pragma("unroll") for (int n = 0; n < 2; ++n) _Pragma("unroll") for (int k = 0; k < 2; ++k) \
;         acc[ai][bj][m][n] = __builtin_amdgcn_mfma_f32_16x16x32_bf16(Bt[n][k], At[m][k], acc[ai][bj][m][n], 0, 0, 0); __builtin_amdgcn_s_setprio(0); } while (0)
; #define PG8_WAIT_V(n) asm volatile("s_waitcnt vmcnt(" #n ")" ::: "memory")
; #define PG8_WAIT_L(n) asm volatile("s_waitcnt lgkmcnt(" #n ")" ::: "memory")
; #define PG8_BAR __builtin_amdgcn_s_barrier()
; #define PG8_SCHED __builtin_amdgcn_sched_barrier(0)
; template <class Epi, class Sched, bool ALIGN_EPI = false, bool SP2 = false>
; __device__ __forceinline__ void gemm_phase(PG8_LAS unsigned char* lds, const Gemm g, const Sched& S, const Epi& E) {
;     ...
;             PG8_WAIT_V(8); PG8_WAIT_L(0); PG8_BAR; PG8_MMA(0, 0, At, B0); PG8_MMA(0, 1, At, B1); PG8_BAR; PG8_SCHED;
;             PG8_LDA(At, 0, 1); PG8_STAGE(PG8_SB(0, 0), b2, voffB); PG8_STAGE(PG8_SB(0, 1), b2 + hstep, voffB); PG8_STAGE(PG8_SA(0, 0), a2, voffA);
;             PG8_WAIT_V(8); PG8_WAIT_L(0); PG8_BAR; PG8_MMA(1, 0, At, B0); PG8_MMA(1, 1, At, B1); PG8_BAR; PG8_SCHED;
	s_setprio 1
	s_waitcnt lgkmcnt(0)
	v_mfma_f32_16x16x32_bf16 v[124:127], v[128:131], v[210:213], v[124:127]
	v_mfma_f32_16x16x32_bf16 v[120:123], v[162:165], v[210:213], v[120:123]
	v_mfma_f32_16x16x32_bf16 v[108:111], v[128:131], v[218:221], v[108:111]
	v_mfma_f32_16x16x32_bf16 v[104:107], v[162:165], v[218:221], v[104:107]
	v_mfma_f32_16x16x32_bf16 v[92:95], v[128:131], v[226:229], v[92:95]
	v_mfma_f32_16x16x32_bf16 v[88:91], v[162:165], v[226:229], v[88:91]
	v_mfma_f32_16x16x32_bf16 v[76:79], v[128:131], v[234:237], v[76:79]
	v_mfma_f32_16x16x32_bf16 v[72:75], v[162:165], v[234:237], v[72:75]
	v_mfma_f32_16x16x32_bf16 v[124:127], v[158:161], v[214:217], v[124:127]
	v_mfma_f32_16x16x32_bf16 v[120:123], v[166:169], v[214:217], v[120:123]
	v_mfma_f32_16x16x32_bf16 v[108:111], v[158:161], v[222:225], v[108:111]
	v_mfma_f32_16x16x32_bf16 v[104:107], v[166:169], v[222:225], v[104:107]
	v_mfma_f32_16x16x32_bf16 v[92:95], v[158:161], v[230:233], v[92:95]
	v_mfma_f32_16x16x32_bf16 v[88:91], v[166:169], v[230:233], v[88:91]
	v_mfma_f32_16x16x32_bf16 v[76:79], v[158:161], v[238:241], v[76:79]
	v_mfma_f32_16x16x32_bf16 v[72:75], v[166:169], v[238:241], v[72:75]
	s_setprio 0
	s_setprio 1
	v_mfma_f32_16x16x32_bf16 v[116:119], v[194:197], v[210:213], v[116:119]
	v_mfma_f32_16x16x32_bf16 v[112:115], v[202:205], v[210:213], v[112:115]
	v_mfma_f32_16x16x32_bf16 v[100:103], v[194:197], v[218:221], v[100:103]
	v_mfma_f32_16x16x32_bf16 v[96:99], v[202:205], v[218:221], v[96:99]
	v_mfma_f32_16x16x32_bf16 v[84:87], v[194:197], v[226:229], v[84:87]
	v_mfma_f32_16x16x32_bf16 v[80:83], v[202:205], v[226:229], v[80:83]
	v_mfma_f32_16x16x32_bf16 v[68:71], v[194:197], v[234:237], v[68:71]
	v_mfma_f32_16x16x32_bf16 v[64:67], v[202:205], v[234:237], v[64:67]
	v_mfma_f32_16x16x32_bf16 v[116:119], v[198:201], v[214:217], v[116:119]
	v_mfma_f32_16x16x32_bf16 v[112:115], v[206:209], v[214:217], v[112:115]
	v_mfma_f32_16x16x32_bf16 v[100:103], v[198:201], v[222:225], v[100:103]
	v_mfma_f32_16x16x32_bf16 v[96:99], v[206:209], v[222:225], v[96:99]
	v_mfma_f32_16x16x32_bf16 v[84:87], v[198:201], v[230:233], v[84:87]
	v_mfma_f32_16x16x32_bf16 v[80:83], v[206:209], v[230:233], v[80:83]
	v_mfma_f32_16x16x32_bf16 v[68:71], v[198:201], v[238:241], v[68:71]
	v_mfma_f32_16x16x32_bf16 v[64:67], v[206:209], v[238:241], v[64:67]
	s_setprio 0
	s_barrier
	s_add_i32 s24, s45, s29
	v_lshl_add_u64 v[170:171], s[58:59], 0, v[142:143]
	s_mov_b32 m0, s24
	ds_read_b128 v[210:213], v193 offset:16384
	ds_read_b128 v[214:217], v193 offset:17408
	ds_read_b128 v[218:221], v193 offset:18432
	ds_read_b128 v[222:225], v193 offset:19456
	ds_read_b128 v[226:229], v193 offset:20480
	ds_read_b128 v[230:233], v193 offset:21504
	ds_read_b128 v[234:237], v193 offset:22528
	ds_read_b128 v[238:241], v193 offset:23552
	global_load_lds_dwordx4 v[170:171], off
	s_add_i32 m0, s24, 0x2000
	s_add_u32 s24, s58, 0x40000
	v_lshl_add_u64 v[242:243], s[58:59], 0, v[146:147]
	s_addc_u32 s25, s59, 0
	s_add_i32 s45, s47, s29
	global_load_lds_dwordx4 v[242:243], off
	v_lshl_add_u64 v[244:245], s[24:25], 0, v[142:143]
	s_mov_b32 m0, s45
	v_lshl_add_u64 v[246:247], s[60:61], 0, v[144:145]
	global_load_lds_dwordx4 v[244:245], off
	v_lshl_add_u64 v[244:245], s[24:25], 0, v[146:147]
	s_add_i32 m0, s45, 0x2000
	s_nop 0
	global_load_lds_dwordx4 v[244:245], off
	v_lshl_add_u64 v[244:245], s[60:61], 0, v[140:141]
	s_mov_b32 m0, s73
	s_nop 0
	global_load_lds_dwordx4 v[244:245], off
	s_mov_b32 m0, s87
	s_nop 0
	global_load_lds_dwordx4 v[246:247], off
	s_waitcnt vmcnt(8)
	s_waitcnt lgkmcnt(0)
	s_barrier
	s_setprio 1
	s_waitcnt lgkmcnt(0)
	v_mfma_f32_16x16x32_bf16 v[60:63], v[128:131], v[210:213], v[60:63]
	v_mfma_f32_16x16x32_bf16 v[56:59], v[162:165], v[210:213], v[56:59]
	v_mfma_f32_16x16x32_bf16 v[44:47], v[128:131], v[218:221], v[44:47]
	v_mfma_f32_16x16x32_bf16 v[40:43], v[162:165], v[218:221], v[40:43]
	v_mfma_f32_16x16x32_bf16 v[28:31], v[128:131], v[226:229], v[28:31]
	v_mfma_f32_16x16x32_bf16 v[24:27], v[162:165], v[226:229], v[24:27]
	v_mfma_f32_16x16x32_bf16 v[12:15], v[128:131], v[234:237], v[12:15]
	v_mfma_f32_16x16x32_bf16 v[8:11], v[162:165], v[234:237], v[8:11]
	v_mfma_f32_16x16x32_bf16 v[60:63], v[158:161], v[214:217], v[60:63]
	v_mfma_f32_16x16x32_bf16 v[56:59], v[166:169], v[214:217], v[56:59]
	v_mfma_f32_16x16x32_bf16 v[44:47], v[158:161], v[222:225], v[44:47]
	v_mfma_f32_16x16x32_bf16 v[40:43], v[166:169], v[222:225], v[40:43]
	v_mfma_f32_16x16x32_bf16 v[28:31], v[158:161], v[230:233], v[28:31]
	v_mfma_f32_16x16x32_bf16 v[24:27], v[166:169], v[230:233], v[24:27]
	v_mfma_f32_16x16x32_bf16 v[12:15], v[158:161], v[238:241], v[12:15]
	v_mfma_f32_16x16x32_bf16 v[8:11], v[166:169], v[238:241], v[8:11]
	s_setprio 0
	s_setprio 1
	v_mfma_f32_16x16x32_bf16 v[52:55], v[194:197], v[210:213], v[52:55]
	v_mfma_f32_16x16x32_bf16 v[48:51], v[202:205], v[210:213], v[48:51]
	v_mfma_f32_16x16x32_bf16 v[36:39], v[194:197], v[218:221], v[36:39]
	v_mfma_f32_16x16x32_bf16 v[32:35], v[202:205], v[218:221], v[32:35]
	v_mfma_f32_16x16x32_bf16 v[20:23], v[194:197], v[226:229], v[20:23]
	v_mfma_f32_16x16x32_bf16 v[16:19], v[202:205], v[226:229], v[16:19]
	v_mfma_f32_16x16x32_bf16 v[4:7], v[194:197], v[234:237], v[4:7]
	v_mfma_f32_16x16x32_bf16 v[0:3], v[202:205], v[234:237], v[0:3]
	v_mfma_f32_16x16x32_bf16 v[52:55], v[198:201], v[214:217], v[52:55]
	v_mfma_f32_16x16x32_bf16 v[48:51], v[206:209], v[214:217], v[48:51]
	v_mfma_f32_16x16x32_bf16 v[36:39], v[198:201], v[222:225], v[36:39]
	v_mfma_f32_16x16x32_bf16 v[32:35], v[206:209], v[222:225], v[32:35]
	v_mfma_f32_16x16x32_bf16 v[20:23], v[198:201], v[230:233], v[20:23]
	v_mfma_f32_16x16x32_bf16 v[16:19], v[206:209], v[230:233], v[16:19]
	v_mfma_f32_16x16x32_bf16 v[4:7], v[198:201], v[238:241], v[4:7]
	v_mfma_f32_16x16x32_bf16 v[0:3], v[206:209], v[238:241], v[0:3]
	s_setprio 0
	s_barrier
; #define PG8_STAGE(bufoff, gbase, voff) do { _Pragma("unroll") for (int _i = 0; _i < 2; ++_i) \
;         __builtin_amdgcn_global_load_lds((const unsigned*)((const char*)(gbase) + (voff)[_i]), (PG8_LAS unsigned*)(lds + (bufoff) + ldsw + _i * 8192), 16, 0, 0); } while (0)
; #define PG8_LDA(dst, b, h) do { _Pragma("unroll") for (int m = 0; m < 4; ++m) _Pragma("unroll") for (int k = 0; k < 2; ++k) dst[m][k] = *(const PG8_LAS bf16x8*)(lds + PG8_SA(b, h) + aoff + m * 2048 + k * 1024); } while (0)
; #define PG8_LDB(dst, b, h) do { _Pragma("unroll") for (int n = 0; n < 2; ++n) _Pragma("unroll") for (int k = 0; k < 2; ++k) dst[n][k] = *(const PG8_LAS bf16x8*)(lds + PG8_SB(b, h) + boff + n * 2048 + k * 1024); } while (0)
; #define PG8_MMA(ai, bj, At, Bt) do { __builtin_amdgcn_s_setprio(1); _Pragma("unroll") for (int m = 0; m < 4; ++m) _Pragma("unroll") for (int n = 0; n < 2; ++n) _Pragma("unroll") for (int k = 0; k < 2; ++k) \
;         acc[ai][bj][m][n] = __builtin_amdgcn_mfma_f32_16x16x32_bf16(Bt[n][k], At[m][k], acc[ai][bj][m][n], 0, 0, 0); __builtin_amdgcn_s_setprio(0); } while (0)
; #define PG8_WAIT_V(n) asm volatile("s_waitcnt vmcnt(" #n ")" ::: "memory")
; #define PG8_WAIT_L(n) asm volatile("s_waitcnt lgkmcnt(" #n ")" ::: "memory")
; #define PG8_BAR __builtin_amdgcn_s_barrier()
; #define PG8_SCHED __builtin_amdgcn_sched_barrier(0)
; template <class Epi, class Sched, bool ALIGN_EPI = false, bool SP2 = false>
; __device__ __forceinline__ void gemm_phase(PG8_LAS unsigned char* lds, const Gemm g, const Sched& S, const Epi& E) {
;     ...
;             PG8_LDB(B0, 1, 0); PG8_LDB(B1, 1, 1); PG8_SCHED; PG8_LDA(At, 1, 0); PG8_STAGE(PG8_SA(0, 1), a2 + hstep, voffA);
;             PG8_WAIT_V(8); PG8_WAIT_L(0); PG8_BAR; PG8_MMA(0, 0, At, B0); PG8_MMA(0, 1, At, B1); PG8_BAR; PG8_SCHED;
	s_add_i32 s45, 0, 0x18000
	v_add_u32_e32 v132, s45, v192
	s_add_i32 s47, 0, 0x1c000
	ds_read_b128 v[128:131], v132
	ds_read_b128 v[158:161], v132 offset:1024
	ds_read_b128 v[162:165], v132 offset:2048
	ds_read_b128 v[166:169], v132 offset:3072
	v_add_u32_e32 v132, s47, v192
	ds_read_b128 v[194:197], v132
	ds_read_b128 v[198:201], v132 offset:1024
	ds_read_b128 v[202:205], v132 offset:2048
	ds_read_b128 v[206:209], v132 offset:3072
	s_add_u32 s24, s60, 0x40000
	s_addc_u32 s25, s61, 0
	s_mov_b32 m0, s88
	v_lshl_add_u64 v[248:249], s[24:25], 0, v[140:141]
	ds_read_b128 v[210:213], v193 offset:32768
	ds_read_b128 v[214:217], v193 offset:33792
	ds_read_b128 v[218:221], v193 offset:34816
	ds_read_b128 v[222:225], v193 offset:35840
	ds_read_b128 v[226:229], v193 offset:36864
	ds_read_b128 v[230:233], v193 offset:37888
	ds_read_b128 v[234:237], v193 offset:38912
	ds_read_b128 v[238:241], v193 offset:39936
	global_load_lds_dwordx4 v[248:249], off
	v_lshl_add_u64 v[248:249], s[24:25], 0, v[144:145]
	s_mov_b32 m0, s89
	s_nop 0
	global_load_lds_dwordx4 v[248:249], off
	s_waitcnt vmcnt(8)
	s_waitcnt lgkmcnt(0)
	s_barrier
	s_setprio 1
	s_waitcnt lgkmcnt(0)
	v_mfma_f32_16x16x32_bf16 v[124:127], v[128:131], v[210:213], v[124:127]
	v_mfma_f32_16x16x32_bf16 v[120:123], v[162:165], v[210:213], v[120:123]
	v_mfma_f32_16x16x32_bf16 v[108:111], v[128:131], v[218:221], v[108:111]
	v_mfma_f32_16x16x32_bf16 v[104:107], v[162:165], v[218:221], v[104:107]
	v_mfma_f32_16x16x32_bf16 v[92:95], v[128:131], v[226:229], v[92:95]
	v_mfma_f32_16x16x32_bf16 v[88:91], v[162:165], v[226:229], v[88:91]
	v_mfma_f32_16x16x32_bf16 v[76:79], v[128:131], v[234:237], v[76:79]
	v_mfma_f32_16x16x32_bf16 v[72:75], v[162:165], v[234:237], v[72:75]
	v_mfma_f32_16x16x32_bf16 v[124:127], v[158:161], v[214:217], v[124:127]
	v_mfma_f32_16x16x32_bf16 v[120:123], v[166:169], v[214:217], v[120:123]
	v_mfma_f32_16x16x32_bf16 v[108:111], v[158:161], v[222:225], v[108:111]
	v_mfma_f32_16x16x32_bf16 v[104:107], v[166:169], v[222:225], v[104:107]
	v_mfma_f32_16x16x32_bf16 v[92:95], v[158:161], v[230:233], v[92:95]
	v_mfma_f32_16x16x32_bf16 v[88:91], v[166:169], v[230:233], v[88:91]
	v_mfma_f32_16x16x32_bf16 v[76:79], v[158:161], v[238:241], v[76:79]
	v_mfma_f32_16x16x32_bf16 v[72:75], v[166:169], v[238:241], v[72:75]
	s_setprio 0
	s_setprio 1
	v_mfma_f32_16x16x32_bf16 v[116:119], v[194:197], v[210:213], v[116:119]
	v_mfma_f32_16x16x32_bf16 v[112:115], v[202:205], v[210:213], v[112:115]
	v_mfma_f32_16x16x32_bf16 v[100:103], v[194:197], v[218:221], v[100:103]
	v_mfma_f32_16x16x32_bf16 v[96:99], v[202:205], v[218:221], v[96:99]
	v_mfma_f32_16x16x32_bf16 v[84:87], v[194:197], v[226:229], v[84:87]
	v_mfma_f32_16x16x32_bf16 v[80:83], v[202:205], v[226:229], v[80:83]
	v_mfma_f32_16x16x32_bf16 v[68:71], v[194:197], v[234:237], v[68:71]
	v_mfma_f32_16x16x32_bf16 v[64:67], v[202:205], v[234:237], v[64:67]
	v_mfma_f32_16x16x32_bf16 v[116:119], v[198:201], v[214:217], v[116:119]
	v_mfma_f32_16x16x32_bf16 v[112:115], v[206:209], v[214:217], v[112:115]
	v_mfma_f32_16x16x32_bf16 v[100:103], v[198:201], v[222:225], v[100:103]
	v_mfma_f32_16x16x32_bf16 v[96:99], v[206:209], v[222:225], v[96:99]
	v_mfma_f32_16x16x32_bf16 v[84:87], v[198:201], v[230:233], v[84:87]
	v_mfma_f32_16x16x32_bf16 v[80:83], v[206:209], v[230:233], v[80:83]
	v_mfma_f32_16x16x32_bf16 v[68:71], v[198:201], v[238:241], v[68:71]
	v_mfma_f32_16x16x32_bf16 v[64:67], v[206:209], v[238:241], v[64:67]
	s_setprio 0
	s_barrier
; #define PG8_STAGE(bufoff, gbase, voff) do { _Pragma("unroll") for (int _i = 0; _i < 2; ++_i) \
;         __builtin_amdgcn_global_load_lds((const unsigned*)((const char*)(gbase) + (voff)[_i]), (PG8_LAS unsigned*)(lds + (bufoff) + ldsw + _i * 8192), 16, 0, 0); } while (0)
; #define PG8_LDA(dst, b, h) do { _Pragma("unroll") for (int m = 0; m < 4; ++m) _Pragma("unroll") for (int k = 0; k < 2; ++k) dst[m][k] = *(const PG8_LAS bf16x8*)(lds + PG8_SA(b, h) + aoff + m * 2048 + k * 1024); } while (0)
; #define PG8_MMA(ai, bj, At, Bt) do { __builtin_amdgcn_s_setprio(1); _Pragma("unroll") for (int m = 0; m < 4; ++m) _Pragma("unroll") for (int n = 0; n < 2; ++n) _Pragma("unroll") for (int k = 0; k < 2; ++k) \
;         acc[ai][bj][m][n] = __builtin_amdgcn_mfma_f32_16x16x32_bf16(Bt[n][k], At[m][k], acc[ai][bj][m][n], 0, 0, 0); __builtin_amdgcn_s_setprio(0); } while (0)
; #define PG8_WAIT_V(n) asm volatile("s_waitcnt vmcnt(" #n ")" ::: "memory")
; #define PG8_WAIT_L(n) asm volatile("s_waitcnt lgkmcnt(" #n ")" ::: "memory")
; #define PG8_BAR __builtin_amdgcn_s_barrier()
; #define PG8_SCHED __builtin_amdgcn_sched_barrier(0)
; template <class Epi, class Sched, bool ALIGN_EPI = false, bool SP2 = false>
; __device__ __forceinline__ void gemm_phase(PG8_LAS unsigned char* lds, const Gemm g, const Sched& S, const Epi& E) {
;     ...
;         for (int t = 0; t < nt; t += 2) {
;             const bool last = (t == nt - 2);
;     ...
;             PG8_LDA(At, 1, 1); PG8_STAGE(PG8_SB(1, 0), b3, voffB); PG8_STAGE(PG8_SB(1, 1), b3 + hstep, voffB); PG8_STAGE(PG8_SA(1, 0), a3, voffA);
;             PG8_WAIT_V(8); PG8_WAIT_L(0); PG8_BAR; PG8_MMA(1, 0, At, B0); PG8_MMA(1, 1, At, B1); PG8_BAR; PG8_SCHED;
	s_add_i32 s24, s45, s29
	v_lshl_add_u64 v[170:171], v[170:171], 0, s[14:15]
	s_mov_b32 m0, s24
	ds_read_b128 v[210:213], v193 offset:49152
	ds_read_b128 v[214:217], v193 offset:50176
	ds_read_b128 v[218:221], v193 offset:51200
	ds_read_b128 v[222:225], v193 offset:52224
	ds_read_b128 v[226:229], v193 offset:53248
	ds_read_b128 v[230:233], v193 offset:54272
	ds_read_b128 v[234:237], v193 offset:55296
	ds_read_b128 v[238:241], v193 offset:56320
	global_load_lds_dwordx4 v[170:171], off
	s_add_i32 m0, s24, 0x2000
	s_add_u32 s24, s58, 0x40080
	v_lshl_add_u64 v[170:171], v[242:243], 0, s[14:15]
	s_addc_u32 s25, s59, 0
	s_add_i32 s45, s47, s29
	global_load_lds_dwordx4 v[170:171], off
	v_lshl_add_u64 v[170:171], s[24:25], 0, v[142:143]
	s_mov_b32 m0, s45
	s_nop 0
	global_load_lds_dwordx4 v[170:171], off
	v_lshl_add_u64 v[170:171], s[24:25], 0, v[146:147]
	s_add_i32 m0, s45, 0x2000
	s_nop 0
	global_load_lds_dwordx4 v[170:171], off
	v_lshl_add_u64 v[170:171], v[244:245], 0, s[14:15]
	s_mov_b32 m0, s90
	s_nop 0
	global_load_lds_dwordx4 v[170:171], off
	v_lshl_add_u64 v[170:171], v[246:247], 0, s[14:15]
	s_mov_b32 m0, s91
	s_nop 0
	global_load_lds_dwordx4 v[170:171], off
	s_waitcnt vmcnt(8)
	s_waitcnt lgkmcnt(0)
	s_barrier
	s_setprio 1
	s_waitcnt lgkmcnt(0)
	v_mfma_f32_16x16x32_bf16 v[60:63], v[128:131], v[210:213], v[60:63]
	v_mfma_f32_16x16x32_bf16 v[56:59], v[162:165], v[210:213], v[56:59]
	v_mfma_f32_16x16x32_bf16 v[44:47], v[128:131], v[218:221], v[44:47]
	v_mfma_f32_16x16x32_bf16 v[40:43], v[162:165], v[218:221], v[40:43]
	v_mfma_f32_16x16x32_bf16 v[28:31], v[128:131], v[226:229], v[28:31]
	v_mfma_f32_16x16x32_bf16 v[24:27], v[162:165], v[226:229], v[24:27]
	v_mfma_f32_16x16x32_bf16 v[12:15], v[128:131], v[234:237], v[12:15]
	v_mfma_f32_16x16x32_bf16 v[8:11], v[162:165], v[234:237], v[8:11]
	v_mfma_f32_16x16x32_bf16 v[60:63], v[158:161], v[214:217], v[60:63]
	v_mfma_f32_16x16x32_bf16 v[56:59], v[166:169], v[214:217], v[56:59]
	v_mfma_f32_16x16x32_bf16 v[44:47], v[158:161], v[222:225], v[44:47]
	v_mfma_f32_16x16x32_bf16 v[40:43], v[166:169], v[222:225], v[40:43]
	v_mfma_f32_16x16x32_bf16 v[28:31], v[158:161], v[230:233], v[28:31]
	v_mfma_f32_16x16x32_bf16 v[24:27], v[166:169], v[230:233], v[24:27]
	v_mfma_f32_16x16x32_bf16 v[12:15], v[158:161], v[238:241], v[12:15]
	v_mfma_f32_16x16x32_bf16 v[8:11], v[166:169], v[238:241], v[8:11]
	s_setprio 0
	s_setprio 1
	v_mfma_f32_16x16x32_bf16 v[52:55], v[194:197], v[210:213], v[52:55]
	v_mfma_f32_16x16x32_bf16 v[48:51], v[202:205], v[210:213], v[48:51]
	v_mfma_f32_16x16x32_bf16 v[36:39], v[194:197], v[218:221], v[36:39]
	v_mfma_f32_16x16x32_bf16 v[32:35], v[202:205], v[218:221], v[32:35]
	v_mfma_f32_16x16x32_bf16 v[20:23], v[194:197], v[226:229], v[20:23]
	v_mfma_f32_16x16x32_bf16 v[16:19], v[202:205], v[226:229], v[16:19]
	v_mfma_f32_16x16x32_bf16 v[4:7], v[194:197], v[234:237], v[4:7]
	v_mfma_f32_16x16x32_bf16 v[0:3], v[202:205], v[234:237], v[0:3]
	v_mfma_f32_16x16x32_bf16 v[52:55], v[198:201], v[214:217], v[52:55]
	v_mfma_f32_16x16x32_bf16 v[48:51], v[206:209], v[214:217], v[48:51]
	v_mfma_f32_16x16x32_bf16 v[36:39], v[198:201], v[222:225], v[36:39]
	v_mfma_f32_16x16x32_bf16 v[32:35], v[206:209], v[222:225], v[32:35]
	v_mfma_f32_16x16x32_bf16 v[20:23], v[198:201], v[230:233], v[20:23]
	v_mfma_f32_16x16x32_bf16 v[16:19], v[206:209], v[230:233], v[16:19]
	v_mfma_f32_16x16x32_bf16 v[4:7], v[198:201], v[238:241], v[4:7]
	v_mfma_f32_16x16x32_bf16 v[0:3], v[206:209], v[238:241], v[0:3]
	s_setprio 0
	s_add_i32 s39, s39, 2
	s_add_u32 s56, s56, 0x100
	s_addc_u32 s57, s57, 0
	s_add_u32 s33, s33, 0x100
	s_addc_u32 s37, s37, 0
	s_cmp_gt_u32 s39, 13
	s_barrier
	s_cbranch_scc0 .LBB0_175
	s_and_b64 vcc, exec, s[4:5]
	s_cbranch_vccz .LBB0_178
	s_barrier

; #define PG8_STAGE(bufoff, gbase, voff) do { _Pragma("unroll") for (int _i = 0; _i < 2; ++_i) \
;         __builtin_amdgcn_global_load_lds((const unsigned*)((const char*)(gbase) + (voff)[_i]), (PG8_LAS unsigned*)(lds + (bufoff) + ldsw + _i * 8192), 16, 0, 0); } while (0)
; #define PG8_LDA(dst, b, h) do { _Pragma("unroll") for (int m = 0; m < 4; ++m) _Pragma("unroll") for (int k = 0; k < 2; ++k) dst[m][k] = *(const PG8_LAS bf16x8*)(lds + PG8_SA(b, h) + aoff + m * 2048 + k * 1024); } while (0)
; #define PG8_LDB(dst, b, h) do { _Pragma("unroll") for (int n = 0; n < 2; ++n) _Pragma("unroll") for (int k = 0; k < 2; ++k) dst[n][k] = *(const PG8_LAS bf16x8*)(lds + PG8_SB(b, h) + boff + n * 2048 + k * 1024); } while (0)
; #define PG8_MMA(ai, bj, At, Bt) do { __builtin_amdgcn_s_setprio(1); _Pragma("unroll") for (int m = 0; m < 4; ++m) _Pragma("unroll") for (int n = 0; n < 2; ++n) _Pragma("unroll") for (int k = 0; k < 2; ++k) \
;         acc[ai][bj][m][n] = __builtin_amdgcn_mfma_f32_16x16x32_bf16(Bt[n][k], At[m][k], acc[ai][bj][m][n], 0, 0, 0); __builtin_amdgcn_s_setprio(0); } while (0)
; #define PG8_BAR __builtin_amdgcn_s_barrier()
; template <class Epi, class Sched, bool ALIGN_EPI = false, bool SP2 = false>
; __device__ __forceinline__ void gemm_phase(PG8_LAS unsigned char* lds, const Gemm g, const Sched& S, const Epi& E) {
;     ...
;         const bool has_next = S.next(ui + 1, nxt);
;         const char* nA = has_next ? (const char*)g.A + (size_t)nxt.pm * tstep : cA; const char* nB = has_next ? (const char*)g.Bt + (size_t)nxt.pn * tstep : cB;
;         for (int t = 0; t < nt; t += 2) {
;             const bool last = (t == nt - 2);
;             const char* a1 = cA + (size_t)(t + 1) * kstep;
;             const char* a2 = last ? nA : cA + (size_t)(t + 2) * kstep; const char* b2 = last ? nB : cB + (size_t)(t + 2) * kstep;
;             const char* a3 = a2 + kstep; const char* b3 = b2 + kstep;
;             if (last && has_next) S.a_ready(nxt);
;             if constexpr (SP2) {
;             PG8_LDB(B0, 0, 0); PG8_LDB(B1, 0, 1); PG8_SCHED; PG8_LDA(At, 0, 0); PG8_STAGE(PG8_SA(1, 1), a1 + hstep, voffA);
;             PG8_WAIT_V(8); PG8_WAIT_L(0); PG8_BAR; PG8_MMA(0, 0, At, B0); PG8_MMA(0, 1, At, B1); PG8_BAR; PG8_SCHED;
;             PG8_LDA(At, 0, 1); PG8_STAGE(PG8_SB(0, 0), b2, voffB); PG8_STAGE(PG8_SB(0, 1), b2 + hstep, voffB); PG8_STAGE(PG8_SA(0, 0), a2, voffA);
.LBB0_553:
	s_ashr_i32 s21, s20, 31
	s_lshl_b64 s[0:1], s[20:21], 19
	s_add_u32 s38, s26, s0
	s_addc_u32 s39, s27, s1
	s_and_b64 s[0:1], s[42:43], exec
	s_cselect_b32 s0, s39, s57
	s_cselect_b32 s1, s38, s56
	s_ashr_i32 s17, s16, 31
	s_lshl_b64 s[24:25], s[16:17], 19
	s_add_u32 s48, s10, s24
	s_addc_u32 s49, s12, s25
	s_and_b64 s[24:25], s[42:43], exec
	s_cselect_b32 s17, s49, s59
	s_cselect_b32 s21, s48, s58
	s_add_u32 s56, s56, 0x40080
	s_addc_u32 s57, s57, 0
	s_add_u32 s22, s58, 0x100
	s_addc_u32 s33, s59, 0
	s_mov_b32 s45, -2
	s_add_u32 s24, s56, 0xfffc0080
	s_addc_u32 s25, s57, -1
	s_add_i32 s47, 0, 0x10000
	s_cmp_eq_u32 s45, 12
	s_cselect_b32 s61, s0, s25
	s_cselect_b32 s60, s1, s24
	s_cselect_b32 s59, s17, s33
	s_cselect_b32 s58, s21, s22
	s_add_i32 s50, 0, 0x14000
	v_add_u32_e32 v162, s47, v159
	v_add_u32_e32 v170, s50, v159
	ds_read_b128 v[146:149], v162
	ds_read_b128 v[150:153], v162 offset:1024
	ds_read_b128 v[154:157], v162 offset:2048
	ds_read_b128 v[162:165], v162 offset:3072
	ds_read_b128 v[166:169], v170
	ds_read_b128 v[192:195], v170 offset:1024
	ds_read_b128 v[196:199], v170 offset:2048
	ds_read_b128 v[200:203], v170 offset:3072
	v_lshl_add_u64 v[170:171], s[56:57], 0, v[142:143]
	s_add_i32 m0, s29, 0xc000
	ds_read_b128 v[204:207], v161
	ds_read_b128 v[208:211], v161 offset:1024
	ds_read_b128 v[212:215], v161 offset:2048
	ds_read_b128 v[216:219], v161 offset:3072
	ds_read_b128 v[220:223], v161 offset:4096
	ds_read_b128 v[224:227], v161 offset:5120
	ds_read_b128 v[228:231], v161 offset:6144
	ds_read_b128 v[232:235], v161 offset:7168
	global_load_lds_dwordx4 v[170:171], off
	v_lshl_add_u64 v[170:171], s[56:57], 0, v[144:145]
	s_add_i32 m0, s29, 0xe000
	s_nop 0
	global_load_lds_dwordx4 v[170:171], off
	s_waitcnt vmcnt(8)
	s_waitcnt lgkmcnt(0)
	s_barrier
	s_setprio 1
	s_waitcnt lgkmcnt(0)
	v_mfma_f32_16x16x32_bf16 v[124:127], v[146:149], v[204:207], 0
	v_mfma_f32_16x16x32_bf16 v[120:123], v[154:157], v[204:207], 0
	v_mfma_f32_16x16x32_bf16 v[108:111], v[146:149], v[212:215], 0
	v_mfma_f32_16x16x32_bf16 v[104:107], v[154:157], v[212:215], 0
	v_mfma_f32_16x16x32_bf16 v[92:95], v[146:149], v[220:223], 0
	v_mfma_f32_16x16x32_bf16 v[88:91], v[154:157], v[220:223], 0
	v_mfma_f32_16x16x32_bf16 v[76:79], v[146:149], v[228:231], 0
	v_mfma_f32_16x16x32_bf16 v[72:75], v[154:157], v[228:231], 0
	v_mfma_f32_16x16x32_bf16 v[124:127], v[150:153], v[208:211], v[124:127]
	v_mfma_f32_16x16x32_bf16 v[120:123], v[162:165], v[208:211], v[120:123]
	v_mfma_f32_16x16x32_bf16 v[108:111], v[150:153], v[216:219], v[108:111]
	v_mfma_f32_16x16x32_bf16 v[104:107], v[162:165], v[216:219], v[104:107]
	v_mfma_f32_16x16x32_bf16 v[92:95], v[150:153], v[224:227], v[92:95]
	v_mfma_f32_16x16x32_bf16 v[88:91], v[162:165], v[224:227], v[88:91]
	v_mfma_f32_16x16x32_bf16 v[76:79], v[150:153], v[232:235], v[76:79]
	v_mfma_f32_16x16x32_bf16 v[72:75], v[162:165], v[232:235], v[72:75]
	s_setprio 0
	s_setprio 1
	v_mfma_f32_16x16x32_bf16 v[116:119], v[166:169], v[204:207], 0
	v_mfma_f32_16x16x32_bf16 v[112:115], v[196:199], v[204:207], 0
	v_mfma_f32_16x16x32_bf16 v[100:103], v[166:169], v[212:215], 0
	v_mfma_f32_16x16x32_bf16 v[96:99], v[196:199], v[212:215], 0
	v_mfma_f32_16x16x32_bf16 v[84:87], v[166:169], v[220:223], 0
	v_mfma_f32_16x16x32_bf16 v[80:83], v[196:199], v[220:223], 0
	v_mfma_f32_16x16x32_bf16 v[68:71], v[166:169], v[228:231], 0
	v_mfma_f32_16x16x32_bf16 v[64:67], v[196:199], v[228:231], 0
	v_mfma_f32_16x16x32_bf16 v[116:119], v[192:195], v[208:211], v[116:119]
	v_mfma_f32_16x16x32_bf16 v[112:115], v[200:203], v[208:211], v[112:115]
	v_mfma_f32_16x16x32_bf16 v[100:103], v[192:195], v[216:219], v[100:103]
	v_mfma_f32_16x16x32_bf16 v[96:99], v[200:203], v[216:219], v[96:99]
	v_mfma_f32_16x16x32_bf16 v[84:87], v[192:195], v[224:227], v[84:87]
	v_mfma_f32_16x16x32_bf16 v[80:83], v[200:203], v[224:227], v[80:83]
	v_mfma_f32_16x16x32_bf16 v[68:71], v[192:195], v[232:235], v[68:71]
	v_mfma_f32_16x16x32_bf16 v[64:67], v[200:203], v[232:235], v[64:67]
	s_setprio 0
	s_barrier
	s_add_i32 s24, s47, s23
	v_lshl_add_u64 v[170:171], s[58:59], 0, v[132:133]
	s_mov_b32 m0, s24
	ds_read_b128 v[204:207], v161 offset:16384
	ds_read_b128 v[208:211], v161 offset:17408
	ds_read_b128 v[212:215], v161 offset:18432
	ds_read_b128 v[216:219], v161 offset:19456
	ds_read_b128 v[220:223], v161 offset:20480
	ds_read_b128 v[224:227], v161 offset:21504
	ds_read_b128 v[228:231], v161 offset:22528
	ds_read_b128 v[232:235], v161 offset:23552
	global_load_lds_dwordx4 v[170:171], off
	s_add_i32 m0, s24, 0x2000
	s_add_u32 s24, s58, 0x40000
	v_lshl_add_u64 v[236:237], s[58:59], 0, v[140:141]
	s_addc_u32 s25, s59, 0
	s_add_i32 s47, s50, s23
	global_load_lds_dwordx4 v[236:237], off
	v_lshl_add_u64 v[238:239], s[24:25], 0, v[132:133]
	s_mov_b32 m0, s47
	v_lshl_add_u64 v[240:241], s[60:61], 0, v[130:131]
	global_load_lds_dwordx4 v[238:239], off
	v_lshl_add_u64 v[238:239], s[24:25], 0, v[140:141]
	s_add_i32 m0, s47, 0x2000
	s_nop 0
	global_load_lds_dwordx4 v[238:239], off
	v_lshl_add_u64 v[238:239], s[60:61], 0, v[128:129]
	s_mov_b32 m0, s29
	s_nop 0
	global_load_lds_dwordx4 v[238:239], off
	s_mov_b32 m0, s62
	s_nop 0
	global_load_lds_dwordx4 v[240:241], off
	s_waitcnt vmcnt(8)
	s_waitcnt lgkmcnt(0)
	s_barrier
; #define PG8_STAGE(bufoff, gbase, voff) do { _Pragma("unroll") for (int _i = 0; _i < 2; ++_i) \
;         __builtin_amdgcn_global_load_lds((const unsigned*)((const char*)(gbase) + (voff)[_i]), (PG8_LAS unsigned*)(lds + (bufoff) + ldsw + _i * 8192), 16, 0, 0); } while (0)
; #define PG8_LDA(dst, b, h) do { _Pragma("unroll") for (int m = 0; m < 4; ++m) _Pragma("unroll") for (int k = 0; k < 2; ++k) dst[m][k] = *(const PG8_LAS bf16x8*)(lds + PG8_SA(b, h) + aoff + m * 2048 + k * 1024); } while (0)
; #define PG8_LDB(dst, b, h) do { _Pragma("unroll") for (int n = 0; n < 2; ++n) _Pragma("unroll") for (int k = 0; k < 2; ++k) dst[n][k] = *(const PG8_LAS bf16x8*)(lds + PG8_SB(b, h) + boff + n * 2048 + k * 1024); } while (0)
; #define PG8_MMA(ai, bj, At, Bt) do { __builtin_amdgcn_s_setprio(1); _Pragma("unroll") for (int m = 0; m < 4; ++m) _Pragma("unroll") for (int n = 0; n < 2; ++n) _Pragma("unroll") for (int k = 0; k < 2; ++k) \
;         acc[ai][bj][m][n] = __builtin_amdgcn_mfma_f32_16x16x32_bf16(Bt[n][k], At[m][k], acc[ai][bj][m][n], 0, 0, 0); __builtin_amdgcn_s_setprio(0); } while (0)
; #define PG8_WAIT_V(n) asm volatile("s_waitcnt vmcnt(" #n ")" ::: "memory")
; #define PG8_WAIT_L(n) asm volatile("s_waitcnt lgkmcnt(" #n ")" ::: "memory")
; #define PG8_BAR __builtin_amdgcn_s_barrier()
; #define PG8_SCHED __builtin_amdgcn_sched_barrier(0)
; template <class Epi, class Sched, bool ALIGN_EPI = false, bool SP2 = false>
; __device__ __forceinline__ void gemm_phase(PG8_LAS unsigned char* lds, const Gemm g, const Sched& S, const Epi& E) {
;     ...
;             PG8_WAIT_V(8); PG8_WAIT_L(0); PG8_BAR; PG8_MMA(1, 0, At, B0); PG8_MMA(1, 1, At, B1); PG8_BAR; PG8_SCHED;
;             PG8_LDB(B0, 1, 0); PG8_LDB(B1, 1, 1); PG8_SCHED; PG8_LDA(At, 1, 0); PG8_STAGE(PG8_SA(0, 1), a2 + hstep, voffA);
;             PG8_WAIT_V(8); PG8_WAIT_L(0); PG8_BAR; PG8_MMA(0, 0, At, B0); PG8_MMA(0, 1, At, B1); PG8_BAR; PG8_SCHED;
	s_setprio 1
	s_waitcnt lgkmcnt(0)
	v_mfma_f32_16x16x32_bf16 v[60:63], v[146:149], v[204:207], 0
	v_mfma_f32_16x16x32_bf16 v[56:59], v[154:157], v[204:207], 0
	v_mfma_f32_16x16x32_bf16 v[44:47], v[146:149], v[212:215], 0
	v_mfma_f32_16x16x32_bf16 v[40:43], v[154:157], v[212:215], 0
	v_mfma_f32_16x16x32_bf16 v[28:31], v[146:149], v[220:223], 0
	v_mfma_f32_16x16x32_bf16 v[24:27], v[154:157], v[220:223], 0
	v_mfma_f32_16x16x32_bf16 v[12:15], v[146:149], v[228:231], 0
	v_mfma_f32_16x16x32_bf16 v[8:11], v[154:157], v[228:231], 0
	v_mfma_f32_16x16x32_bf16 v[60:63], v[150:153], v[208:211], v[60:63]
	v_mfma_f32_16x16x32_bf16 v[56:59], v[162:165], v[208:211], v[56:59]
	v_mfma_f32_16x16x32_bf16 v[44:47], v[150:153], v[216:219], v[44:47]
	v_mfma_f32_16x16x32_bf16 v[40:43], v[162:165], v[216:219], v[40:43]
	v_mfma_f32_16x16x32_bf16 v[28:31], v[150:153], v[224:227], v[28:31]
	v_mfma_f32_16x16x32_bf16 v[24:27], v[162:165], v[224:227], v[24:27]
	v_mfma_f32_16x16x32_bf16 v[12:15], v[150:153], v[232:235], v[12:15]
	v_mfma_f32_16x16x32_bf16 v[8:11], v[162:165], v[232:235], v[8:11]
	s_setprio 0
	s_setprio 1
	v_mfma_f32_16x16x32_bf16 v[52:55], v[166:169], v[204:207], 0
	v_mfma_f32_16x16x32_bf16 v[48:51], v[196:199], v[204:207], 0
	v_mfma_f32_16x16x32_bf16 v[36:39], v[166:169], v[212:215], 0
	v_mfma_f32_16x16x32_bf16 v[32:35], v[196:199], v[212:215], 0
	v_mfma_f32_16x16x32_bf16 v[20:23], v[166:169], v[220:223], 0
	v_mfma_f32_16x16x32_bf16 v[16:19], v[196:199], v[220:223], 0
	v_mfma_f32_16x16x32_bf16 v[4:7], v[166:169], v[228:231], 0
	v_mfma_f32_16x16x32_bf16 v[0:3], v[196:199], v[228:231], 0
	v_mfma_f32_16x16x32_bf16 v[52:55], v[192:195], v[208:211], v[52:55]
	v_mfma_f32_16x16x32_bf16 v[48:51], v[200:203], v[208:211], v[48:51]
	v_mfma_f32_16x16x32_bf16 v[36:39], v[192:195], v[216:219], v[36:39]
	v_mfma_f32_16x16x32_bf16 v[32:35], v[200:203], v[216:219], v[32:35]
	v_mfma_f32_16x16x32_bf16 v[20:23], v[192:195], v[224:227], v[20:23]
	v_mfma_f32_16x16x32_bf16 v[16:19], v[200:203], v[224:227], v[16:19]
	v_mfma_f32_16x16x32_bf16 v[4:7], v[192:195], v[232:235], v[4:7]
	v_mfma_f32_16x16x32_bf16 v[0:3], v[200:203], v[232:235], v[0:3]
	s_setprio 0
	s_barrier
	s_add_i32 s47, 0, 0x18000
	s_add_i32 s50, 0, 0x1c000
	v_add_u32_e32 v162, s47, v159
	v_add_u32_e32 v184, s50, v159
	ds_read_b128 v[146:149], v162
	ds_read_b128 v[150:153], v162 offset:1024
	ds_read_b128 v[154:157], v162 offset:2048
	ds_read_b128 v[162:165], v162 offset:3072
	ds_read_b128 v[166:169], v184
	ds_read_b128 v[192:195], v184 offset:1024
	ds_read_b128 v[196:199], v184 offset:2048
	ds_read_b128 v[200:203], v184 offset:3072
	s_add_u32 s24, s60, 0x40000
	s_addc_u32 s25, s61, 0
	s_mov_b32 m0, s63
	v_lshl_add_u64 v[242:243], s[24:25], 0, v[128:129]
	ds_read_b128 v[204:207], v161 offset:32768
	ds_read_b128 v[208:211], v161 offset:33792
	ds_read_b128 v[212:215], v161 offset:34816
	ds_read_b128 v[216:219], v161 offset:35840
	ds_read_b128 v[220:223], v161 offset:36864
	ds_read_b128 v[224:227], v161 offset:37888
	ds_read_b128 v[228:231], v161 offset:38912
	ds_read_b128 v[232:235], v161 offset:39936
	global_load_lds_dwordx4 v[242:243], off
	v_lshl_add_u64 v[242:243], s[24:25], 0, v[130:131]
	s_mov_b32 m0, s64
	s_nop 0
	global_load_lds_dwordx4 v[242:243], off
	s_waitcnt vmcnt(8)
	s_waitcnt lgkmcnt(0)
	s_barrier
	s_setprio 1
	s_waitcnt lgkmcnt(0)
	v_mfma_f32_16x16x32_bf16 v[124:127], v[146:149], v[204:207], v[124:127]
	v_mfma_f32_16x16x32_bf16 v[120:123], v[154:157], v[204:207], v[120:123]
	v_mfma_f32_16x16x32_bf16 v[108:111], v[146:149], v[212:215], v[108:111]
	v_mfma_f32_16x16x32_bf16 v[104:107], v[154:157], v[212:215], v[104:107]
	v_mfma_f32_16x16x32_bf16 v[92:95], v[146:149], v[220:223], v[92:95]
	v_mfma_f32_16x16x32_bf16 v[88:91], v[154:157], v[220:223], v[88:91]
	v_mfma_f32_16x16x32_bf16 v[76:79], v[146:149], v[228:231], v[76:79]
	v_mfma_f32_16x16x32_bf16 v[72:75], v[154:157], v[228:231], v[72:75]
	v_mfma_f32_16x16x32_bf16 v[124:127], v[150:153], v[208:211], v[124:127]
	v_mfma_f32_16x16x32_bf16 v[120:123], v[162:165], v[208:211], v[120:123]
	v_mfma_f32_16x16x32_bf16 v[108:111], v[150:153], v[216:219], v[108:111]
	v_mfma_f32_16x16x32_bf16 v[104:107], v[162:165], v[216:219], v[104:107]
	v_mfma_f32_16x16x32_bf16 v[92:95], v[150:153], v[224:227], v[92:95]
	v_mfma_f32_16x16x32_bf16 v[88:91], v[162:165], v[224:227], v[88:91]
	v_mfma_f32_16x16x32_bf16 v[76:79], v[150:153], v[232:235], v[76:79]
	v_mfma_f32_16x16x32_bf16 v[72:75], v[162:165], v[232:235], v[72:75]
	s_setprio 0
	s_setprio 1
	v_mfma_f32_16x16x32_bf16 v[116:119], v[166:169], v[204:207], v[116:119]
	v_mfma_f32_16x16x32_bf16 v[112:115], v[196:199], v[204:207], v[112:115]
	v_mfma_f32_16x16x32_bf16 v[100:103], v[166:169], v[212:215], v[100:103]
	v_mfma_f32_16x16x32_bf16 v[96:99], v[196:199], v[212:215], v[96:99]
	v_mfma_f32_16x16x32_bf16 v[84:87], v[166:169], v[220:223], v[84:87]
	v_mfma_f32_16x16x32_bf16 v[80:83], v[196:199], v[220:223], v[80:83]
	v_mfma_f32_16x16x32_bf16 v[68:71], v[166:169], v[228:231], v[68:71]
	v_mfma_f32_16x16x32_bf16 v[64:67], v[196:199], v[228:231], v[64:67]
	v_mfma_f32_16x16x32_bf16 v[116:119], v[192:195], v[208:211], v[116:119]
	v_mfma_f32_16x16x32_bf16 v[112:115], v[200:203], v[208:211], v[112:115]
	v_mfma_f32_16x16x32_bf16 v[100:103], v[192:195], v[216:219], v[100:103]
	v_mfma_f32_16x16x32_bf16 v[96:99], v[200:203], v[216:219], v[96:99]
	v_mfma_f32_16x16x32_bf16 v[84:87], v[192:195], v[224:227], v[84:87]
	v_mfma_f32_16x16x32_bf16 v[80:83], v[200:203], v[224:227], v[80:83]
	v_mfma_f32_16x16x32_bf16 v[68:71], v[192:195], v[232:235], v[68:71]
	v_mfma_f32_16x16x32_bf16 v[64:67], v[200:203], v[232:235], v[64:67]
	s_setprio 0
	s_barrier
; #define PG8_STAGE(bufoff, gbase, voff) do { _Pragma("unroll") for (int _i = 0; _i < 2; ++_i) \
;         __builtin_amdgcn_global_load_lds((const unsigned*)((const char*)(gbase) + (voff)[_i]), (PG8_LAS unsigned*)(lds + (bufoff) + ldsw + _i * 8192), 16, 0, 0); } while (0)
; #define PG8_LDA(dst, b, h) do { _Pragma("unroll") for (int m = 0; m < 4; ++m) _Pragma("unroll") for (int k = 0; k < 2; ++k) dst[m][k] = *(const PG8_LAS bf16x8*)(lds + PG8_SA(b, h) + aoff + m * 2048 + k * 1024); } while (0)
; #define PG8_LDB(dst, b, h) do { _Pragma("unroll") for (int n = 0; n < 2; ++n) _Pragma("unroll") for (int k = 0; k < 2; ++k) dst[n][k] = *(const PG8_LAS bf16x8*)(lds + PG8_SB(b, h) + boff + n * 2048 + k * 1024); } while (0)
; template <class Epi, class Sched, bool ALIGN_EPI = false, bool SP2 = false>
; __device__ __forceinline__ void gemm_phase(PG8_LAS unsigned char* lds, const Gemm g, const Sched& S, const Epi& E) {
;     ...
;         for (int t = 0; t < nt; t += 2) {
;             const bool last = (t == nt - 2);
;             const char* a1 = cA + (size_t)(t + 1) * kstep;
;             const char* a2 = last ? nA : cA + (size_t)(t + 2) * kstep; const char* b2 = last ? nB : cB + (size_t)(t + 2) * kstep;
;             const char* a3 = a2 + kstep; const char* b3 = b2 + kstep;
;             if (last && has_next) S.a_ready(nxt);
;             if constexpr (SP2) {
;             PG8_LDB(B0, 0, 0); PG8_LDB(B1, 0, 1); PG8_SCHED; PG8_LDA(At, 0, 0); PG8_STAGE(PG8_SA(1, 1), a1 + hstep, voffA);
;             PG8_WAIT_V(8); PG8_WAIT_L(0); PG8_BAR; PG8_MMA(0, 0, At, B0); PG8_MMA(0, 1, At, B1); PG8_BAR; PG8_SCHED;
;             PG8_LDA(At, 0, 1); PG8_STAGE(PG8_SB(0, 0), b2, voffB); PG8_STAGE(PG8_SB(0, 1), b2 + hstep, voffB); PG8_STAGE(PG8_SA(0, 0), a2, voffA);
;             PG8_WAIT_V(8); PG8_WAIT_L(0); PG8_BAR; PG8_MMA(1, 0, At, B0); PG8_MMA(1, 1, At, B1); PG8_BAR; PG8_SCHED;
;             PG8_LDB(B0, 1, 0); PG8_LDB(B1, 1, 1); PG8_SCHED; PG8_LDA(At, 1, 0); PG8_STAGE(PG8_SA(0, 1), a2 + hstep, voffA);
;             PG8_WAIT_V(8); PG8_WAIT_L(0); PG8_BAR; PG8_MMA(0, 0, At, B0); PG8_MMA(0, 1, At, B1); PG8_BAR; PG8_SCHED;
;             PG8_LDA(At, 1, 1); PG8_STAGE(PG8_SB(1, 0), b3, voffB); PG8_STAGE(PG8_SB(1, 1), b3 + hstep, voffB); PG8_STAGE(PG8_SA(1, 0), a3, voffA);
;             PG8_WAIT_V(8); PG8_WAIT_L(0); PG8_BAR; PG8_MMA(1, 0, At, B0); PG8_MMA(1, 1, At, B1); PG8_BAR; PG8_SCHED;
	s_add_i32 s24, s47, s23
	v_lshl_add_u64 v[170:171], v[170:171], 0, s[14:15]
	s_mov_b32 m0, s24
	ds_read_b128 v[204:207], v161 offset:49152
	ds_read_b128 v[208:211], v161 offset:50176
	ds_read_b128 v[212:215], v161 offset:51200
	ds_read_b128 v[216:219], v161 offset:52224
	ds_read_b128 v[220:223], v161 offset:53248
	ds_read_b128 v[224:227], v161 offset:54272
	ds_read_b128 v[228:231], v161 offset:55296
	ds_read_b128 v[232:235], v161 offset:56320
	global_load_lds_dwordx4 v[170:171], off
	s_add_i32 m0, s24, 0x2000
	s_add_u32 s24, s58, 0x40080
	v_lshl_add_u64 v[170:171], v[236:237], 0, s[14:15]
	s_addc_u32 s25, s59, 0
	s_add_i32 s47, s50, s23
	global_load_lds_dwordx4 v[170:171], off
	v_lshl_add_u64 v[170:171], s[24:25], 0, v[132:133]
	s_mov_b32 m0, s47
	s_nop 0
	global_load_lds_dwordx4 v[170:171], off
	v_lshl_add_u64 v[170:171], s[24:25], 0, v[140:141]
	s_add_i32 m0, s47, 0x2000
	s_nop 0
	global_load_lds_dwordx4 v[170:171], off
	v_lshl_add_u64 v[170:171], v[238:239], 0, s[14:15]
	s_mov_b32 m0, s65
	s_nop 0
	global_load_lds_dwordx4 v[170:171], off
	v_lshl_add_u64 v[170:171], v[240:241], 0, s[14:15]
	s_mov_b32 m0, s66
	s_nop 0
	global_load_lds_dwordx4 v[170:171], off
	s_waitcnt vmcnt(8)
	s_waitcnt lgkmcnt(0)
	s_barrier
	s_setprio 1
	s_waitcnt lgkmcnt(0)
	v_mfma_f32_16x16x32_bf16 v[60:63], v[146:149], v[204:207], v[60:63]
	v_mfma_f32_16x16x32_bf16 v[56:59], v[154:157], v[204:207], v[56:59]
	v_mfma_f32_16x16x32_bf16 v[44:47], v[146:149], v[212:215], v[44:47]
	v_mfma_f32_16x16x32_bf16 v[40:43], v[154:157], v[212:215], v[40:43]
	v_mfma_f32_16x16x32_bf16 v[28:31], v[146:149], v[220:223], v[28:31]
	v_mfma_f32_16x16x32_bf16 v[24:27], v[154:157], v[220:223], v[24:27]
	v_mfma_f32_16x16x32_bf16 v[12:15], v[146:149], v[228:231], v[12:15]
	v_mfma_f32_16x16x32_bf16 v[8:11], v[154:157], v[228:231], v[8:11]
	v_mfma_f32_16x16x32_bf16 v[60:63], v[150:153], v[208:211], v[60:63]
	v_mfma_f32_16x16x32_bf16 v[56:59], v[162:165], v[208:211], v[56:59]
	v_mfma_f32_16x16x32_bf16 v[44:47], v[150:153], v[216:219], v[44:47]
	v_mfma_f32_16x16x32_bf16 v[40:43], v[162:165], v[216:219], v[40:43]
	v_mfma_f32_16x16x32_bf16 v[28:31], v[150:153], v[224:227], v[28:31]
	v_mfma_f32_16x16x32_bf16 v[24:27], v[162:165], v[224:227], v[24:27]
	v_mfma_f32_16x16x32_bf16 v[12:15], v[150:153], v[232:235], v[12:15]
	v_mfma_f32_16x16x32_bf16 v[8:11], v[162:165], v[232:235], v[8:11]
	s_setprio 0
	s_setprio 1
	v_mfma_f32_16x16x32_bf16 v[52:55], v[166:169], v[204:207], v[52:55]
	v_mfma_f32_16x16x32_bf16 v[48:51], v[196:199], v[204:207], v[48:51]
	v_mfma_f32_16x16x32_bf16 v[36:39], v[166:169], v[212:215], v[36:39]
	v_mfma_f32_16x16x32_bf16 v[32:35], v[196:199], v[212:215], v[32:35]
	v_mfma_f32_16x16x32_bf16 v[20:23], v[166:169], v[220:223], v[20:23]
	v_mfma_f32_16x16x32_bf16 v[16:19], v[196:199], v[220:223], v[16:19]
	v_mfma_f32_16x16x32_bf16 v[4:7], v[166:169], v[228:231], v[4:7]
	v_mfma_f32_16x16x32_bf16 v[0:3], v[196:199], v[228:231], v[0:3]
	v_mfma_f32_16x16x32_bf16 v[52:55], v[192:195], v[208:211], v[52:55]
	v_mfma_f32_16x16x32_bf16 v[48:51], v[200:203], v[208:211], v[48:51]
	v_mfma_f32_16x16x32_bf16 v[36:39], v[192:195], v[216:219], v[36:39]
	v_mfma_f32_16x16x32_bf16 v[32:35], v[200:203], v[216:219], v[32:35]
	v_mfma_f32_16x16x32_bf16 v[20:23], v[192:195], v[224:227], v[20:23]
	v_mfma_f32_16x16x32_bf16 v[16:19], v[200:203], v[224:227], v[16:19]
	v_mfma_f32_16x16x32_bf16 v[4:7], v[192:195], v[232:235], v[4:7]
	v_mfma_f32_16x16x32_bf16 v[0:3], v[200:203], v[232:235], v[0:3]
	s_setprio 0
	s_add_i32 s45, s45, 2
	s_add_u32 s56, s56, 0x100
	s_addc_u32 s57, s57, 0
	s_add_u32 s22, s22, 0x100
	s_addc_u32 s33, s33, 0
	s_cmp_gt_u32 s45, 13
	s_barrier
.LBB0_554:
	s_add_u32 s24, s56, 0xfffc0080
	s_addc_u32 s25, s57, -1
	s_add_i32 s47, 0, 0x10000
	s_cmp_eq_u32 s45, 12
	s_cselect_b32 s61, s0, s25
	s_cselect_b32 s60, s1, s24
	s_cselect_b32 s59, s17, s33
	s_cselect_b32 s58, s21, s22
	s_add_i32 s50, 0, 0x14000
	v_add_u32_e32 v162, s47, v159
	v_add_u32_e32 v170, s50, v159
	ds_read_b128 v[146:149], v162
	ds_read_b128 v[150:153], v162 offset:1024
	ds_read_b128 v[154:157], v162 offset:2048
	ds_read_b128 v[162:165], v162 offset:3072
	ds_read_b128 v[166:169], v170
	ds_read_b128 v[192:195], v170 offset:1024
	ds_read_b128 v[196:199], v170 offset:2048
	ds_read_b128 v[200:203], v170 offset:3072
	v_lshl_add_u64 v[170:171], s[56:57], 0, v[142:143]
	s_add_i32 m0, s29, 0xc000
	ds_read_b128 v[204:207], v161
	ds_read_b128 v[208:211], v161 offset:1024
	ds_read_b128 v[212:215], v161 offset:2048
	ds_read_b128 v[216:219], v161 offset:3072
	ds_read_b128 v[220:223], v161 offset:4096
	ds_read_b128 v[224:227], v161 offset:5120
	ds_read_b128 v[228:231], v161 offset:6144
	ds_read_b128 v[232:235], v161 offset:7168
	global_load_lds_dwordx4 v[170:171], off
	v_lshl_add_u64 v[170:171], s[56:57], 0, v[144:145]
	s_add_i32 m0, s29, 0xe000
	s_nop 0
	global_load_lds_dwordx4 v[170:171], off
	s_waitcnt vmcnt(8)
	s_waitcnt lgkmcnt(0)
	s_barrier
; #define PG8_STAGE(bufoff, gbase, voff) do { _Pragma("unroll") for (int _i = 0; _i < 2; ++_i) \
;         __builtin_amdgcn_global_load_lds((const unsigned*)((const char*)(gbase) + (voff)[_i]), (PG8_LAS unsigned*)(lds + (bufoff) + ldsw + _i * 8192), 16, 0, 0); } while (0)
; #define PG8_LDA(dst, b, h) do { _Pragma("unroll") for (int m = 0; m < 4; ++m) _Pragma("unroll") for (int k = 0; k < 2; ++k) dst[m][k] = *(const PG8_LAS bf16x8*)(lds + PG8_SA(b, h) + aoff + m * 2048 + k * 1024); } while (0)
; #define PG8_MMA(ai, bj, At, Bt) do { __builtin_amdgcn_s_setprio(1); _Pragma("unroll") for (int m = 0; m < 4; ++m) _Pragma("unroll") for (int n = 0; n < 2; ++n) _Pragma("unroll") for (int k = 0; k < 2; ++k) \
;         acc[ai][bj][m][n] = __builtin_amdgcn_mfma_f32_16x16x32_bf16(Bt[n][k], At[m][k], acc[ai][bj][m][n], 0, 0, 0); __builtin_amdgcn_s_setprio(0); } while (0)
; #define PG8_WAIT_V(n) asm volatile("s_waitcnt vmcnt(" #n ")" ::: "memory")
; #define PG8_WAIT_L(n) asm volatile("s_waitcnt lgkmcnt(" #n ")" ::: "memory")
; #define PG8_BAR __builtin_amdgcn_s_barrier()
; #define PG8_SCHED __builtin_amdgcn_sched_barrier(0)
; template <class Epi, class Sched, bool ALIGN_EPI = false, bool SP2 = false>
; __device__ __forceinline__ void gemm_phase(PG8_LAS unsigned char* lds, const Gemm g, const Sched& S, const Epi& E) {
;     ...
;             PG8_WAIT_V(8); PG8_WAIT_L(0); PG8_BAR; PG8_MMA(0, 0, At, B0); PG8_MMA(0, 1, At, B1); PG8_BAR; PG8_SCHED;
;             PG8_LDA(At, 0, 1); PG8_STAGE(PG8_SB(0, 0), b2, voffB); PG8_STAGE(PG8_SB(0, 1), b2 + hstep, voffB); PG8_STAGE(PG8_SA(0, 0), a2, voffA);
;             PG8_WAIT_V(8); PG8_WAIT_L(0); PG8_BAR; PG8_MMA(1, 0, At, B0); PG8_MMA(1, 1, At, B1); PG8_BAR; PG8_SCHED;
	s_setprio 1
	s_waitcnt lgkmcnt(0)
	v_mfma_f32_16x16x32_bf16 v[124:127], v[146:149], v[204:207], v[124:127]
	v_mfma_f32_16x16x32_bf16 v[120:123], v[154:157], v[204:207], v[120:123]
	v_mfma_f32_16x16x32_bf16 v[108:111], v[146:149], v[212:215], v[108:111]
	v_mfma_f32_16x16x32_bf16 v[104:107], v[154:157], v[212:215], v[104:107]
	v_mfma_f32_16x16x32_bf16 v[92:95], v[146:149], v[220:223], v[92:95]
	v_mfma_f32_16x16x32_bf16 v[88:91], v[154:157], v[220:223], v[88:91]
	v_mfma_f32_16x16x32_bf16 v[76:79], v[146:149], v[228:231], v[76:79]
	v_mfma_f32_16x16x32_bf16 v[72:75], v[154:157], v[228:231], v[72:75]
	v_mfma_f32_16x16x32_bf16 v[124:127], v[150:153], v[208:211], v[124:127]
	v_mfma_f32_16x16x32_bf16 v[120:123], v[162:165], v[208:211], v[120:123]
	v_mfma_f32_16x16x32_bf16 v[108:111], v[150:153], v[216:219], v[108:111]
	v_mfma_f32_16x16x32_bf16 v[104:107], v[162:165], v[216:219], v[104:107]
	v_mfma_f32_16x16x32_bf16 v[92:95], v[150:153], v[224:227], v[92:95]
	v_mfma_f32_16x16x32_bf16 v[88:91], v[162:165], v[224:227], v[88:91]
	v_mfma_f32_16x16x32_bf16 v[76:79], v[150:153], v[232:235], v[76:79]
	v_mfma_f32_16x16x32_bf16 v[72:75], v[162:165], v[232:235], v[72:75]
	s_setprio 0
	s_setprio 1
	v_mfma_f32_16x16x32_bf16 v[116:119], v[166:169], v[204:207], v[116:119]
	v_mfma_f32_16x16x32_bf16 v[112:115], v[196:199], v[204:207], v[112:115]
	v_mfma_f32_16x16x32_bf16 v[100:103], v[166:169], v[212:215], v[100:103]
	v_mfma_f32_16x16x32_bf16 v[96:99], v[196:199], v[212:215], v[96:99]
	v_mfma_f32_16x16x32_bf16 v[84:87], v[166:169], v[220:223], v[84:87]
	v_mfma_f32_16x16x32_bf16 v[80:83], v[196:199], v[220:223], v[80:83]
	v_mfma_f32_16x16x32_bf16 v[68:71], v[166:169], v[228:231], v[68:71]
	v_mfma_f32_16x16x32_bf16 v[64:67], v[196:199], v[228:231], v[64:67]
	v_mfma_f32_16x16x32_bf16 v[116:119], v[192:195], v[208:211], v[116:119]
	v_mfma_f32_16x16x32_bf16 v[112:115], v[200:203], v[208:211], v[112:115]
	v_mfma_f32_16x16x32_bf16 v[100:103], v[192:195], v[216:219], v[100:103]
	v_mfma_f32_16x16x32_bf16 v[96:99], v[200:203], v[216:219], v[96:99]
	v_mfma_f32_16x16x32_bf16 v[84:87], v[192:195], v[224:227], v[84:87]
	v_mfma_f32_16x16x32_bf16 v[80:83], v[200:203], v[224:227], v[80:83]
	v_mfma_f32_16x16x32_bf16 v[68:71], v[192:195], v[232:235], v[68:71]
	v_mfma_f32_16x16x32_bf16 v[64:67], v[200:203], v[232:235], v[64:67]
	s_setprio 0
	s_barrier
	s_add_i32 s24, s47, s23
	v_lshl_add_u64 v[170:171], s[58:59], 0, v[132:133]
	s_mov_b32 m0, s24
	ds_read_b128 v[204:207], v161 offset:16384
	ds_read_b128 v[208:211], v161 offset:17408
	ds_read_b128 v[212:215], v161 offset:18432
	ds_read_b128 v[216:219], v161 offset:19456
	ds_read_b128 v[220:223], v161 offset:20480
	ds_read_b128 v[224:227], v161 offset:21504
	ds_read_b128 v[228:231], v161 offset:22528
	ds_read_b128 v[232:235], v161 offset:23552
	global_load_lds_dwordx4 v[170:171], off
	s_add_i32 m0, s24, 0x2000
	s_add_u32 s24, s58, 0x40000
	v_lshl_add_u64 v[236:237], s[58:59], 0, v[140:141]
	s_addc_u32 s25, s59, 0
	s_add_i32 s47, s50, s23
	global_load_lds_dwordx4 v[236:237], off
	v_lshl_add_u64 v[238:239], s[24:25], 0, v[132:133]
	s_mov_b32 m0, s47
	v_lshl_add_u64 v[240:241], s[60:61], 0, v[130:131]
	global_load_lds_dwordx4 v[238:239], off
	v_lshl_add_u64 v[238:239], s[24:25], 0, v[140:141]
	s_add_i32 m0, s47, 0x2000
	s_nop 0
	global_load_lds_dwordx4 v[238:239], off
	v_lshl_add_u64 v[238:239], s[60:61], 0, v[128:129]
	s_mov_b32 m0, s29
	s_nop 0
	global_load_lds_dwordx4 v[238:239], off
	s_mov_b32 m0, s62
	s_nop 0
	global_load_lds_dwordx4 v[240:241], off
	s_waitcnt vmcnt(8)
	s_waitcnt lgkmcnt(0)
	s_barrier
	s_setprio 1
	s_waitcnt lgkmcnt(0)
	v_mfma_f32_16x16x32_bf16 v[60:63], v[146:149], v[204:207], v[60:63]
	v_mfma_f32_16x16x32_bf16 v[56:59], v[154:157], v[204:207], v[56:59]
	v_mfma_f32_16x16x32_bf16 v[44:47], v[146:149], v[212:215], v[44:47]
	v_mfma_f32_16x16x32_bf16 v[40:43], v[154:157], v[212:215], v[40:43]
	v_mfma_f32_16x16x32_bf16 v[28:31], v[146:149], v[220:223], v[28:31]
	v_mfma_f32_16x16x32_bf16 v[24:27], v[154:157], v[220:223], v[24:27]
	v_mfma_f32_16x16x32_bf16 v[12:15], v[146:149], v[228:231], v[12:15]
	v_mfma_f32_16x16x32_bf16 v[8:11], v[154:157], v[228:231], v[8:11]
	v_mfma_f32_16x16x32_bf16 v[60:63], v[150:153], v[208:211], v[60:63]
	v_mfma_f32_16x16x32_bf16 v[56:59], v[162:165], v[208:211], v[56:59]
	v_mfma_f32_16x16x32_bf16 v[44:47], v[150:153], v[216:219], v[44:47]
	v_mfma_f32_16x16x32_bf16 v[40:43], v[162:165], v[216:219], v[40:43]
	v_mfma_f32_16x16x32_bf16 v[28:31], v[150:153], v[224:227], v[28:31]
	v_mfma_f32_16x16x32_bf16 v[24:27], v[162:165], v[224:227], v[24:27]
	v_mfma_f32_16x16x32_bf16 v[12:15], v[150:153], v[232:235], v[12:15]
	v_mfma_f32_16x16x32_bf16 v[8:11], v[162:165], v[232:235], v[8:11]
	s_setprio 0
	s_setprio 1
	v_mfma_f32_16x16x32_bf16 v[52:55], v[166:169], v[204:207], v[52:55]
	v_mfma_f32_16x16x32_bf16 v[48:51], v[196:199], v[204:207], v[48:51]
	v_mfma_f32_16x16x32_bf16 v[36:39], v[166:169], v[212:215], v[36:39]
	v_mfma_f32_16x16x32_bf16 v[32:35], v[196:199], v[212:215], v[32:35]
	v_mfma_f32_16x16x32_bf16 v[20:23], v[166:169], v[220:223], v[20:23]
	v_mfma_f32_16x16x32_bf16 v[16:19], v[196:199], v[220:223], v[16:19]
	v_mfma_f32_16x16x32_bf16 v[4:7], v[166:169], v[228:231], v[4:7]
	v_mfma_f32_16x16x32_bf16 v[0:3], v[196:199], v[228:231], v[0:3]
	v_mfma_f32_16x16x32_bf16 v[52:55], v[192:195], v[208:211], v[52:55]
	v_mfma_f32_16x16x32_bf16 v[48:51], v[200:203], v[208:211], v[48:51]
	v_mfma_f32_16x16x32_bf16 v[36:39], v[192:195], v[216:219], v[36:39]
	v_mfma_f32_16x16x32_bf16 v[32:35], v[200:203], v[216:219], v[32:35]
	v_mfma_f32_16x16x32_bf16 v[20:23], v[192:195], v[224:227], v[20:23]
	v_mfma_f32_16x16x32_bf16 v[16:19], v[200:203], v[224:227], v[16:19]
	v_mfma_f32_16x16x32_bf16 v[4:7], v[192:195], v[232:235], v[4:7]
	v_mfma_f32_16x16x32_bf16 v[0:3], v[200:203], v[232:235], v[0:3]
	s_setprio 0
	s_barrier
; #define PG8_STAGE(bufoff, gbase, voff) do { _Pragma("unroll") for (int _i = 0; _i < 2; ++_i) \
;         __builtin_amdgcn_global_load_lds((const unsigned*)((const char*)(gbase) + (voff)[_i]), (PG8_LAS unsigned*)(lds + (bufoff) + ldsw + _i * 8192), 16, 0, 0); } while (0)
; #define PG8_LDA(dst, b, h) do { _Pragma("unroll") for (int m = 0; m < 4; ++m) _Pragma("unroll") for (int k = 0; k < 2; ++k) dst[m][k] = *(const PG8_LAS bf16x8*)(lds + PG8_SA(b, h) + aoff + m * 2048 + k * 1024); } while (0)
; #define PG8_LDB(dst, b, h) do { _Pragma("unroll") for (int n = 0; n < 2; ++n) _Pragma("unroll") for (int k = 0; k < 2; ++k) dst[n][k] = *(const PG8_LAS bf16x8*)(lds + PG8_SB(b, h) + boff + n * 2048 + k * 1024); } while (0)
; #define PG8_MMA(ai, bj, At, Bt) do { __builtin_amdgcn_s_setprio(1); _Pragma("unroll") for (int m = 0; m < 4; ++m) _Pragma("unroll") for (int n = 0; n < 2; ++n) _Pragma("unroll") for (int k = 0; k < 2; ++k) \
;         acc[ai][bj][m][n] = __builtin_amdgcn_mfma_f32_16x16x32_bf16(Bt[n][k], At[m][k], acc[ai][bj][m][n], 0, 0, 0); __builtin_amdgcn_s_setprio(0); } while (0)
; #define PG8_WAIT_V(n) asm volatile("s_waitcnt vmcnt(" #n ")" ::: "memory")
; #define PG8_WAIT_L(n) asm volatile("s_waitcnt lgkmcnt(" #n ")" ::: "memory")
; #define PG8_BAR __builtin_amdgcn_s_barrier()
; #define PG8_SCHED __builtin_amdgcn_sched_barrier(0)
; template <class Epi, class Sched, bool ALIGN_EPI = false, bool SP2 = false>
; __device__ __forceinline__ void gemm_phase(PG8_LAS unsigned char* lds, const Gemm g, const Sched& S, const Epi& E) {
;     ...
;             PG8_LDB(B0, 1, 0); PG8_LDB(B1, 1, 1); PG8_SCHED; PG8_LDA(At, 1, 0); PG8_STAGE(PG8_SA(0, 1), a2 + hstep, voffA);
;             PG8_WAIT_V(8); PG8_WAIT_L(0); PG8_BAR; PG8_MMA(0, 0, At, B0); PG8_MMA(0, 1, At, B1); PG8_BAR; PG8_SCHED;
	s_add_i32 s47, 0, 0x18000
	s_add_i32 s50, 0, 0x1c000
	v_add_u32_e32 v162, s47, v159
	v_add_u32_e32 v184, s50, v159
	ds_read_b128 v[146:149], v162
	ds_read_b128 v[150:153], v162 offset:1024
	ds_read_b128 v[154:157], v162 offset:2048
	ds_read_b128 v[162:165], v162 offset:3072
	ds_read_b128 v[166:169], v184
	ds_read_b128 v[192:195], v184 offset:1024
	ds_read_b128 v[196:199], v184 offset:2048
	ds_read_b128 v[200:203], v184 offset:3072
	s_add_u32 s24, s60, 0x40000
	s_addc_u32 s25, s61, 0
	s_mov_b32 m0, s63
	v_lshl_add_u64 v[242:243], s[24:25], 0, v[128:129]
	ds_read_b128 v[204:207], v161 offset:32768
	ds_read_b128 v[208:211], v161 offset:33792
	ds_read_b128 v[212:215], v161 offset:34816
	ds_read_b128 v[216:219], v161 offset:35840
	ds_read_b128 v[220:223], v161 offset:36864
	ds_read_b128 v[224:227], v161 offset:37888
	ds_read_b128 v[228:231], v161 offset:38912
	ds_read_b128 v[232:235], v161 offset:39936
	global_load_lds_dwordx4 v[242:243], off
	v_lshl_add_u64 v[242:243], s[24:25], 0, v[130:131]
	s_mov_b32 m0, s64
	s_nop 0
	global_load_lds_dwordx4 v[242:243], off
	s_waitcnt vmcnt(8)
	s_waitcnt lgkmcnt(0)
	s_barrier
	s_setprio 1
	s_waitcnt lgkmcnt(0)
	v_mfma_f32_16x16x32_bf16 v[124:127], v[146:149], v[204:207], v[124:127]
	v_mfma_f32_16x16x32_bf16 v[120:123], v[154:157], v[204:207], v[120:123]
	v_mfma_f32_16x16x32_bf16 v[108:111], v[146:149], v[212:215], v[108:111]
	v_mfma_f32_16x16x32_bf16 v[104:107], v[154:157], v[212:215], v[104:107]
	v_mfma_f32_16x16x32_bf16 v[92:95], v[146:149], v[220:223], v[92:95]
	v_mfma_f32_16x16x32_bf16 v[88:91], v[154:157], v[220:223], v[88:91]
	v_mfma_f32_16x16x32_bf16 v[76:79], v[146:149], v[228:231], v[76:79]
	v_mfma_f32_16x16x32_bf16 v[72:75], v[154:157], v[228:231], v[72:75]
	v_mfma_f32_16x16x32_bf16 v[124:127], v[150:153], v[208:211], v[124:127]
	v_mfma_f32_16x16x32_bf16 v[120:123], v[162:165], v[208:211], v[120:123]
	v_mfma_f32_16x16x32_bf16 v[108:111], v[150:153], v[216:219], v[108:111]
	v_mfma_f32_16x16x32_bf16 v[104:107], v[162:165], v[216:219], v[104:107]
	v_mfma_f32_16x16x32_bf16 v[92:95], v[150:153], v[224:227], v[92:95]
	v_mfma_f32_16x16x32_bf16 v[88:91], v[162:165], v[224:227], v[88:91]
	v_mfma_f32_16x16x32_bf16 v[76:79], v[150:153], v[232:235], v[76:79]
	v_mfma_f32_16x16x32_bf16 v[72:75], v[162:165], v[232:235], v[72:75]
	s_setprio 0
	s_setprio 1
	v_mfma_f32_16x16x32_bf16 v[116:119], v[166:169], v[204:207], v[116:119]
	v_mfma_f32_16x16x32_bf16 v[112:115], v[196:199], v[204:207], v[112:115]
	v_mfma_f32_16x16x32_bf16 v[100:103], v[166:169], v[212:215], v[100:103]
	v_mfma_f32_16x16x32_bf16 v[96:99], v[196:199], v[212:215], v[96:99]
	v_mfma_f32_16x16x32_bf16 v[84:87], v[166:169], v[220:223], v[84:87]
	v_mfma_f32_16x16x32_bf16 v[80:83], v[196:199], v[220:223], v[80:83]
	v_mfma_f32_16x16x32_bf16 v[68:71], v[166:169], v[228:231], v[68:71]
	v_mfma_f32_16x16x32_bf16 v[64:67], v[196:199], v[228:231], v[64:67]
	v_mfma_f32_16x16x32_bf16 v[116:119], v[192:195], v[208:211], v[116:119]
	v_mfma_f32_16x16x32_bf16 v[112:115], v[200:203], v[208:211], v[112:115]
	v_mfma_f32_16x16x32_bf16 v[100:103], v[192:195], v[216:219], v[100:103]
	v_mfma_f32_16x16x32_bf16 v[96:99], v[200:203], v[216:219], v[96:99]
	v_mfma_f32_16x16x32_bf16 v[84:87], v[192:195], v[224:227], v[84:87]
	v_mfma_f32_16x16x32_bf16 v[80:83], v[200:203], v[224:227], v[80:83]
	v_mfma_f32_16x16x32_bf16 v[68:71], v[192:195], v[232:235], v[68:71]
	v_mfma_f32_16x16x32_bf16 v[64:67], v[200:203], v[232:235], v[64:67]
	s_setprio 0
	s_barrier
; #define PG8_STAGE(bufoff, gbase, voff) do { _Pragma("unroll") for (int _i = 0; _i < 2; ++_i) \
;         __builtin_amdgcn_global_load_lds((const unsigned*)((const char*)(gbase) + (voff)[_i]), (PG8_LAS unsigned*)(lds + (bufoff) + ldsw + _i * 8192), 16, 0, 0); } while (0)
; #define PG8_LDA(dst, b, h) do { _Pragma("unroll") for (int m = 0; m < 4; ++m) _Pragma("unroll") for (int k = 0; k < 2; ++k) dst[m][k] = *(const PG8_LAS bf16x8*)(lds + PG8_SA(b, h) + aoff + m * 2048 + k * 1024); } while (0)
; #define PG8_MMA(ai, bj, At, Bt) do { __builtin_amdgcn_s_setprio(1); _Pragma("unroll") for (int m = 0; m < 4; ++m) _Pragma("unroll") for (int n = 0; n < 2; ++n) _Pragma("unroll") for (int k = 0; k < 2; ++k) \
;         acc[ai][bj][m][n] = __builtin_amdgcn_mfma_f32_16x16x32_bf16(Bt[n][k], At[m][k], acc[ai][bj][m][n], 0, 0, 0); __builtin_amdgcn_s_setprio(0); } while (0)
; #define PG8_WAIT_V(n) asm volatile("s_waitcnt vmcnt(" #n ")" ::: "memory")
; #define PG8_WAIT_L(n) asm volatile("s_waitcnt lgkmcnt(" #n ")" ::: "memory")
; #define PG8_BAR __builtin_amdgcn_s_barrier()
; #define PG8_SCHED __builtin_amdgcn_sched_barrier(0)
; template <class Epi, class Sched, bool ALIGN_EPI = false, bool SP2 = false>
; __device__ __forceinline__ void gemm_phase(PG8_LAS unsigned char* lds, const Gemm g, const Sched& S, const Epi& E) {
;     ...
;         for (int t = 0; t < nt; t += 2) {
;             const bool last = (t == nt - 2);
;     ...
;             PG8_LDA(At, 1, 1); PG8_STAGE(PG8_SB(1, 0), b3, voffB); PG8_STAGE(PG8_SB(1, 1), b3 + hstep, voffB); PG8_STAGE(PG8_SA(1, 0), a3, voffA);
;             PG8_WAIT_V(8); PG8_WAIT_L(0); PG8_BAR; PG8_MMA(1, 0, At, B0); PG8_MMA(1, 1, At, B1); PG8_BAR; PG8_SCHED;
	s_add_i32 s24, s47, s23
	v_lshl_add_u64 v[170:171], v[170:171], 0, s[14:15]
	s_mov_b32 m0, s24
	ds_read_b128 v[204:207], v161 offset:49152
	ds_read_b128 v[208:211], v161 offset:50176
	ds_read_b128 v[212:215], v161 offset:51200
	ds_read_b128 v[216:219], v161 offset:52224
	ds_read_b128 v[220:223], v161 offset:53248
	ds_read_b128 v[224:227], v161 offset:54272
	ds_read_b128 v[228:231], v161 offset:55296
	ds_read_b128 v[232:235], v161 offset:56320
	global_load_lds_dwordx4 v[170:171], off
	s_add_i32 m0, s24, 0x2000
	s_add_u32 s24, s58, 0x40080
	v_lshl_add_u64 v[170:171], v[236:237], 0, s[14:15]
	s_addc_u32 s25, s59, 0
	s_add_i32 s47, s50, s23
	global_load_lds_dwordx4 v[170:171], off
	v_lshl_add_u64 v[170:171], s[24:25], 0, v[132:133]
	s_mov_b32 m0, s47
	s_nop 0
	global_load_lds_dwordx4 v[170:171], off
	v_lshl_add_u64 v[170:171], s[24:25], 0, v[140:141]
	s_add_i32 m0, s47, 0x2000
	s_nop 0
	global_load_lds_dwordx4 v[170:171], off
	v_lshl_add_u64 v[170:171], v[238:239], 0, s[14:15]
	s_mov_b32 m0, s65
	s_nop 0
	global_load_lds_dwordx4 v[170:171], off
	v_lshl_add_u64 v[170:171], v[240:241], 0, s[14:15]
	s_mov_b32 m0, s66
	s_nop 0
	global_load_lds_dwordx4 v[170:171], off
	s_waitcnt vmcnt(8)
	s_waitcnt lgkmcnt(0)
	s_barrier
	s_setprio 1
	s_waitcnt lgkmcnt(0)
	v_mfma_f32_16x16x32_bf16 v[60:63], v[146:149], v[204:207], v[60:63]
	v_mfma_f32_16x16x32_bf16 v[56:59], v[154:157], v[204:207], v[56:59]
	v_mfma_f32_16x16x32_bf16 v[44:47], v[146:149], v[212:215], v[44:47]
	v_mfma_f32_16x16x32_bf16 v[40:43], v[154:157], v[212:215], v[40:43]
	v_mfma_f32_16x16x32_bf16 v[28:31], v[146:149], v[220:223], v[28:31]
	v_mfma_f32_16x16x32_bf16 v[24:27], v[154:157], v[220:223], v[24:27]
	v_mfma_f32_16x16x32_bf16 v[12:15], v[146:149], v[228:231], v[12:15]
	v_mfma_f32_16x16x32_bf16 v[8:11], v[154:157], v[228:231], v[8:11]
	v_mfma_f32_16x16x32_bf16 v[60:63], v[150:153], v[208:211], v[60:63]
	v_mfma_f32_16x16x32_bf16 v[56:59], v[162:165], v[208:211], v[56:59]
	v_mfma_f32_16x16x32_bf16 v[44:47], v[150:153], v[216:219], v[44:47]
	v_mfma_f32_16x16x32_bf16 v[40:43], v[162:165], v[216:219], v[40:43]
	v_mfma_f32_16x16x32_bf16 v[28:31], v[150:153], v[224:227], v[28:31]
	v_mfma_f32_16x16x32_bf16 v[24:27], v[162:165], v[224:227], v[24:27]
	v_mfma_f32_16x16x32_bf16 v[12:15], v[150:153], v[232:235], v[12:15]
	v_mfma_f32_16x16x32_bf16 v[8:11], v[162:165], v[232:235], v[8:11]
	s_setprio 0
	s_setprio 1
	v_mfma_f32_16x16x32_bf16 v[52:55], v[166:169], v[204:207], v[52:55]
	v_mfma_f32_16x16x32_bf16 v[48:51], v[196:199], v[204:207], v[48:51]
	v_mfma_f32_16x16x32_bf16 v[36:39], v[166:169], v[212:215], v[36:39]
	v_mfma_f32_16x16x32_bf16 v[32:35], v[196:199], v[212:215], v[32:35]
	v_mfma_f32_16x16x32_bf16 v[20:23], v[166:169], v[220:223], v[20:23]
	v_mfma_f32_16x16x32_bf16 v[16:19], v[196:199], v[220:223], v[16:19]
	v_mfma_f32_16x16x32_bf16 v[4:7], v[166:169], v[228:231], v[4:7]
	v_mfma_f32_16x16x32_bf16 v[0:3], v[196:199], v[228:231], v[0:3]
	v_mfma_f32_16x16x32_bf16 v[52:55], v[192:195], v[208:211], v[52:55]
	v_mfma_f32_16x16x32_bf16 v[48:51], v[200:203], v[208:211], v[48:51]
	v_mfma_f32_16x16x32_bf16 v[36:39], v[192:195], v[216:219], v[36:39]
	v_mfma_f32_16x16x32_bf16 v[32:35], v[200:203], v[216:219], v[32:35]
	v_mfma_f32_16x16x32_bf16 v[20:23], v[192:195], v[224:227], v[20:23]
	v_mfma_f32_16x16x32_bf16 v[16:19], v[200:203], v[224:227], v[16:19]
	v_mfma_f32_16x16x32_bf16 v[4:7], v[192:195], v[232:235], v[4:7]
	v_mfma_f32_16x16x32_bf16 v[0:3], v[200:203], v[232:235], v[0:3]
	s_setprio 0
	s_add_i32 s45, s45, 2
	s_add_u32 s56, s56, 0x100
	s_addc_u32 s57, s57, 0
	s_add_u32 s22, s22, 0x100
	s_addc_u32 s33, s33, 0
	s_cmp_gt_u32 s45, 13
	s_barrier
	s_cbranch_scc0 .LBB0_554
	s_and_b64 vcc, exec, s[8:9]
	s_cbranch_vccz .LBB0_557
	s_barrier

; #define PG8_STAGE(bufoff, gbase, voff) do { _Pragma("unroll") for (int _i = 0; _i < 2; ++_i) \
;         __builtin_amdgcn_global_load_lds((const unsigned*)((const char*)(gbase) + (voff)[_i]), (PG8_LAS unsigned*)(lds + (bufoff) + ldsw + _i * 8192), 16, 0, 0); } while (0)
; #define PG8_LDA(dst, b, h) do { _Pragma("unroll") for (int m = 0; m < 4; ++m) _Pragma("unroll") for (int k = 0; k < 2; ++k) dst[m][k] = *(const PG8_LAS bf16x8*)(lds + PG8_SA(b, h) + aoff + m * 2048 + k * 1024); } while (0)
; #define PG8_LDB(dst, b, h) do { _Pragma("unroll") for (int n = 0; n < 2; ++n) _Pragma("unroll") for (int k = 0; k < 2; ++k) dst[n][k] = *(const PG8_LAS bf16x8*)(lds + PG8_SB(b, h) + boff + n * 2048 + k * 1024); } while (0)
; #define PG8_MMA(ai, bj, At, Bt) do { __builtin_amdgcn_s_setprio(1); _Pragma("unroll") for (int m = 0; m < 4; ++m) _Pragma("unroll") for (int n = 0; n < 2; ++n) _Pragma("unroll") for (int k = 0; k < 2; ++k) \
;         acc[ai][bj][m][n] = __builtin_amdgcn_mfma_f32_16x16x32_bf16(Bt[n][k], At[m][k], acc[ai][bj][m][n], 0, 0, 0); __builtin_amdgcn_s_setprio(0); } while (0)
; #define PG8_WAIT_V(n) asm volatile("s_waitcnt vmcnt(" #n ")" ::: "memory")
; template <class Epi, class Sched, bool ALIGN_EPI = false, bool SP2 = false>
; __device__ __forceinline__ void gemm_phase(PG8_LAS unsigned char* lds, const Gemm g, const Sched& S, const Epi& E) {
;     ...
;         const char* nA = has_next ? (const char*)g.A + (size_t)nxt.pm * tstep : cA; const char* nB = has_next ? (const char*)g.Bt + (size_t)nxt.pn * tstep : cB;
;         for (int t = 0; t < nt; t += 2) {
;             const bool last = (t == nt - 2);
;             const char* a1 = cA + (size_t)(t + 1) * kstep;
;             const char* a2 = last ? nA : cA + (size_t)(t + 2) * kstep; const char* b2 = last ? nB : cB + (size_t)(t + 2) * kstep;
;             const char* a3 = a2 + kstep; const char* b3 = b2 + kstep;
;             if (last && has_next) S.a_ready(nxt);
;             if constexpr (SP2) {
;             PG8_LDB(B0, 0, 0); PG8_LDB(B1, 0, 1); PG8_SCHED; PG8_LDA(At, 0, 0); PG8_STAGE(PG8_SA(1, 1), a1 + hstep, voffA);
;             PG8_WAIT_V(8); PG8_WAIT_L(0); PG8_BAR; PG8_MMA(0, 0, At, B0); PG8_MMA(0, 1, At, B1); PG8_BAR; PG8_SCHED;
;             PG8_LDA(At, 0, 1); PG8_STAGE(PG8_SB(0, 0), b2, voffB); PG8_STAGE(PG8_SB(0, 1), b2 + hstep, voffB); PG8_STAGE(PG8_SA(0, 0), a2, voffA);
.LBB0_698:
	s_add_u32 s48, s48, 0x80
	s_addc_u32 s49, s49, 0
	s_add_u32 s59, s52, 0x100
	s_addc_u32 vcc_lo, s53, 0
	s_mov_b32 s52, 0
	s_add_i32 vcc_hi, s52, 2
	s_add_u32 s24, s48, 0x80
	s_addc_u32 s25, s49, 0
	s_add_i32 s66, 0, 0x10000
	s_cmp_eq_u32 s79, s52
	s_cselect_b32 s53, s39, s25
	s_cselect_b32 s52, s38, s24
	v_add_u32_e32 v132, s66, v147
	s_cselect_b32 s25, s43, vcc_lo
	s_cselect_b32 s24, s42, s59
	s_add_i32 s29, 0, 0x14000
	ds_read_b128 v[156:159], v132
	ds_read_b128 v[162:165], v132 offset:1024
	ds_read_b128 v[166:169], v132 offset:2048
	ds_read_b128 v[192:195], v132 offset:3072
	v_add_u32_e32 v132, s29, v147
	ds_read_b128 v[196:199], v132
	ds_read_b128 v[200:203], v132 offset:1024
	ds_read_b128 v[204:207], v132 offset:2048
	ds_read_b128 v[208:211], v132 offset:3072
	v_lshl_add_u64 v[170:171], s[48:49], 0, v[152:153]
	s_add_i32 m0, s90, 0xc000
	ds_read_b128 v[212:215], v160
	ds_read_b128 v[216:219], v160 offset:1024
	ds_read_b128 v[220:223], v160 offset:2048
	ds_read_b128 v[224:227], v160 offset:3072
	ds_read_b128 v[228:231], v160 offset:4096
	ds_read_b128 v[232:235], v160 offset:5120
	ds_read_b128 v[236:239], v160 offset:6144
	ds_read_b128 v[240:243], v160 offset:7168
	global_load_lds_dwordx4 v[170:171], off
	v_lshl_add_u64 v[170:171], s[48:49], 0, v[154:155]
	s_add_i32 m0, s90, 0xe000
	s_nop 0
	global_load_lds_dwordx4 v[170:171], off
	s_waitcnt vmcnt(8)
	s_waitcnt lgkmcnt(0)
	s_barrier
	s_setprio 1
	s_waitcnt lgkmcnt(0)
	v_mfma_f32_16x16x32_bf16 v[124:127], v[156:159], v[212:215], 0
	v_mfma_f32_16x16x32_bf16 v[120:123], v[166:169], v[212:215], 0
	v_mfma_f32_16x16x32_bf16 v[108:111], v[156:159], v[220:223], 0
	v_mfma_f32_16x16x32_bf16 v[104:107], v[166:169], v[220:223], 0
	v_mfma_f32_16x16x32_bf16 v[92:95], v[156:159], v[228:231], 0
	v_mfma_f32_16x16x32_bf16 v[88:91], v[166:169], v[228:231], 0
	v_mfma_f32_16x16x32_bf16 v[76:79], v[156:159], v[236:239], 0
	v_mfma_f32_16x16x32_bf16 v[72:75], v[166:169], v[236:239], 0
	v_mfma_f32_16x16x32_bf16 v[124:127], v[162:165], v[216:219], v[124:127]
	v_mfma_f32_16x16x32_bf16 v[120:123], v[192:195], v[216:219], v[120:123]
	v_mfma_f32_16x16x32_bf16 v[108:111], v[162:165], v[224:227], v[108:111]
	v_mfma_f32_16x16x32_bf16 v[104:107], v[192:195], v[224:227], v[104:107]
	v_mfma_f32_16x16x32_bf16 v[92:95], v[162:165], v[232:235], v[92:95]
	v_mfma_f32_16x16x32_bf16 v[88:91], v[192:195], v[232:235], v[88:91]
	v_mfma_f32_16x16x32_bf16 v[76:79], v[162:165], v[240:243], v[76:79]
	v_mfma_f32_16x16x32_bf16 v[72:75], v[192:195], v[240:243], v[72:75]
	s_setprio 0
	s_setprio 1
	v_mfma_f32_16x16x32_bf16 v[116:119], v[196:199], v[212:215], 0
	v_mfma_f32_16x16x32_bf16 v[112:115], v[204:207], v[212:215], 0
	v_mfma_f32_16x16x32_bf16 v[100:103], v[196:199], v[220:223], 0
	v_mfma_f32_16x16x32_bf16 v[96:99], v[204:207], v[220:223], 0
	v_mfma_f32_16x16x32_bf16 v[84:87], v[196:199], v[228:231], 0
	v_mfma_f32_16x16x32_bf16 v[80:83], v[204:207], v[228:231], 0
	v_mfma_f32_16x16x32_bf16 v[68:71], v[196:199], v[236:239], 0
	v_mfma_f32_16x16x32_bf16 v[64:67], v[204:207], v[236:239], 0
	v_mfma_f32_16x16x32_bf16 v[116:119], v[200:203], v[216:219], v[116:119]
	v_mfma_f32_16x16x32_bf16 v[112:115], v[208:211], v[216:219], v[112:115]
	v_mfma_f32_16x16x32_bf16 v[100:103], v[200:203], v[224:227], v[100:103]
	v_mfma_f32_16x16x32_bf16 v[96:99], v[208:211], v[224:227], v[96:99]
	v_mfma_f32_16x16x32_bf16 v[84:87], v[200:203], v[232:235], v[84:87]
	v_mfma_f32_16x16x32_bf16 v[80:83], v[208:211], v[232:235], v[80:83]
	v_mfma_f32_16x16x32_bf16 v[68:71], v[200:203], v[240:243], v[68:71]
	v_mfma_f32_16x16x32_bf16 v[64:67], v[208:211], v[240:243], v[64:67]
	s_setprio 0
	s_barrier
	s_add_i32 s66, s66, s89
	v_lshl_add_u64 v[170:171], s[24:25], 0, v[130:131]
	s_mov_b32 m0, s66
	ds_read_b128 v[212:215], v160 offset:16384
	ds_read_b128 v[216:219], v160 offset:17408
	ds_read_b128 v[220:223], v160 offset:18432
	ds_read_b128 v[224:227], v160 offset:19456
	ds_read_b128 v[228:231], v160 offset:20480
	ds_read_b128 v[232:235], v160 offset:21504
	ds_read_b128 v[236:239], v160 offset:22528
	ds_read_b128 v[240:243], v160 offset:23552
	global_load_lds_dwordx4 v[170:171], off
	s_add_i32 m0, s66, 0x2000
	v_lshl_add_u64 v[244:245], s[24:25], 0, v[142:143]
	s_add_u32 s24, s24, s10
	s_addc_u32 s25, s25, 0
	s_add_i32 s29, s29, s89
	global_load_lds_dwordx4 v[244:245], off
	v_lshl_add_u64 v[246:247], s[24:25], 0, v[130:131]
	s_mov_b32 m0, s29
	v_lshl_add_u64 v[248:249], s[24:25], 0, v[142:143]
	global_load_lds_dwordx4 v[246:247], off
	s_add_i32 m0, s29, 0x2000
	v_lshl_add_u64 v[250:251], s[52:53], 0, v[128:129]
	global_load_lds_dwordx4 v[248:249], off
	s_mov_b32 m0, s90
	v_lshl_add_u64 v[252:253], s[52:53], 0, v[140:141]
	global_load_lds_dwordx4 v[250:251], off
	s_mov_b32 m0, s91
	s_nop 0
	global_load_lds_dwordx4 v[252:253], off
	s_waitcnt vmcnt(8)
	s_waitcnt lgkmcnt(0)
	s_barrier
; #define PG8_STAGE(bufoff, gbase, voff) do { _Pragma("unroll") for (int _i = 0; _i < 2; ++_i) \
;         __builtin_amdgcn_global_load_lds((const unsigned*)((const char*)(gbase) + (voff)[_i]), (PG8_LAS unsigned*)(lds + (bufoff) + ldsw + _i * 8192), 16, 0, 0); } while (0)
; #define PG8_LDA(dst, b, h) do { _Pragma("unroll") for (int m = 0; m < 4; ++m) _Pragma("unroll") for (int k = 0; k < 2; ++k) dst[m][k] = *(const PG8_LAS bf16x8*)(lds + PG8_SA(b, h) + aoff + m * 2048 + k * 1024); } while (0)
; #define PG8_LDB(dst, b, h) do { _Pragma("unroll") for (int n = 0; n < 2; ++n) _Pragma("unroll") for (int k = 0; k < 2; ++k) dst[n][k] = *(const PG8_LAS bf16x8*)(lds + PG8_SB(b, h) + boff + n * 2048 + k * 1024); } while (0)
; #define PG8_MMA(ai, bj, At, Bt) do { __builtin_amdgcn_s_setprio(1); _Pragma("unroll") for (int m = 0; m < 4; ++m) _Pragma("unroll") for (int n = 0; n < 2; ++n) _Pragma("unroll") for (int k = 0; k < 2; ++k) \
;         acc[ai][bj][m][n] = __builtin_amdgcn_mfma_f32_16x16x32_bf16(Bt[n][k], At[m][k], acc[ai][bj][m][n], 0, 0, 0); __builtin_amdgcn_s_setprio(0); } while (0)
; #define PG8_WAIT_V(n) asm volatile("s_waitcnt vmcnt(" #n ")" ::: "memory")
; #define PG8_WAIT_L(n) asm volatile("s_waitcnt lgkmcnt(" #n ")" ::: "memory")
; #define PG8_BAR __builtin_amdgcn_s_barrier()
; #define PG8_SCHED __builtin_amdgcn_sched_barrier(0)
; template <class Epi, class Sched, bool ALIGN_EPI = false, bool SP2 = false>
; __device__ __forceinline__ void gemm_phase(PG8_LAS unsigned char* lds, const Gemm g, const Sched& S, const Epi& E) {
;     ...
;             PG8_WAIT_V(8); PG8_WAIT_L(0); PG8_BAR; PG8_MMA(1, 0, At, B0); PG8_MMA(1, 1, At, B1); PG8_BAR; PG8_SCHED;
;             PG8_LDB(B0, 1, 0); PG8_LDB(B1, 1, 1); PG8_SCHED; PG8_LDA(At, 1, 0); PG8_STAGE(PG8_SA(0, 1), a2 + hstep, voffA);
;             PG8_WAIT_V(8); PG8_WAIT_L(0); PG8_BAR; PG8_MMA(0, 0, At, B0); PG8_MMA(0, 1, At, B1); PG8_BAR; PG8_SCHED;
	s_setprio 1
	s_waitcnt lgkmcnt(0)
	v_mfma_f32_16x16x32_bf16 v[60:63], v[156:159], v[212:215], 0
	v_mfma_f32_16x16x32_bf16 v[56:59], v[166:169], v[212:215], 0
	v_mfma_f32_16x16x32_bf16 v[44:47], v[156:159], v[220:223], 0
	v_mfma_f32_16x16x32_bf16 v[40:43], v[166:169], v[220:223], 0
	v_mfma_f32_16x16x32_bf16 v[28:31], v[156:159], v[228:231], 0
	v_mfma_f32_16x16x32_bf16 v[24:27], v[166:169], v[228:231], 0
	v_mfma_f32_16x16x32_bf16 v[12:15], v[156:159], v[236:239], 0
	v_mfma_f32_16x16x32_bf16 v[8:11], v[166:169], v[236:239], 0
	v_mfma_f32_16x16x32_bf16 v[60:63], v[162:165], v[216:219], v[60:63]
	v_mfma_f32_16x16x32_bf16 v[56:59], v[192:195], v[216:219], v[56:59]
	v_mfma_f32_16x16x32_bf16 v[44:47], v[162:165], v[224:227], v[44:47]
	v_mfma_f32_16x16x32_bf16 v[40:43], v[192:195], v[224:227], v[40:43]
	v_mfma_f32_16x16x32_bf16 v[28:31], v[162:165], v[232:235], v[28:31]
	v_mfma_f32_16x16x32_bf16 v[24:27], v[192:195], v[232:235], v[24:27]
	v_mfma_f32_16x16x32_bf16 v[12:15], v[162:165], v[240:243], v[12:15]
	v_mfma_f32_16x16x32_bf16 v[8:11], v[192:195], v[240:243], v[8:11]
	s_setprio 0
	s_setprio 1
	v_mfma_f32_16x16x32_bf16 v[52:55], v[196:199], v[212:215], 0
	v_mfma_f32_16x16x32_bf16 v[48:51], v[204:207], v[212:215], 0
	v_mfma_f32_16x16x32_bf16 v[36:39], v[196:199], v[220:223], 0
	v_mfma_f32_16x16x32_bf16 v[32:35], v[204:207], v[220:223], 0
	v_mfma_f32_16x16x32_bf16 v[20:23], v[196:199], v[228:231], 0
	v_mfma_f32_16x16x32_bf16 v[16:19], v[204:207], v[228:231], 0
	v_mfma_f32_16x16x32_bf16 v[4:7], v[196:199], v[236:239], 0
	v_mfma_f32_16x16x32_bf16 v[0:3], v[204:207], v[236:239], 0
	v_mfma_f32_16x16x32_bf16 v[52:55], v[200:203], v[216:219], v[52:55]
	v_mfma_f32_16x16x32_bf16 v[48:51], v[208:211], v[216:219], v[48:51]
	v_mfma_f32_16x16x32_bf16 v[36:39], v[200:203], v[224:227], v[36:39]
	v_mfma_f32_16x16x32_bf16 v[32:35], v[208:211], v[224:227], v[32:35]
	v_mfma_f32_16x16x32_bf16 v[20:23], v[200:203], v[232:235], v[20:23]
	v_mfma_f32_16x16x32_bf16 v[16:19], v[208:211], v[232:235], v[16:19]
	v_mfma_f32_16x16x32_bf16 v[4:7], v[200:203], v[240:243], v[4:7]
	v_mfma_f32_16x16x32_bf16 v[0:3], v[208:211], v[240:243], v[0:3]
	s_setprio 0
	s_barrier
	s_add_i32 s29, 0, 0x18000
	v_add_u32_e32 v132, s29, v147
	s_add_i32 s66, 0, 0x1c000
	ds_read_b128 v[156:159], v132
	ds_read_b128 v[162:165], v132 offset:1024
	ds_read_b128 v[166:169], v132 offset:2048
	ds_read_b128 v[192:195], v132 offset:3072
	v_add_u32_e32 v132, s66, v147
	ds_read_b128 v[196:199], v132
	ds_read_b128 v[200:203], v132 offset:1024
	ds_read_b128 v[204:207], v132 offset:2048
	ds_read_b128 v[208:211], v132 offset:3072
	s_add_u32 s24, s52, s10
	s_addc_u32 s25, s53, 0
	s_mov_b32 m0, s92
	v_lshl_add_u64 v[184:185], s[24:25], 0, v[128:129]
	ds_read_b128 v[212:215], v160 offset:32768
	ds_read_b128 v[216:219], v160 offset:33792
	ds_read_b128 v[220:223], v160 offset:34816
	ds_read_b128 v[224:227], v160 offset:35840
	ds_read_b128 v[228:231], v160 offset:36864
	ds_read_b128 v[232:235], v160 offset:37888
	ds_read_b128 v[236:239], v160 offset:38912
	ds_read_b128 v[240:243], v160 offset:39936
	global_load_lds_dwordx4 v[184:185], off
	v_lshl_add_u64 v[184:185], s[24:25], 0, v[140:141]
	s_mov_b32 m0, s93
	s_nop 0
	global_load_lds_dwordx4 v[184:185], off
	s_waitcnt vmcnt(8)
	s_waitcnt lgkmcnt(0)
	s_barrier
	s_setprio 1
	s_waitcnt lgkmcnt(0)
	v_mfma_f32_16x16x32_bf16 v[124:127], v[156:159], v[212:215], v[124:127]
	v_mfma_f32_16x16x32_bf16 v[120:123], v[166:169], v[212:215], v[120:123]
	v_mfma_f32_16x16x32_bf16 v[108:111], v[156:159], v[220:223], v[108:111]
	v_mfma_f32_16x16x32_bf16 v[104:107], v[166:169], v[220:223], v[104:107]
	v_mfma_f32_16x16x32_bf16 v[92:95], v[156:159], v[228:231], v[92:95]
	v_mfma_f32_16x16x32_bf16 v[88:91], v[166:169], v[228:231], v[88:91]
	v_mfma_f32_16x16x32_bf16 v[76:79], v[156:159], v[236:239], v[76:79]
	v_mfma_f32_16x16x32_bf16 v[72:75], v[166:169], v[236:239], v[72:75]
	v_mfma_f32_16x16x32_bf16 v[124:127], v[162:165], v[216:219], v[124:127]
	v_mfma_f32_16x16x32_bf16 v[120:123], v[192:195], v[216:219], v[120:123]
	v_mfma_f32_16x16x32_bf16 v[108:111], v[162:165], v[224:227], v[108:111]
	v_mfma_f32_16x16x32_bf16 v[104:107], v[192:195], v[224:227], v[104:107]
	v_mfma_f32_16x16x32_bf16 v[92:95], v[162:165], v[232:235], v[92:95]
	v_mfma_f32_16x16x32_bf16 v[88:91], v[192:195], v[232:235], v[88:91]
	v_mfma_f32_16x16x32_bf16 v[76:79], v[162:165], v[240:243], v[76:79]
	v_mfma_f32_16x16x32_bf16 v[72:75], v[192:195], v[240:243], v[72:75]
	s_setprio 0
	s_setprio 1
	v_mfma_f32_16x16x32_bf16 v[116:119], v[196:199], v[212:215], v[116:119]
	v_mfma_f32_16x16x32_bf16 v[112:115], v[204:207], v[212:215], v[112:115]
	v_mfma_f32_16x16x32_bf16 v[100:103], v[196:199], v[220:223], v[100:103]
	v_mfma_f32_16x16x32_bf16 v[96:99], v[204:207], v[220:223], v[96:99]
	v_mfma_f32_16x16x32_bf16 v[84:87], v[196:199], v[228:231], v[84:87]
	v_mfma_f32_16x16x32_bf16 v[80:83], v[204:207], v[228:231], v[80:83]
	v_mfma_f32_16x16x32_bf16 v[68:71], v[196:199], v[236:239], v[68:71]
	v_mfma_f32_16x16x32_bf16 v[64:67], v[204:207], v[236:239], v[64:67]
	v_mfma_f32_16x16x32_bf16 v[116:119], v[200:203], v[216:219], v[116:119]
	v_mfma_f32_16x16x32_bf16 v[112:115], v[208:211], v[216:219], v[112:115]
	v_mfma_f32_16x16x32_bf16 v[100:103], v[200:203], v[224:227], v[100:103]
	v_mfma_f32_16x16x32_bf16 v[96:99], v[208:211], v[224:227], v[96:99]
	v_mfma_f32_16x16x32_bf16 v[84:87], v[200:203], v[232:235], v[84:87]
	v_mfma_f32_16x16x32_bf16 v[80:83], v[208:211], v[232:235], v[80:83]
	v_mfma_f32_16x16x32_bf16 v[68:71], v[200:203], v[240:243], v[68:71]
	v_mfma_f32_16x16x32_bf16 v[64:67], v[208:211], v[240:243], v[64:67]
	s_setprio 0
	s_barrier
; #define PG8_STAGE(bufoff, gbase, voff) do { _Pragma("unroll") for (int _i = 0; _i < 2; ++_i) \
;         __builtin_amdgcn_global_load_lds((const unsigned*)((const char*)(gbase) + (voff)[_i]), (PG8_LAS unsigned*)(lds + (bufoff) + ldsw + _i * 8192), 16, 0, 0); } while (0)
; #define PG8_LDA(dst, b, h) do { _Pragma("unroll") for (int m = 0; m < 4; ++m) _Pragma("unroll") for (int k = 0; k < 2; ++k) dst[m][k] = *(const PG8_LAS bf16x8*)(lds + PG8_SA(b, h) + aoff + m * 2048 + k * 1024); } while (0)
; #define PG8_LDB(dst, b, h) do { _Pragma("unroll") for (int n = 0; n < 2; ++n) _Pragma("unroll") for (int k = 0; k < 2; ++k) dst[n][k] = *(const PG8_LAS bf16x8*)(lds + PG8_SB(b, h) + boff + n * 2048 + k * 1024); } while (0)
; template <class Epi, class Sched, bool ALIGN_EPI = false, bool SP2 = false>
; __device__ __forceinline__ void gemm_phase(PG8_LAS unsigned char* lds, const Gemm g, const Sched& S, const Epi& E) {
;     ...
;         for (int t = 0; t < nt; t += 2) {
;             const bool last = (t == nt - 2);
;             const char* a1 = cA + (size_t)(t + 1) * kstep;
;             const char* a2 = last ? nA : cA + (size_t)(t + 2) * kstep; const char* b2 = last ? nB : cB + (size_t)(t + 2) * kstep;
;             const char* a3 = a2 + kstep; const char* b3 = b2 + kstep;
;             if (last && has_next) S.a_ready(nxt);
;             if constexpr (SP2) {
;             PG8_LDB(B0, 0, 0); PG8_LDB(B1, 0, 1); PG8_SCHED; PG8_LDA(At, 0, 0); PG8_STAGE(PG8_SA(1, 1), a1 + hstep, voffA);
;             PG8_WAIT_V(8); PG8_WAIT_L(0); PG8_BAR; PG8_MMA(0, 0, At, B0); PG8_MMA(0, 1, At, B1); PG8_BAR; PG8_SCHED;
;             PG8_LDA(At, 0, 1); PG8_STAGE(PG8_SB(0, 0), b2, voffB); PG8_STAGE(PG8_SB(0, 1), b2 + hstep, voffB); PG8_STAGE(PG8_SA(0, 0), a2, voffA);
;             PG8_WAIT_V(8); PG8_WAIT_L(0); PG8_BAR; PG8_MMA(1, 0, At, B0); PG8_MMA(1, 1, At, B1); PG8_BAR; PG8_SCHED;
;             PG8_LDB(B0, 1, 0); PG8_LDB(B1, 1, 1); PG8_SCHED; PG8_LDA(At, 1, 0); PG8_STAGE(PG8_SA(0, 1), a2 + hstep, voffA);
;             PG8_WAIT_V(8); PG8_WAIT_L(0); PG8_BAR; PG8_MMA(0, 0, At, B0); PG8_MMA(0, 1, At, B1); PG8_BAR; PG8_SCHED;
;             PG8_LDA(At, 1, 1); PG8_STAGE(PG8_SB(1, 0), b3, voffB); PG8_STAGE(PG8_SB(1, 1), b3 + hstep, voffB); PG8_STAGE(PG8_SA(1, 0), a3, voffA);
;             PG8_WAIT_V(8); PG8_WAIT_L(0); PG8_BAR; PG8_MMA(1, 0, At, B0); PG8_MMA(1, 1, At, B1); PG8_BAR; PG8_SCHED;
	s_add_i32 s24, s29, s89
	v_lshl_add_u64 v[170:171], v[170:171], 0, s[14:15]
	s_mov_b32 m0, s24
	ds_read_b128 v[212:215], v160 offset:49152
	ds_read_b128 v[216:219], v160 offset:50176
	ds_read_b128 v[220:223], v160 offset:51200
	ds_read_b128 v[224:227], v160 offset:52224
	ds_read_b128 v[228:231], v160 offset:53248
	ds_read_b128 v[232:235], v160 offset:54272
	ds_read_b128 v[236:239], v160 offset:55296
	ds_read_b128 v[240:243], v160 offset:56320
	global_load_lds_dwordx4 v[170:171], off
	v_lshl_add_u64 v[170:171], v[244:245], 0, s[14:15]
	s_add_i32 m0, s24, 0x2000
	s_add_i32 s24, s66, s89
	global_load_lds_dwordx4 v[170:171], off
	v_lshl_add_u64 v[170:171], v[246:247], 0, s[14:15]
	s_mov_b32 m0, s24
	s_nop 0
	global_load_lds_dwordx4 v[170:171], off
	v_lshl_add_u64 v[170:171], v[248:249], 0, s[14:15]
	s_add_i32 m0, s24, 0x2000
	s_nop 0
	global_load_lds_dwordx4 v[170:171], off
	v_lshl_add_u64 v[170:171], v[250:251], 0, s[14:15]
	s_mov_b32 m0, s96
	s_nop 0
	global_load_lds_dwordx4 v[170:171], off
	v_lshl_add_u64 v[170:171], v[252:253], 0, s[14:15]
	s_mov_b32 m0, s97
	s_nop 0
	global_load_lds_dwordx4 v[170:171], off
	s_waitcnt vmcnt(8)
	s_waitcnt lgkmcnt(0)
	s_barrier
	s_setprio 1
	s_waitcnt lgkmcnt(0)
	v_mfma_f32_16x16x32_bf16 v[60:63], v[156:159], v[212:215], v[60:63]
	v_mfma_f32_16x16x32_bf16 v[56:59], v[166:169], v[212:215], v[56:59]
	v_mfma_f32_16x16x32_bf16 v[44:47], v[156:159], v[220:223], v[44:47]
	v_mfma_f32_16x16x32_bf16 v[40:43], v[166:169], v[220:223], v[40:43]
	v_mfma_f32_16x16x32_bf16 v[28:31], v[156:159], v[228:231], v[28:31]
	v_mfma_f32_16x16x32_bf16 v[24:27], v[166:169], v[228:231], v[24:27]
	v_mfma_f32_16x16x32_bf16 v[12:15], v[156:159], v[236:239], v[12:15]
	v_mfma_f32_16x16x32_bf16 v[8:11], v[166:169], v[236:239], v[8:11]
	v_mfma_f32_16x16x32_bf16 v[60:63], v[162:165], v[216:219], v[60:63]
	v_mfma_f32_16x16x32_bf16 v[56:59], v[192:195], v[216:219], v[56:59]
	v_mfma_f32_16x16x32_bf16 v[44:47], v[162:165], v[224:227], v[44:47]
	v_mfma_f32_16x16x32_bf16 v[40:43], v[192:195], v[224:227], v[40:43]
	v_mfma_f32_16x16x32_bf16 v[28:31], v[162:165], v[232:235], v[28:31]
	v_mfma_f32_16x16x32_bf16 v[24:27], v[192:195], v[232:235], v[24:27]
	v_mfma_f32_16x16x32_bf16 v[12:15], v[162:165], v[240:243], v[12:15]
	v_mfma_f32_16x16x32_bf16 v[8:11], v[192:195], v[240:243], v[8:11]
	s_setprio 0
	s_setprio 1
	v_mfma_f32_16x16x32_bf16 v[52:55], v[196:199], v[212:215], v[52:55]
	v_mfma_f32_16x16x32_bf16 v[48:51], v[204:207], v[212:215], v[48:51]
	v_mfma_f32_16x16x32_bf16 v[36:39], v[196:199], v[220:223], v[36:39]
	v_mfma_f32_16x16x32_bf16 v[32:35], v[204:207], v[220:223], v[32:35]
	v_mfma_f32_16x16x32_bf16 v[20:23], v[196:199], v[228:231], v[20:23]
	v_mfma_f32_16x16x32_bf16 v[16:19], v[204:207], v[228:231], v[16:19]
	v_mfma_f32_16x16x32_bf16 v[4:7], v[196:199], v[236:239], v[4:7]
	v_mfma_f32_16x16x32_bf16 v[0:3], v[204:207], v[236:239], v[0:3]
	v_mfma_f32_16x16x32_bf16 v[52:55], v[200:203], v[216:219], v[52:55]
	v_mfma_f32_16x16x32_bf16 v[48:51], v[208:211], v[216:219], v[48:51]
	v_mfma_f32_16x16x32_bf16 v[36:39], v[200:203], v[224:227], v[36:39]
	v_mfma_f32_16x16x32_bf16 v[32:35], v[208:211], v[224:227], v[32:35]
	v_mfma_f32_16x16x32_bf16 v[20:23], v[200:203], v[232:235], v[20:23]
	v_mfma_f32_16x16x32_bf16 v[16:19], v[208:211], v[232:235], v[16:19]
	v_mfma_f32_16x16x32_bf16 v[4:7], v[200:203], v[240:243], v[4:7]
	v_mfma_f32_16x16x32_bf16 v[0:3], v[208:211], v[240:243], v[0:3]
	s_setprio 0
	s_add_u32 s48, s48, 0x100
	s_addc_u32 s49, s49, 0
	s_add_u32 s59, s59, 0x100
	s_addc_u32 vcc_lo, vcc_lo, 0
	s_cmp_ge_u32 vcc_hi, s78
	s_mov_b32 s52, vcc_hi
	s_barrier
.LBB0_699:
	s_add_i32 vcc_hi, s52, 2
	s_add_u32 s24, s48, 0x80
	s_addc_u32 s25, s49, 0
	s_add_i32 s66, 0, 0x10000
	s_cmp_eq_u32 s79, s52
	s_cselect_b32 s53, s39, s25
	s_cselect_b32 s52, s38, s24
	v_add_u32_e32 v132, s66, v147
	s_cselect_b32 s25, s43, vcc_lo
	s_cselect_b32 s24, s42, s59
	s_add_i32 s29, 0, 0x14000
	ds_read_b128 v[156:159], v132
	ds_read_b128 v[162:165], v132 offset:1024
	ds_read_b128 v[166:169], v132 offset:2048
	ds_read_b128 v[192:195], v132 offset:3072
	v_add_u32_e32 v132, s29, v147
	ds_read_b128 v[196:199], v132
	ds_read_b128 v[200:203], v132 offset:1024
	ds_read_b128 v[204:207], v132 offset:2048
	ds_read_b128 v[208:211], v132 offset:3072
	v_lshl_add_u64 v[170:171], s[48:49], 0, v[152:153]
	s_add_i32 m0, s90, 0xc000
	ds_read_b128 v[212:215], v160
	ds_read_b128 v[216:219], v160 offset:1024
	ds_read_b128 v[220:223], v160 offset:2048
	ds_read_b128 v[224:227], v160 offset:3072
	ds_read_b128 v[228:231], v160 offset:4096
	ds_read_b128 v[232:235], v160 offset:5120
	ds_read_b128 v[236:239], v160 offset:6144
	ds_read_b128 v[240:243], v160 offset:7168
	global_load_lds_dwordx4 v[170:171], off
	v_lshl_add_u64 v[170:171], s[48:49], 0, v[154:155]
	s_add_i32 m0, s90, 0xe000
	s_nop 0
	global_load_lds_dwordx4 v[170:171], off
	s_waitcnt vmcnt(8)
	s_waitcnt lgkmcnt(0)
	s_barrier
; #define PG8_STAGE(bufoff, gbase, voff) do { _Pragma("unroll") for (int _i = 0; _i < 2; ++_i) \
;         __builtin_amdgcn_global_load_lds((const unsigned*)((const char*)(gbase) + (voff)[_i]), (PG8_LAS unsigned*)(lds + (bufoff) + ldsw + _i * 8192), 16, 0, 0); } while (0)
; #define PG8_LDA(dst, b, h) do { _Pragma("unroll") for (int m = 0; m < 4; ++m) _Pragma("unroll") for (int k = 0; k < 2; ++k) dst[m][k] = *(const PG8_LAS bf16x8*)(lds + PG8_SA(b, h) + aoff + m * 2048 + k * 1024); } while (0)
; #define PG8_MMA(ai, bj, At, Bt) do { __builtin_amdgcn_s_setprio(1); _Pragma("unroll") for (int m = 0; m < 4; ++m) _Pragma("unroll") for (int n = 0; n < 2; ++n) _Pragma("unroll") for (int k = 0; k < 2; ++k) \
;         acc[ai][bj][m][n] = __builtin_amdgcn_mfma_f32_16x16x32_bf16(Bt[n][k], At[m][k], acc[ai][bj][m][n], 0, 0, 0); __builtin_amdgcn_s_setprio(0); } while (0)
; #define PG8_WAIT_V(n) asm volatile("s_waitcnt vmcnt(" #n ")" ::: "memory")
; #define PG8_WAIT_L(n) asm volatile("s_waitcnt lgkmcnt(" #n ")" ::: "memory")
; #define PG8_BAR __builtin_amdgcn_s_barrier()
; #define PG8_SCHED __builtin_amdgcn_sched_barrier(0)
; template <class Epi, class Sched, bool ALIGN_EPI = false, bool SP2 = false>
; __device__ __forceinline__ void gemm_phase(PG8_LAS unsigned char* lds, const Gemm g, const Sched& S, const Epi& E) {
;     ...
;             PG8_WAIT_V(8); PG8_WAIT_L(0); PG8_BAR; PG8_MMA(0, 0, At, B0); PG8_MMA(0, 1, At, B1); PG8_BAR; PG8_SCHED;
;             PG8_LDA(At, 0, 1); PG8_STAGE(PG8_SB(0, 0), b2, voffB); PG8_STAGE(PG8_SB(0, 1), b2 + hstep, voffB); PG8_STAGE(PG8_SA(0, 0), a2, voffA);
;             PG8_WAIT_V(8); PG8_WAIT_L(0); PG8_BAR; PG8_MMA(1, 0, At, B0); PG8_MMA(1, 1, At, B1); PG8_BAR; PG8_SCHED;
	s_setprio 1
	s_waitcnt lgkmcnt(0)
	v_mfma_f32_16x16x32_bf16 v[124:127], v[156:159], v[212:215], v[124:127]
	v_mfma_f32_16x16x32_bf16 v[120:123], v[166:169], v[212:215], v[120:123]
	v_mfma_f32_16x16x32_bf16 v[108:111], v[156:159], v[220:223], v[108:111]
	v_mfma_f32_16x16x32_bf16 v[104:107], v[166:169], v[220:223], v[104:107]
	v_mfma_f32_16x16x32_bf16 v[92:95], v[156:159], v[228:231], v[92:95]
	v_mfma_f32_16x16x32_bf16 v[88:91], v[166:169], v[228:231], v[88:91]
	v_mfma_f32_16x16x32_bf16 v[76:79], v[156:159], v[236:239], v[76:79]
	v_mfma_f32_16x16x32_bf16 v[72:75], v[166:169], v[236:239], v[72:75]
	v_mfma_f32_16x16x32_bf16 v[124:127], v[162:165], v[216:219], v[124:127]
	v_mfma_f32_16x16x32_bf16 v[120:123], v[192:195], v[216:219], v[120:123]
	v_mfma_f32_16x16x32_bf16 v[108:111], v[162:165], v[224:227], v[108:111]
	v_mfma_f32_16x16x32_bf16 v[104:107], v[192:195], v[224:227], v[104:107]
	v_mfma_f32_16x16x32_bf16 v[92:95], v[162:165], v[232:235], v[92:95]
	v_mfma_f32_16x16x32_bf16 v[88:91], v[192:195], v[232:235], v[88:91]
	v_mfma_f32_16x16x32_bf16 v[76:79], v[162:165], v[240:243], v[76:79]
	v_mfma_f32_16x16x32_bf16 v[72:75], v[192:195], v[240:243], v[72:75]
	s_setprio 0
	s_setprio 1
	v_mfma_f32_16x16x32_bf16 v[116:119], v[196:199], v[212:215], v[116:119]
	v_mfma_f32_16x16x32_bf16 v[112:115], v[204:207], v[212:215], v[112:115]
	v_mfma_f32_16x16x32_bf16 v[100:103], v[196:199], v[220:223], v[100:103]
	v_mfma_f32_16x16x32_bf16 v[96:99], v[204:207], v[220:223], v[96:99]
	v_mfma_f32_16x16x32_bf16 v[84:87], v[196:199], v[228:231], v[84:87]
	v_mfma_f32_16x16x32_bf16 v[80:83], v[204:207], v[228:231], v[80:83]
	v_mfma_f32_16x16x32_bf16 v[68:71], v[196:199], v[236:239], v[68:71]
	v_mfma_f32_16x16x32_bf16 v[64:67], v[204:207], v[236:239], v[64:67]
	v_mfma_f32_16x16x32_bf16 v[116:119], v[200:203], v[216:219], v[116:119]
	v_mfma_f32_16x16x32_bf16 v[112:115], v[208:211], v[216:219], v[112:115]
	v_mfma_f32_16x16x32_bf16 v[100:103], v[200:203], v[224:227], v[100:103]
	v_mfma_f32_16x16x32_bf16 v[96:99], v[208:211], v[224:227], v[96:99]
	v_mfma_f32_16x16x32_bf16 v[84:87], v[200:203], v[232:235], v[84:87]
	v_mfma_f32_16x16x32_bf16 v[80:83], v[208:211], v[232:235], v[80:83]
	v_mfma_f32_16x16x32_bf16 v[68:71], v[200:203], v[240:243], v[68:71]
	v_mfma_f32_16x16x32_bf16 v[64:67], v[208:211], v[240:243], v[64:67]
	s_setprio 0
	s_barrier
	s_add_i32 s66, s66, s89
	v_lshl_add_u64 v[170:171], s[24:25], 0, v[130:131]
	s_mov_b32 m0, s66
	ds_read_b128 v[212:215], v160 offset:16384
	ds_read_b128 v[216:219], v160 offset:17408
	ds_read_b128 v[220:223], v160 offset:18432
	ds_read_b128 v[224:227], v160 offset:19456
	ds_read_b128 v[228:231], v160 offset:20480
	ds_read_b128 v[232:235], v160 offset:21504
	ds_read_b128 v[236:239], v160 offset:22528
	ds_read_b128 v[240:243], v160 offset:23552
	global_load_lds_dwordx4 v[170:171], off
	s_add_i32 m0, s66, 0x2000
	v_lshl_add_u64 v[244:245], s[24:25], 0, v[142:143]
	s_add_u32 s24, s24, s10
	s_addc_u32 s25, s25, 0
	s_add_i32 s29, s29, s89
	global_load_lds_dwordx4 v[244:245], off
	v_lshl_add_u64 v[246:247], s[24:25], 0, v[130:131]
	s_mov_b32 m0, s29
	v_lshl_add_u64 v[248:249], s[24:25], 0, v[142:143]
	global_load_lds_dwordx4 v[246:247], off
	s_add_i32 m0, s29, 0x2000
	v_lshl_add_u64 v[250:251], s[52:53], 0, v[128:129]
	global_load_lds_dwordx4 v[248:249], off
	s_mov_b32 m0, s90
	v_lshl_add_u64 v[252:253], s[52:53], 0, v[140:141]
	global_load_lds_dwordx4 v[250:251], off
	s_mov_b32 m0, s91
	s_nop 0
	global_load_lds_dwordx4 v[252:253], off
	s_waitcnt vmcnt(8)
	s_waitcnt lgkmcnt(0)
	s_barrier
	s_setprio 1
	s_waitcnt lgkmcnt(0)
	v_mfma_f32_16x16x32_bf16 v[60:63], v[156:159], v[212:215], v[60:63]
	v_mfma_f32_16x16x32_bf16 v[56:59], v[166:169], v[212:215], v[56:59]
	v_mfma_f32_16x16x32_bf16 v[44:47], v[156:159], v[220:223], v[44:47]
	v_mfma_f32_16x16x32_bf16 v[40:43], v[166:169], v[220:223], v[40:43]
	v_mfma_f32_16x16x32_bf16 v[28:31], v[156:159], v[228:231], v[28:31]
	v_mfma_f32_16x16x32_bf16 v[24:27], v[166:169], v[228:231], v[24:27]
	v_mfma_f32_16x16x32_bf16 v[12:15], v[156:159], v[236:239], v[12:15]
	v_mfma_f32_16x16x32_bf16 v[8:11], v[166:169], v[236:239], v[8:11]
	v_mfma_f32_16x16x32_bf16 v[60:63], v[162:165], v[216:219], v[60:63]
	v_mfma_f32_16x16x32_bf16 v[56:59], v[192:195], v[216:219], v[56:59]
	v_mfma_f32_16x16x32_bf16 v[44:47], v[162:165], v[224:227], v[44:47]
	v_mfma_f32_16x16x32_bf16 v[40:43], v[192:195], v[224:227], v[40:43]
	v_mfma_f32_16x16x32_bf16 v[28:31], v[162:165], v[232:235], v[28:31]
	v_mfma_f32_16x16x32_bf16 v[24:27], v[192:195], v[232:235], v[24:27]
	v_mfma_f32_16x16x32_bf16 v[12:15], v[162:165], v[240:243], v[12:15]
	v_mfma_f32_16x16x32_bf16 v[8:11], v[192:195], v[240:243], v[8:11]
	s_setprio 0
	s_setprio 1
	v_mfma_f32_16x16x32_bf16 v[52:55], v[196:199], v[212:215], v[52:55]
	v_mfma_f32_16x16x32_bf16 v[48:51], v[204:207], v[212:215], v[48:51]
	v_mfma_f32_16x16x32_bf16 v[36:39], v[196:199], v[220:223], v[36:39]
	v_mfma_f32_16x16x32_bf16 v[32:35], v[204:207], v[220:223], v[32:35]
	v_mfma_f32_16x16x32_bf16 v[20:23], v[196:199], v[228:231], v[20:23]
	v_mfma_f32_16x16x32_bf16 v[16:19], v[204:207], v[228:231], v[16:19]
	v_mfma_f32_16x16x32_bf16 v[4:7], v[196:199], v[236:239], v[4:7]
	v_mfma_f32_16x16x32_bf16 v[0:3], v[204:207], v[236:239], v[0:3]
	v_mfma_f32_16x16x32_bf16 v[52:55], v[200:203], v[216:219], v[52:55]
	v_mfma_f32_16x16x32_bf16 v[48:51], v[208:211], v[216:219], v[48:51]
	v_mfma_f32_16x16x32_bf16 v[36:39], v[200:203], v[224:227], v[36:39]
	v_mfma_f32_16x16x32_bf16 v[32:35], v[208:211], v[224:227], v[32:35]
	v_mfma_f32_16x16x32_bf16 v[20:23], v[200:203], v[232:235], v[20:23]
	v_mfma_f32_16x16x32_bf16 v[16:19], v[208:211], v[232:235], v[16:19]
	v_mfma_f32_16x16x32_bf16 v[4:7], v[200:203], v[240:243], v[4:7]
	v_mfma_f32_16x16x32_bf16 v[0:3], v[208:211], v[240:243], v[0:3]
	s_setprio 0
	s_barrier
; #define PG8_STAGE(bufoff, gbase, voff) do { _Pragma("unroll") for (int _i = 0; _i < 2; ++_i) \
;         __builtin_amdgcn_global_load_lds((const unsigned*)((const char*)(gbase) + (voff)[_i]), (PG8_LAS unsigned*)(lds + (bufoff) + ldsw + _i * 8192), 16, 0, 0); } while (0)
; #define PG8_LDA(dst, b, h) do { _Pragma("unroll") for (int m = 0; m < 4; ++m) _Pragma("unroll") for (int k = 0; k < 2; ++k) dst[m][k] = *(const PG8_LAS bf16x8*)(lds + PG8_SA(b, h) + aoff + m * 2048 + k * 1024); } while (0)
; #define PG8_LDB(dst, b, h) do { _Pragma("unroll") for (int n = 0; n < 2; ++n) _Pragma("unroll") for (int k = 0; k < 2; ++k) dst[n][k] = *(const PG8_LAS bf16x8*)(lds + PG8_SB(b, h) + boff + n * 2048 + k * 1024); } while (0)
; #define PG8_MMA(ai, bj, At, Bt) do { __builtin_amdgcn_s_setprio(1); _Pragma("unroll") for (int m = 0; m < 4; ++m) _Pragma("unroll") for (int n = 0; n < 2; ++n) _Pragma("unroll") for (int k = 0; k < 2; ++k) \
;         acc[ai][bj][m][n] = __builtin_amdgcn_mfma_f32_16x16x32_bf16(Bt[n][k], At[m][k], acc[ai][bj][m][n], 0, 0, 0); __builtin_amdgcn_s_setprio(0); } while (0)
; #define PG8_WAIT_V(n) asm volatile("s_waitcnt vmcnt(" #n ")" ::: "memory")
; #define PG8_WAIT_L(n) asm volatile("s_waitcnt lgkmcnt(" #n ")" ::: "memory")
; #define PG8_BAR __builtin_amdgcn_s_barrier()
; #define PG8_SCHED __builtin_amdgcn_sched_barrier(0)
; template <class Epi, class Sched, bool ALIGN_EPI = false, bool SP2 = false>
; __device__ __forceinline__ void gemm_phase(PG8_LAS unsigned char* lds, const Gemm g, const Sched& S, const Epi& E) {
;     ...
;             PG8_LDB(B0, 1, 0); PG8_LDB(B1, 1, 1); PG8_SCHED; PG8_LDA(At, 1, 0); PG8_STAGE(PG8_SA(0, 1), a2 + hstep, voffA);
;             PG8_WAIT_V(8); PG8_WAIT_L(0); PG8_BAR; PG8_MMA(0, 0, At, B0); PG8_MMA(0, 1, At, B1); PG8_BAR; PG8_SCHED;
	s_add_i32 s29, 0, 0x18000
	v_add_u32_e32 v132, s29, v147
	s_add_i32 s66, 0, 0x1c000
	ds_read_b128 v[156:159], v132
	ds_read_b128 v[162:165], v132 offset:1024
	ds_read_b128 v[166:169], v132 offset:2048
	ds_read_b128 v[192:195], v132 offset:3072
	v_add_u32_e32 v132, s66, v147
	ds_read_b128 v[196:199], v132
	ds_read_b128 v[200:203], v132 offset:1024
	ds_read_b128 v[204:207], v132 offset:2048
	ds_read_b128 v[208:211], v132 offset:3072
	s_add_u32 s24, s52, s10
	s_addc_u32 s25, s53, 0
	s_mov_b32 m0, s92
	v_lshl_add_u64 v[184:185], s[24:25], 0, v[128:129]
	ds_read_b128 v[212:215], v160 offset:32768
	ds_read_b128 v[216:219], v160 offset:33792
	ds_read_b128 v[220:223], v160 offset:34816
	ds_read_b128 v[224:227], v160 offset:35840
	ds_read_b128 v[228:231], v160 offset:36864
	ds_read_b128 v[232:235], v160 offset:37888
	ds_read_b128 v[236:239], v160 offset:38912
	ds_read_b128 v[240:243], v160 offset:39936
	global_load_lds_dwordx4 v[184:185], off
	v_lshl_add_u64 v[184:185], s[24:25], 0, v[140:141]
	s_mov_b32 m0, s93
	s_nop 0
	global_load_lds_dwordx4 v[184:185], off
	s_waitcnt vmcnt(8)
	s_waitcnt lgkmcnt(0)
	s_barrier
	s_setprio 1
	s_waitcnt lgkmcnt(0)
	v_mfma_f32_16x16x32_bf16 v[124:127], v[156:159], v[212:215], v[124:127]
	v_mfma_f32_16x16x32_bf16 v[120:123], v[166:169], v[212:215], v[120:123]
	v_mfma_f32_16x16x32_bf16 v[108:111], v[156:159], v[220:223], v[108:111]
	v_mfma_f32_16x16x32_bf16 v[104:107], v[166:169], v[220:223], v[104:107]
	v_mfma_f32_16x16x32_bf16 v[92:95], v[156:159], v[228:231], v[92:95]
	v_mfma_f32_16x16x32_bf16 v[88:91], v[166:169], v[228:231], v[88:91]
	v_mfma_f32_16x16x32_bf16 v[76:79], v[156:159], v[236:239], v[76:79]
	v_mfma_f32_16x16x32_bf16 v[72:75], v[166:169], v[236:239], v[72:75]
	v_mfma_f32_16x16x32_bf16 v[124:127], v[162:165], v[216:219], v[124:127]
	v_mfma_f32_16x16x32_bf16 v[120:123], v[192:195], v[216:219], v[120:123]
	v_mfma_f32_16x16x32_bf16 v[108:111], v[162:165], v[224:227], v[108:111]
	v_mfma_f32_16x16x32_bf16 v[104:107], v[192:195], v[224:227], v[104:107]
	v_mfma_f32_16x16x32_bf16 v[92:95], v[162:165], v[232:235], v[92:95]
	v_mfma_f32_16x16x32_bf16 v[88:91], v[192:195], v[232:235], v[88:91]
	v_mfma_f32_16x16x32_bf16 v[76:79], v[162:165], v[240:243], v[76:79]
	v_mfma_f32_16x16x32_bf16 v[72:75], v[192:195], v[240:243], v[72:75]
	s_setprio 0
	s_setprio 1
	v_mfma_f32_16x16x32_bf16 v[116:119], v[196:199], v[212:215], v[116:119]
	v_mfma_f32_16x16x32_bf16 v[112:115], v[204:207], v[212:215], v[112:115]
	v_mfma_f32_16x16x32_bf16 v[100:103], v[196:199], v[220:223], v[100:103]
	v_mfma_f32_16x16x32_bf16 v[96:99], v[204:207], v[220:223], v[96:99]
	v_mfma_f32_16x16x32_bf16 v[84:87], v[196:199], v[228:231], v[84:87]
	v_mfma_f32_16x16x32_bf16 v[80:83], v[204:207], v[228:231], v[80:83]
	v_mfma_f32_16x16x32_bf16 v[68:71], v[196:199], v[236:239], v[68:71]
	v_mfma_f32_16x16x32_bf16 v[64:67], v[204:207], v[236:239], v[64:67]
	v_mfma_f32_16x16x32_bf16 v[116:119], v[200:203], v[216:219], v[116:119]
	v_mfma_f32_16x16x32_bf16 v[112:115], v[208:211], v[216:219], v[112:115]
	v_mfma_f32_16x16x32_bf16 v[100:103], v[200:203], v[224:227], v[100:103]
	v_mfma_f32_16x16x32_bf16 v[96:99], v[208:211], v[224:227], v[96:99]
	v_mfma_f32_16x16x32_bf16 v[84:87], v[200:203], v[232:235], v[84:87]
	v_mfma_f32_16x16x32_bf16 v[80:83], v[208:211], v[232:235], v[80:83]
	v_mfma_f32_16x16x32_bf16 v[68:71], v[200:203], v[240:243], v[68:71]
	v_mfma_f32_16x16x32_bf16 v[64:67], v[208:211], v[240:243], v[64:67]
	s_setprio 0
	s_barrier
; #define PG8_STAGE(bufoff, gbase, voff) do { _Pragma("unroll") for (int _i = 0; _i < 2; ++_i) \
;         __builtin_amdgcn_global_load_lds((const unsigned*)((const char*)(gbase) + (voff)[_i]), (PG8_LAS unsigned*)(lds + (bufoff) + ldsw + _i * 8192), 16, 0, 0); } while (0)
; #define PG8_LDA(dst, b, h) do { _Pragma("unroll") for (int m = 0; m < 4; ++m) _Pragma("unroll") for (int k = 0; k < 2; ++k) dst[m][k] = *(const PG8_LAS bf16x8*)(lds + PG8_SA(b, h) + aoff + m * 2048 + k * 1024); } while (0)
; #define PG8_MMA(ai, bj, At, Bt) do { __builtin_amdgcn_s_setprio(1); _Pragma("unroll") for (int m = 0; m < 4; ++m) _Pragma("unroll") for (int n = 0; n < 2; ++n) _Pragma("unroll") for (int k = 0; k < 2; ++k) \
;         acc[ai][bj][m][n] = __builtin_amdgcn_mfma_f32_16x16x32_bf16(Bt[n][k], At[m][k], acc[ai][bj][m][n], 0, 0, 0); __builtin_amdgcn_s_setprio(0); } while (0)
; #define PG8_WAIT_V(n) asm volatile("s_waitcnt vmcnt(" #n ")" ::: "memory")
; #define PG8_WAIT_L(n) asm volatile("s_waitcnt lgkmcnt(" #n ")" ::: "memory")
; #define PG8_BAR __builtin_amdgcn_s_barrier()
; #define PG8_SCHED __builtin_amdgcn_sched_barrier(0)
; template <class Epi, class Sched, bool ALIGN_EPI = false, bool SP2 = false>
; __device__ __forceinline__ void gemm_phase(PG8_LAS unsigned char* lds, const Gemm g, const Sched& S, const Epi& E) {
;     ...
;         for (int t = 0; t < nt; t += 2) {
;             const bool last = (t == nt - 2);
;     ...
;             PG8_LDA(At, 1, 1); PG8_STAGE(PG8_SB(1, 0), b3, voffB); PG8_STAGE(PG8_SB(1, 1), b3 + hstep, voffB); PG8_STAGE(PG8_SA(1, 0), a3, voffA);
;             PG8_WAIT_V(8); PG8_WAIT_L(0); PG8_BAR; PG8_MMA(1, 0, At, B0); PG8_MMA(1, 1, At, B1); PG8_BAR; PG8_SCHED;
	s_add_i32 s24, s29, s89
	v_lshl_add_u64 v[170:171], v[170:171], 0, s[14:15]
	s_mov_b32 m0, s24
	ds_read_b128 v[212:215], v160 offset:49152
	ds_read_b128 v[216:219], v160 offset:50176
	ds_read_b128 v[220:223], v160 offset:51200
	ds_read_b128 v[224:227], v160 offset:52224
	ds_read_b128 v[228:231], v160 offset:53248
	ds_read_b128 v[232:235], v160 offset:54272
	ds_read_b128 v[236:239], v160 offset:55296
	ds_read_b128 v[240:243], v160 offset:56320
	global_load_lds_dwordx4 v[170:171], off
	v_lshl_add_u64 v[170:171], v[244:245], 0, s[14:15]
	s_add_i32 m0, s24, 0x2000
	s_add_i32 s24, s66, s89
	global_load_lds_dwordx4 v[170:171], off
	v_lshl_add_u64 v[170:171], v[246:247], 0, s[14:15]
	s_mov_b32 m0, s24
	s_nop 0
	global_load_lds_dwordx4 v[170:171], off
	v_lshl_add_u64 v[170:171], v[248:249], 0, s[14:15]
	s_add_i32 m0, s24, 0x2000
	s_nop 0
	global_load_lds_dwordx4 v[170:171], off
	v_lshl_add_u64 v[170:171], v[250:251], 0, s[14:15]
	s_mov_b32 m0, s96
	s_nop 0
	global_load_lds_dwordx4 v[170:171], off
	v_lshl_add_u64 v[170:171], v[252:253], 0, s[14:15]
	s_mov_b32 m0, s97
	s_nop 0
	global_load_lds_dwordx4 v[170:171], off
	s_waitcnt vmcnt(8)
	s_waitcnt lgkmcnt(0)
	s_barrier
	s_setprio 1
	s_waitcnt lgkmcnt(0)
	v_mfma_f32_16x16x32_bf16 v[60:63], v[156:159], v[212:215], v[60:63]
	v_mfma_f32_16x16x32_bf16 v[56:59], v[166:169], v[212:215], v[56:59]
	v_mfma_f32_16x16x32_bf16 v[44:47], v[156:159], v[220:223], v[44:47]
	v_mfma_f32_16x16x32_bf16 v[40:43], v[166:169], v[220:223], v[40:43]
	v_mfma_f32_16x16x32_bf16 v[28:31], v[156:159], v[228:231], v[28:31]
	v_mfma_f32_16x16x32_bf16 v[24:27], v[166:169], v[228:231], v[24:27]
	v_mfma_f32_16x16x32_bf16 v[12:15], v[156:159], v[236:239], v[12:15]
	v_mfma_f32_16x16x32_bf16 v[8:11], v[166:169], v[236:239], v[8:11]
	v_mfma_f32_16x16x32_bf16 v[60:63], v[162:165], v[216:219], v[60:63]
	v_mfma_f32_16x16x32_bf16 v[56:59], v[192:195], v[216:219], v[56:59]
	v_mfma_f32_16x16x32_bf16 v[44:47], v[162:165], v[224:227], v[44:47]
	v_mfma_f32_16x16x32_bf16 v[40:43], v[192:195], v[224:227], v[40:43]
	v_mfma_f32_16x16x32_bf16 v[28:31], v[162:165], v[232:235], v[28:31]
	v_mfma_f32_16x16x32_bf16 v[24:27], v[192:195], v[232:235], v[24:27]
	v_mfma_f32_16x16x32_bf16 v[12:15], v[162:165], v[240:243], v[12:15]
	v_mfma_f32_16x16x32_bf16 v[8:11], v[192:195], v[240:243], v[8:11]
	s_setprio 0
	s_setprio 1
	v_mfma_f32_16x16x32_bf16 v[52:55], v[196:199], v[212:215], v[52:55]
	v_mfma_f32_16x16x32_bf16 v[48:51], v[204:207], v[212:215], v[48:51]
	v_mfma_f32_16x16x32_bf16 v[36:39], v[196:199], v[220:223], v[36:39]
	v_mfma_f32_16x16x32_bf16 v[32:35], v[204:207], v[220:223], v[32:35]
	v_mfma_f32_16x16x32_bf16 v[20:23], v[196:199], v[228:231], v[20:23]
	v_mfma_f32_16x16x32_bf16 v[16:19], v[204:207], v[228:231], v[16:19]
	v_mfma_f32_16x16x32_bf16 v[4:7], v[196:199], v[236:239], v[4:7]
	v_mfma_f32_16x16x32_bf16 v[0:3], v[204:207], v[236:239], v[0:3]
	v_mfma_f32_16x16x32_bf16 v[52:55], v[200:203], v[216:219], v[52:55]
	v_mfma_f32_16x16x32_bf16 v[48:51], v[208:211], v[216:219], v[48:51]
	v_mfma_f32_16x16x32_bf16 v[36:39], v[200:203], v[224:227], v[36:39]
	v_mfma_f32_16x16x32_bf16 v[32:35], v[208:211], v[224:227], v[32:35]
	v_mfma_f32_16x16x32_bf16 v[20:23], v[200:203], v[232:235], v[20:23]
	v_mfma_f32_16x16x32_bf16 v[16:19], v[208:211], v[232:235], v[16:19]
	v_mfma_f32_16x16x32_bf16 v[4:7], v[200:203], v[240:243], v[4:7]
	v_mfma_f32_16x16x32_bf16 v[0:3], v[208:211], v[240:243], v[0:3]
	s_setprio 0
	s_add_u32 s48, s48, 0x100
	s_addc_u32 s49, s49, 0
	s_add_u32 s59, s59, 0x100
	s_addc_u32 vcc_lo, vcc_lo, 0
	s_cmp_ge_u32 vcc_hi, s78
	s_mov_b32 s52, vcc_hi
	s_barrier
	s_cbranch_scc0 .LBB0_699
	s_and_b64 vcc, exec, s[36:37]
	s_cbranch_vccz .LBB0_702
